# waitcnt placement: GEMM mainloop pre-barrier s_waitcnt lgkmcnt(0) removed (the post-barrier wait before the first MFMA guards the fragments), 52 sites, on top of vt_pair2
# speedup vs baseline: 1.0110x; 1.0070x over previous
; #define PG8_STAGE(bufoff, gbase, voff) do { _Pragma("unroll") for (int _i = 0; _i < 2; ++_i) \
;         __builtin_amdgcn_global_load_lds((const unsigned*)((const char*)(gbase) + (voff)[_i]), (PG8_LAS unsigned*)(lds + (bufoff) + ldsw + _i * 8192), 16, 0, 0); } while (0)
; #define PG8_LDA(dst, b, h) do { _Pragma("unroll") for (int m = 0; m < 4; ++m) _Pragma("unroll") for (int k = 0; k < 2; ++k) dst[m][k] = *(const PG8_LAS bf16x8*)(lds + PG8_SA(b, h) + aoff + m * 2048 + k * 1024); } while (0)
; #define PG8_LDB(dst, b, h) do { _Pragma("unroll") for (int n = 0; n < 2; ++n) _Pragma("unroll") for (int k = 0; k < 2; ++k) dst[n][k] = *(const PG8_LAS bf16x8*)(lds + PG8_SB(b, h) + boff + n * 2048 + k * 1024); } while (0)
; #define PG8_MMA(ai, bj, At, Bt) do { __builtin_amdgcn_s_setprio(1); _Pragma("unroll") for (int m = 0; m < 4; ++m) _Pragma("unroll") for (int n = 0; n < 2; ++n) _Pragma("unroll") for (int k = 0; k < 2; ++k) \
;         acc[ai][bj][m][n] = __builtin_amdgcn_mfma_f32_16x16x32_bf16(Bt[n][k], At[m][k], acc[ai][bj][m][n], 0, 0, 0); __builtin_amdgcn_s_setprio(0); } while (0)
; #define PG8_WAIT_V(n) asm volatile("s_waitcnt vmcnt(" #n ")" ::: "memory")
; #define PG8_WAIT_L(n) asm volatile("s_waitcnt lgkmcnt(" #n ")" ::: "memory")
; #define PG8_BAR __builtin_amdgcn_s_barrier()
; #define PG8_SCHED __builtin_amdgcn_sched_barrier(0)
; template <class Epi, class Sched>
; __device__ __forceinline__ void gemm_phase(int wid_s, PG8_LAS unsigned char* lds, const Gemm g, const Sched& S, const Epi& E) {
;     ...
;         for (int t = 0; t < nt; t += 2) {
;             const bool last = (t == nt - 2);
;             const char* a1 = cA + (size_t)(t + 1) * kstep;
;             const char* a2 = last ? nA : cA + (size_t)(t + 2) * kstep; const char* b2 = last ? nB : cB + (size_t)(t + 2) * kstep;
;             const char* a3 = a2 + kstep; const char* b3 = b2 + kstep;
;             PG8_LDB(B0, 0, 0); PG8_LDB(B1, 0, 1); PG8_SCHED; PG8_LDA(At, 0, 0); PG8_STAGE(PG8_SA(1, 1), a1 + hstepA, voffA);
;             PG8_WAIT_V(8); PG8_WAIT_L(0); PG8_BAR; PG8_MMA(0, 0, At, B0); PG8_MMA(0, 1, At, B1); PG8_BAR; PG8_SCHED;
;             PG8_LDA(At, 0, 1); PG8_STAGE(PG8_SB(0, 0), b2, voffB); PG8_STAGE(PG8_SB(0, 1), b2 + hstepB, voffB); PG8_STAGE(PG8_SA(0, 0), a2, voffA);
.LBB0_491:
	s_add_i32 s34, s8, 2
	s_add_u32 s35, s6, 0x80
	s_addc_u32 s9, s7, 0
	s_add_i32 s50, 0, 0x10000
	s_cmp_eq_u32 s92, s8
	s_cselect_b32 s9, s29, s9
	s_cselect_b32 s8, s28, s35
	v_add_u32_e32 v142, s50, v158
	s_cselect_b32 s49, s31, s47
	s_cselect_b32 s48, s30, s33
	s_add_i32 s35, 0, 0x14000
	ds_read_b128 v[138:141], v142
	ds_read_b128 v[154:157], v142 offset:1024
	ds_read_b128 v[164:167], v142 offset:2048
	ds_read_b128 v[186:189], v142 offset:3072
	v_add_u32_e32 v142, s35, v158
	ds_read_b128 v[190:193], v142
	ds_read_b128 v[194:197], v142 offset:1024
	ds_read_b128 v[198:201], v142 offset:2048
	ds_read_b128 v[202:205], v142 offset:3072
	v_lshl_add_u64 v[238:239], s[6:7], 0, v[136:137]
	s_add_i32 m0, s18, 0xc000
	ds_read_b128 v[206:209], v162
	ds_read_b128 v[210:213], v162 offset:1024
	ds_read_b128 v[214:217], v162 offset:2048
	ds_read_b128 v[218:221], v162 offset:3072
	ds_read_b128 v[222:225], v162 offset:4096
	ds_read_b128 v[226:229], v162 offset:5120
	ds_read_b128 v[230:233], v162 offset:6144
	ds_read_b128 v[234:237], v162 offset:7168
	global_load_lds_dwordx4 v[238:239], off
	v_lshl_add_u64 v[238:239], s[6:7], 0, v[134:135]
	s_add_i32 m0, s18, 0xe000
	s_nop 0
	global_load_lds_dwordx4 v[238:239], off
	s_waitcnt vmcnt(8)
	s_barrier
	s_setprio 1
	s_waitcnt lgkmcnt(0)
	v_mfma_f32_16x16x32_bf16 v[120:123], v[138:141], v[206:209], v[120:123]
	v_mfma_f32_16x16x32_bf16 v[124:127], v[164:167], v[206:209], v[124:127]
	v_mfma_f32_16x16x32_bf16 v[108:111], v[138:141], v[214:217], v[108:111]
	v_mfma_f32_16x16x32_bf16 v[104:107], v[164:167], v[214:217], v[104:107]
	v_mfma_f32_16x16x32_bf16 v[92:95], v[138:141], v[222:225], v[92:95]
	v_mfma_f32_16x16x32_bf16 v[88:91], v[164:167], v[222:225], v[88:91]
	v_mfma_f32_16x16x32_bf16 v[76:79], v[138:141], v[230:233], v[76:79]
	v_mfma_f32_16x16x32_bf16 v[72:75], v[164:167], v[230:233], v[72:75]
	v_mfma_f32_16x16x32_bf16 v[120:123], v[154:157], v[210:213], v[120:123]
	v_mfma_f32_16x16x32_bf16 v[124:127], v[186:189], v[210:213], v[124:127]
	v_mfma_f32_16x16x32_bf16 v[108:111], v[154:157], v[218:221], v[108:111]
	v_mfma_f32_16x16x32_bf16 v[104:107], v[186:189], v[218:221], v[104:107]
	v_mfma_f32_16x16x32_bf16 v[92:95], v[154:157], v[226:229], v[92:95]
	v_mfma_f32_16x16x32_bf16 v[88:91], v[186:189], v[226:229], v[88:91]
	v_mfma_f32_16x16x32_bf16 v[76:79], v[154:157], v[234:237], v[76:79]
	v_mfma_f32_16x16x32_bf16 v[72:75], v[186:189], v[234:237], v[72:75]
	s_setprio 0
	s_setprio 1
	v_mfma_f32_16x16x32_bf16 v[116:119], v[190:193], v[206:209], v[116:119]
	v_mfma_f32_16x16x32_bf16 v[112:115], v[198:201], v[206:209], v[112:115]
	v_mfma_f32_16x16x32_bf16 v[100:103], v[190:193], v[214:217], v[100:103]
	v_mfma_f32_16x16x32_bf16 v[96:99], v[198:201], v[214:217], v[96:99]
	v_mfma_f32_16x16x32_bf16 v[84:87], v[190:193], v[222:225], v[84:87]
	v_mfma_f32_16x16x32_bf16 v[80:83], v[198:201], v[222:225], v[80:83]
	v_mfma_f32_16x16x32_bf16 v[68:71], v[190:193], v[230:233], v[68:71]
	v_mfma_f32_16x16x32_bf16 v[64:67], v[198:201], v[230:233], v[64:67]
	v_mfma_f32_16x16x32_bf16 v[116:119], v[194:197], v[210:213], v[116:119]
	v_mfma_f32_16x16x32_bf16 v[112:115], v[202:205], v[210:213], v[112:115]
	v_mfma_f32_16x16x32_bf16 v[100:103], v[194:197], v[218:221], v[100:103]
	v_mfma_f32_16x16x32_bf16 v[96:99], v[202:205], v[218:221], v[96:99]
	v_mfma_f32_16x16x32_bf16 v[84:87], v[194:197], v[226:229], v[84:87]
	v_mfma_f32_16x16x32_bf16 v[80:83], v[202:205], v[226:229], v[80:83]
	v_mfma_f32_16x16x32_bf16 v[68:71], v[194:197], v[234:237], v[68:71]
	v_mfma_f32_16x16x32_bf16 v[64:67], v[202:205], v[234:237], v[64:67]
	s_setprio 0
	s_barrier
	s_add_i32 s50, s50, s53
	v_lshl_add_u64 v[238:239], s[48:49], 0, v[144:145]
	s_mov_b32 m0, s50
	ds_read_b128 v[206:209], v162 offset:16384
	ds_read_b128 v[210:213], v162 offset:17408
	ds_read_b128 v[214:217], v162 offset:18432
	ds_read_b128 v[218:221], v162 offset:19456
	ds_read_b128 v[222:225], v162 offset:20480
	ds_read_b128 v[226:229], v162 offset:21504
	ds_read_b128 v[230:233], v162 offset:22528
	ds_read_b128 v[234:237], v162 offset:23552
	global_load_lds_dwordx4 v[238:239], off
	s_add_i32 m0, s50, 0x2000
	v_lshl_add_u64 v[240:241], s[48:49], 0, v[132:133]
	s_add_u32 s48, s48, s12
	s_addc_u32 s49, s49, s13
	s_add_i32 s35, s35, s53
	global_load_lds_dwordx4 v[240:241], off
	v_lshl_add_u64 v[242:243], s[48:49], 0, v[144:145]
	s_mov_b32 m0, s35
	v_lshl_add_u64 v[244:245], s[48:49], 0, v[132:133]
	global_load_lds_dwordx4 v[242:243], off
	s_add_i32 m0, s35, 0x2000
	v_lshl_add_u64 v[246:247], s[8:9], 0, v[128:129]
	global_load_lds_dwordx4 v[244:245], off
	s_mov_b32 m0, s18
	v_lshl_add_u64 v[248:249], s[8:9], 0, v[130:131]
	global_load_lds_dwordx4 v[246:247], off
	s_mov_b32 m0, s19
	s_nop 0
	global_load_lds_dwordx4 v[248:249], off
	s_waitcnt vmcnt(8)
	s_barrier
; #define PG8_STAGE(bufoff, gbase, voff) do { _Pragma("unroll") for (int _i = 0; _i < 2; ++_i) \
;         __builtin_amdgcn_global_load_lds((const unsigned*)((const char*)(gbase) + (voff)[_i]), (PG8_LAS unsigned*)(lds + (bufoff) + ldsw + _i * 8192), 16, 0, 0); } while (0)
; #define PG8_LDA(dst, b, h) do { _Pragma("unroll") for (int m = 0; m < 4; ++m) _Pragma("unroll") for (int k = 0; k < 2; ++k) dst[m][k] = *(const PG8_LAS bf16x8*)(lds + PG8_SA(b, h) + aoff + m * 2048 + k * 1024); } while (0)
; #define PG8_LDB(dst, b, h) do { _Pragma("unroll") for (int n = 0; n < 2; ++n) _Pragma("unroll") for (int k = 0; k < 2; ++k) dst[n][k] = *(const PG8_LAS bf16x8*)(lds + PG8_SB(b, h) + boff + n * 2048 + k * 1024); } while (0)
; #define PG8_MMA(ai, bj, At, Bt) do { __builtin_amdgcn_s_setprio(1); _Pragma("unroll") for (int m = 0; m < 4; ++m) _Pragma("unroll") for (int n = 0; n < 2; ++n) _Pragma("unroll") for (int k = 0; k < 2; ++k) \
;         acc[ai][bj][m][n] = __builtin_amdgcn_mfma_f32_16x16x32_bf16(Bt[n][k], At[m][k], acc[ai][bj][m][n], 0, 0, 0); __builtin_amdgcn_s_setprio(0); } while (0)
; #define PG8_WAIT_V(n) asm volatile("s_waitcnt vmcnt(" #n ")" ::: "memory")
; #define PG8_WAIT_L(n) asm volatile("s_waitcnt lgkmcnt(" #n ")" ::: "memory")
; #define PG8_BAR __builtin_amdgcn_s_barrier()
; #define PG8_SCHED __builtin_amdgcn_sched_barrier(0)
; template <class Epi, class Sched>
; __device__ __forceinline__ void gemm_phase(int wid_s, PG8_LAS unsigned char* lds, const Gemm g, const Sched& S, const Epi& E) {
;     ...
;             PG8_WAIT_V(8); PG8_WAIT_L(0); PG8_BAR; PG8_MMA(1, 0, At, B0); PG8_MMA(1, 1, At, B1); PG8_BAR; PG8_SCHED;
;             PG8_LDB(B0, 1, 0); PG8_LDB(B1, 1, 1); PG8_SCHED; PG8_LDA(At, 1, 0); PG8_STAGE(PG8_SA(0, 1), a2 + hstepA, voffA);
;             PG8_WAIT_V(8); PG8_WAIT_L(0); PG8_BAR; PG8_MMA(0, 0, At, B0); PG8_MMA(0, 1, At, B1); PG8_BAR; PG8_SCHED;
	s_setprio 1
	s_waitcnt lgkmcnt(0)
	v_mfma_f32_16x16x32_bf16 v[60:63], v[138:141], v[206:209], v[60:63]
	v_mfma_f32_16x16x32_bf16 v[56:59], v[164:167], v[206:209], v[56:59]
	v_mfma_f32_16x16x32_bf16 v[44:47], v[138:141], v[214:217], v[44:47]
	v_mfma_f32_16x16x32_bf16 v[40:43], v[164:167], v[214:217], v[40:43]
	v_mfma_f32_16x16x32_bf16 v[28:31], v[138:141], v[222:225], v[28:31]
	v_mfma_f32_16x16x32_bf16 v[24:27], v[164:167], v[222:225], v[24:27]
	v_mfma_f32_16x16x32_bf16 v[12:15], v[138:141], v[230:233], v[12:15]
	v_mfma_f32_16x16x32_bf16 v[8:11], v[164:167], v[230:233], v[8:11]
	v_mfma_f32_16x16x32_bf16 v[60:63], v[154:157], v[210:213], v[60:63]
	v_mfma_f32_16x16x32_bf16 v[56:59], v[186:189], v[210:213], v[56:59]
	v_mfma_f32_16x16x32_bf16 v[44:47], v[154:157], v[218:221], v[44:47]
	v_mfma_f32_16x16x32_bf16 v[40:43], v[186:189], v[218:221], v[40:43]
	v_mfma_f32_16x16x32_bf16 v[28:31], v[154:157], v[226:229], v[28:31]
	v_mfma_f32_16x16x32_bf16 v[24:27], v[186:189], v[226:229], v[24:27]
	v_mfma_f32_16x16x32_bf16 v[12:15], v[154:157], v[234:237], v[12:15]
	v_mfma_f32_16x16x32_bf16 v[8:11], v[186:189], v[234:237], v[8:11]
	s_setprio 0
	s_setprio 1
	v_mfma_f32_16x16x32_bf16 v[52:55], v[190:193], v[206:209], v[52:55]
	v_mfma_f32_16x16x32_bf16 v[48:51], v[198:201], v[206:209], v[48:51]
	v_mfma_f32_16x16x32_bf16 v[36:39], v[190:193], v[214:217], v[36:39]
	v_mfma_f32_16x16x32_bf16 v[32:35], v[198:201], v[214:217], v[32:35]
	v_mfma_f32_16x16x32_bf16 v[20:23], v[190:193], v[222:225], v[20:23]
	v_mfma_f32_16x16x32_bf16 v[16:19], v[198:201], v[222:225], v[16:19]
	v_mfma_f32_16x16x32_bf16 v[4:7], v[190:193], v[230:233], v[4:7]
	v_mfma_f32_16x16x32_bf16 v[0:3], v[198:201], v[230:233], v[0:3]
	v_mfma_f32_16x16x32_bf16 v[52:55], v[194:197], v[210:213], v[52:55]
	v_mfma_f32_16x16x32_bf16 v[48:51], v[202:205], v[210:213], v[48:51]
	v_mfma_f32_16x16x32_bf16 v[36:39], v[194:197], v[218:221], v[36:39]
	v_mfma_f32_16x16x32_bf16 v[32:35], v[202:205], v[218:221], v[32:35]
	v_mfma_f32_16x16x32_bf16 v[20:23], v[194:197], v[226:229], v[20:23]
	v_mfma_f32_16x16x32_bf16 v[16:19], v[202:205], v[226:229], v[16:19]
	v_mfma_f32_16x16x32_bf16 v[4:7], v[194:197], v[234:237], v[4:7]
	v_mfma_f32_16x16x32_bf16 v[0:3], v[202:205], v[234:237], v[0:3]
	s_setprio 0
	s_barrier
	s_add_i32 s35, 0, 0x18000
	v_add_u32_e32 v142, s35, v158
	s_add_i32 s48, 0, 0x1c000
	ds_read_b128 v[138:141], v142
	ds_read_b128 v[154:157], v142 offset:1024
	ds_read_b128 v[164:167], v142 offset:2048
	ds_read_b128 v[186:189], v142 offset:3072
	v_add_u32_e32 v142, s48, v158
	ds_read_b128 v[190:193], v142
	ds_read_b128 v[194:197], v142 offset:1024
	ds_read_b128 v[198:201], v142 offset:2048
	ds_read_b128 v[202:205], v142 offset:3072
	s_add_u32 s8, s8, s10
	s_addc_u32 s9, s9, s11
	s_mov_b32 m0, s94
	v_lshl_add_u64 v[250:251], s[8:9], 0, v[128:129]
	ds_read_b128 v[206:209], v162 offset:32768
	ds_read_b128 v[210:213], v162 offset:33792
	ds_read_b128 v[214:217], v162 offset:34816
	ds_read_b128 v[218:221], v162 offset:35840
	ds_read_b128 v[222:225], v162 offset:36864
	ds_read_b128 v[226:229], v162 offset:37888
	ds_read_b128 v[230:233], v162 offset:38912
	ds_read_b128 v[234:237], v162 offset:39936
	global_load_lds_dwordx4 v[250:251], off
	v_lshl_add_u64 v[250:251], s[8:9], 0, v[130:131]
	s_mov_b32 m0, s95
	s_nop 0
	global_load_lds_dwordx4 v[250:251], off
	s_waitcnt vmcnt(8)
	s_barrier
	s_setprio 1
	s_waitcnt lgkmcnt(0)
	v_mfma_f32_16x16x32_bf16 v[120:123], v[138:141], v[206:209], v[120:123]
	v_mfma_f32_16x16x32_bf16 v[124:127], v[164:167], v[206:209], v[124:127]
	v_mfma_f32_16x16x32_bf16 v[108:111], v[138:141], v[214:217], v[108:111]
	v_mfma_f32_16x16x32_bf16 v[104:107], v[164:167], v[214:217], v[104:107]
	v_mfma_f32_16x16x32_bf16 v[92:95], v[138:141], v[222:225], v[92:95]
	v_mfma_f32_16x16x32_bf16 v[88:91], v[164:167], v[222:225], v[88:91]
	v_mfma_f32_16x16x32_bf16 v[76:79], v[138:141], v[230:233], v[76:79]
	v_mfma_f32_16x16x32_bf16 v[72:75], v[164:167], v[230:233], v[72:75]
	v_mfma_f32_16x16x32_bf16 v[120:123], v[154:157], v[210:213], v[120:123]
	v_mfma_f32_16x16x32_bf16 v[124:127], v[186:189], v[210:213], v[124:127]
	v_mfma_f32_16x16x32_bf16 v[108:111], v[154:157], v[218:221], v[108:111]
	v_mfma_f32_16x16x32_bf16 v[104:107], v[186:189], v[218:221], v[104:107]
	v_mfma_f32_16x16x32_bf16 v[92:95], v[154:157], v[226:229], v[92:95]
	v_mfma_f32_16x16x32_bf16 v[88:91], v[186:189], v[226:229], v[88:91]
	v_mfma_f32_16x16x32_bf16 v[76:79], v[154:157], v[234:237], v[76:79]
	v_mfma_f32_16x16x32_bf16 v[72:75], v[186:189], v[234:237], v[72:75]
	s_setprio 0
	s_setprio 1
	v_mfma_f32_16x16x32_bf16 v[116:119], v[190:193], v[206:209], v[116:119]
	v_mfma_f32_16x16x32_bf16 v[112:115], v[198:201], v[206:209], v[112:115]
	v_mfma_f32_16x16x32_bf16 v[100:103], v[190:193], v[214:217], v[100:103]
	v_mfma_f32_16x16x32_bf16 v[96:99], v[198:201], v[214:217], v[96:99]
	v_mfma_f32_16x16x32_bf16 v[84:87], v[190:193], v[222:225], v[84:87]
	v_mfma_f32_16x16x32_bf16 v[80:83], v[198:201], v[222:225], v[80:83]
	v_mfma_f32_16x16x32_bf16 v[68:71], v[190:193], v[230:233], v[68:71]
	v_mfma_f32_16x16x32_bf16 v[64:67], v[198:201], v[230:233], v[64:67]
	v_mfma_f32_16x16x32_bf16 v[116:119], v[194:197], v[210:213], v[116:119]
	v_mfma_f32_16x16x32_bf16 v[112:115], v[202:205], v[210:213], v[112:115]
	v_mfma_f32_16x16x32_bf16 v[100:103], v[194:197], v[218:221], v[100:103]
	v_mfma_f32_16x16x32_bf16 v[96:99], v[202:205], v[218:221], v[96:99]
	v_mfma_f32_16x16x32_bf16 v[84:87], v[194:197], v[226:229], v[84:87]
	v_mfma_f32_16x16x32_bf16 v[80:83], v[202:205], v[226:229], v[80:83]
	v_mfma_f32_16x16x32_bf16 v[68:71], v[194:197], v[234:237], v[68:71]
	v_mfma_f32_16x16x32_bf16 v[64:67], v[202:205], v[234:237], v[64:67]
	s_setprio 0
	s_barrier
; #define PG8_STAGE(bufoff, gbase, voff) do { _Pragma("unroll") for (int _i = 0; _i < 2; ++_i) \
;         __builtin_amdgcn_global_load_lds((const unsigned*)((const char*)(gbase) + (voff)[_i]), (PG8_LAS unsigned*)(lds + (bufoff) + ldsw + _i * 8192), 16, 0, 0); } while (0)
; #define PG8_LDA(dst, b, h) do { _Pragma("unroll") for (int m = 0; m < 4; ++m) _Pragma("unroll") for (int k = 0; k < 2; ++k) dst[m][k] = *(const PG8_LAS bf16x8*)(lds + PG8_SA(b, h) + aoff + m * 2048 + k * 1024); } while (0)
; #define PG8_MMA(ai, bj, At, Bt) do { __builtin_amdgcn_s_setprio(1); _Pragma("unroll") for (int m = 0; m < 4; ++m) _Pragma("unroll") for (int n = 0; n < 2; ++n) _Pragma("unroll") for (int k = 0; k < 2; ++k) \
;         acc[ai][bj][m][n] = __builtin_amdgcn_mfma_f32_16x16x32_bf16(Bt[n][k], At[m][k], acc[ai][bj][m][n], 0, 0, 0); __builtin_amdgcn_s_setprio(0); } while (0)
; #define PG8_WAIT_V(n) asm volatile("s_waitcnt vmcnt(" #n ")" ::: "memory")
; #define PG8_WAIT_L(n) asm volatile("s_waitcnt lgkmcnt(" #n ")" ::: "memory")
; #define PG8_BAR __builtin_amdgcn_s_barrier()
; #define PG8_SCHED __builtin_amdgcn_sched_barrier(0)
; template <class Epi, class Sched>
; __device__ __forceinline__ void gemm_phase(int wid_s, PG8_LAS unsigned char* lds, const Gemm g, const Sched& S, const Epi& E) {
;     ...
;         for (int t = 0; t < nt; t += 2) {
;             const bool last = (t == nt - 2);
;             const char* a1 = cA + (size_t)(t + 1) * kstep;
;             const char* a2 = last ? nA : cA + (size_t)(t + 2) * kstep; const char* b2 = last ? nB : cB + (size_t)(t + 2) * kstep;
;             const char* a3 = a2 + kstep; const char* b3 = b2 + kstep;
;     ...
;             PG8_LDA(At, 1, 1); PG8_STAGE(PG8_SB(1, 0), b3, voffB); PG8_STAGE(PG8_SB(1, 1), b3 + hstepB, voffB); PG8_STAGE(PG8_SA(1, 0), a3, voffA);
;             PG8_WAIT_V(8); PG8_WAIT_L(0); PG8_BAR; PG8_MMA(1, 0, At, B0); PG8_MMA(1, 1, At, B1); PG8_BAR; PG8_SCHED;
	s_add_i32 s8, s35, s53
	v_lshl_add_u64 v[238:239], v[238:239], 0, s[96:97]
	s_mov_b32 m0, s8
	ds_read_b128 v[206:209], v162 offset:49152
	ds_read_b128 v[210:213], v162 offset:50176
	ds_read_b128 v[214:217], v162 offset:51200
	ds_read_b128 v[218:221], v162 offset:52224
	ds_read_b128 v[222:225], v162 offset:53248
	ds_read_b128 v[226:229], v162 offset:54272
	ds_read_b128 v[230:233], v162 offset:55296
	ds_read_b128 v[234:237], v162 offset:56320
	global_load_lds_dwordx4 v[238:239], off
	v_lshl_add_u64 v[238:239], v[240:241], 0, s[96:97]
	s_add_i32 m0, s8, 0x2000
	s_add_i32 s8, s48, s53
	global_load_lds_dwordx4 v[238:239], off
	v_lshl_add_u64 v[238:239], v[242:243], 0, s[96:97]
	s_mov_b32 m0, s8
	s_nop 0
	global_load_lds_dwordx4 v[238:239], off
	v_lshl_add_u64 v[238:239], v[244:245], 0, s[96:97]
	s_add_i32 m0, s8, 0x2000
	s_nop 0
	global_load_lds_dwordx4 v[238:239], off
	v_lshl_add_u64 v[238:239], v[246:247], 0, s[96:97]
	s_mov_b32 m0, s40
	s_nop 0
	global_load_lds_dwordx4 v[238:239], off
	v_lshl_add_u64 v[238:239], v[248:249], 0, s[96:97]
	s_mov_b32 m0, s41
	s_nop 0
	global_load_lds_dwordx4 v[238:239], off
	s_waitcnt vmcnt(8)
	s_barrier
	s_setprio 1
	s_waitcnt lgkmcnt(0)
	v_mfma_f32_16x16x32_bf16 v[60:63], v[138:141], v[206:209], v[60:63]
	v_mfma_f32_16x16x32_bf16 v[56:59], v[164:167], v[206:209], v[56:59]
	v_mfma_f32_16x16x32_bf16 v[44:47], v[138:141], v[214:217], v[44:47]
	v_mfma_f32_16x16x32_bf16 v[40:43], v[164:167], v[214:217], v[40:43]
	v_mfma_f32_16x16x32_bf16 v[28:31], v[138:141], v[222:225], v[28:31]
	v_mfma_f32_16x16x32_bf16 v[24:27], v[164:167], v[222:225], v[24:27]
	v_mfma_f32_16x16x32_bf16 v[12:15], v[138:141], v[230:233], v[12:15]
	v_mfma_f32_16x16x32_bf16 v[8:11], v[164:167], v[230:233], v[8:11]
	v_mfma_f32_16x16x32_bf16 v[60:63], v[154:157], v[210:213], v[60:63]
	v_mfma_f32_16x16x32_bf16 v[56:59], v[186:189], v[210:213], v[56:59]
	v_mfma_f32_16x16x32_bf16 v[44:47], v[154:157], v[218:221], v[44:47]
	v_mfma_f32_16x16x32_bf16 v[40:43], v[186:189], v[218:221], v[40:43]
	v_mfma_f32_16x16x32_bf16 v[28:31], v[154:157], v[226:229], v[28:31]
	v_mfma_f32_16x16x32_bf16 v[24:27], v[186:189], v[226:229], v[24:27]
	v_mfma_f32_16x16x32_bf16 v[12:15], v[154:157], v[234:237], v[12:15]
	v_mfma_f32_16x16x32_bf16 v[8:11], v[186:189], v[234:237], v[8:11]
	s_setprio 0
	s_setprio 1
	v_mfma_f32_16x16x32_bf16 v[52:55], v[190:193], v[206:209], v[52:55]
	v_mfma_f32_16x16x32_bf16 v[48:51], v[198:201], v[206:209], v[48:51]
	v_mfma_f32_16x16x32_bf16 v[36:39], v[190:193], v[214:217], v[36:39]
	v_mfma_f32_16x16x32_bf16 v[32:35], v[198:201], v[214:217], v[32:35]
	v_mfma_f32_16x16x32_bf16 v[20:23], v[190:193], v[222:225], v[20:23]
	v_mfma_f32_16x16x32_bf16 v[16:19], v[198:201], v[222:225], v[16:19]
	v_mfma_f32_16x16x32_bf16 v[4:7], v[190:193], v[230:233], v[4:7]
	v_mfma_f32_16x16x32_bf16 v[0:3], v[198:201], v[230:233], v[0:3]
	v_mfma_f32_16x16x32_bf16 v[52:55], v[194:197], v[210:213], v[52:55]
	v_mfma_f32_16x16x32_bf16 v[48:51], v[202:205], v[210:213], v[48:51]
	v_mfma_f32_16x16x32_bf16 v[36:39], v[194:197], v[218:221], v[36:39]
	v_mfma_f32_16x16x32_bf16 v[32:35], v[202:205], v[218:221], v[32:35]
	v_mfma_f32_16x16x32_bf16 v[20:23], v[194:197], v[226:229], v[20:23]
	v_mfma_f32_16x16x32_bf16 v[16:19], v[202:205], v[226:229], v[16:19]
	v_mfma_f32_16x16x32_bf16 v[4:7], v[194:197], v[234:237], v[4:7]
	v_mfma_f32_16x16x32_bf16 v[0:3], v[202:205], v[234:237], v[0:3]
	s_setprio 0
	s_barrier
	s_add_u32 s33, s33, 0x100
	s_addc_u32 s47, s47, 0
	s_add_u32 s6, s6, 0x100
	s_addc_u32 s7, s7, 0
	s_cmp_ge_i32 s34, s37
	s_mov_b32 s8, s34
	s_cbranch_scc0 .LBB0_491
	s_movk_i32 s33, 0x300

; #define PG8_STAGE(bufoff, gbase, voff) do { _Pragma("unroll") for (int _i = 0; _i < 2; ++_i) \
;         __builtin_amdgcn_global_load_lds((const unsigned*)((const char*)(gbase) + (voff)[_i]), (PG8_LAS unsigned*)(lds + (bufoff) + ldsw + _i * 8192), 16, 0, 0); } while (0)
; #define PG8_LDA(dst, b, h) do { _Pragma("unroll") for (int m = 0; m < 4; ++m) _Pragma("unroll") for (int k = 0; k < 2; ++k) dst[m][k] = *(const PG8_LAS bf16x8*)(lds + PG8_SA(b, h) + aoff + m * 2048 + k * 1024); } while (0)
; #define PG8_LDB(dst, b, h) do { _Pragma("unroll") for (int n = 0; n < 2; ++n) _Pragma("unroll") for (int k = 0; k < 2; ++k) dst[n][k] = *(const PG8_LAS bf16x8*)(lds + PG8_SB(b, h) + boff + n * 2048 + k * 1024); } while (0)
; #define PG8_MMA(ai, bj, At, Bt) do { __builtin_amdgcn_s_setprio(1); _Pragma("unroll") for (int m = 0; m < 4; ++m) _Pragma("unroll") for (int n = 0; n < 2; ++n) _Pragma("unroll") for (int k = 0; k < 2; ++k) \
;         acc[ai][bj][m][n] = __builtin_amdgcn_mfma_f32_16x16x32_bf16(Bt[n][k], At[m][k], acc[ai][bj][m][n], 0, 0, 0); __builtin_amdgcn_s_setprio(0); } while (0)
; #define PG8_WAIT_V(n) asm volatile("s_waitcnt vmcnt(" #n ")" ::: "memory")
; #define PG8_WAIT_L(n) asm volatile("s_waitcnt lgkmcnt(" #n ")" ::: "memory")
; #define PG8_BAR __builtin_amdgcn_s_barrier()
; #define PG8_SCHED __builtin_amdgcn_sched_barrier(0)
; template <class Epi, class Sched>
; __device__ __forceinline__ void gemm_phase(int wid_s, PG8_LAS unsigned char* lds, const Gemm g, const Sched& S, const Epi& E) {
;     ...
;         for (int t = 0; t < nt; t += 2) {
;             const bool last = (t == nt - 2);
;             const char* a1 = cA + (size_t)(t + 1) * kstep;
;             const char* a2 = last ? nA : cA + (size_t)(t + 2) * kstep; const char* b2 = last ? nB : cB + (size_t)(t + 2) * kstep;
;             const char* a3 = a2 + kstep; const char* b3 = b2 + kstep;
;             PG8_LDB(B0, 0, 0); PG8_LDB(B1, 0, 1); PG8_SCHED; PG8_LDA(At, 0, 0); PG8_STAGE(PG8_SA(1, 1), a1 + hstepA, voffA);
;             PG8_WAIT_V(8); PG8_WAIT_L(0); PG8_BAR; PG8_MMA(0, 0, At, B0); PG8_MMA(0, 1, At, B1); PG8_BAR; PG8_SCHED;
;             PG8_LDA(At, 0, 1); PG8_STAGE(PG8_SB(0, 0), b2, voffB); PG8_STAGE(PG8_SB(0, 1), b2 + hstepB, voffB); PG8_STAGE(PG8_SA(0, 0), a2, voffA);
.LBB0_1061:
	s_add_i32 s55, s28, 2
	s_add_u32 s56, s26, 0x80
	s_addc_u32 s29, s27, 0
	s_add_i32 s92, 0, 0x10000
	s_cmp_eq_u32 s46, s28
	s_cselect_b32 s29, s5, s29
	s_cselect_b32 s28, s4, s56
	v_add_u32_e32 v138, s92, v141
	s_cselect_b32 s57, s25, s54
	s_cselect_b32 s56, s24, s33
	s_add_i32 s94, 0, 0x14000
	ds_read_b128 v[154:157], v138
	ds_read_b128 v[158:161], v138 offset:1024
	ds_read_b128 v[162:165], v138 offset:2048
	ds_read_b128 v[186:189], v138 offset:3072
	v_add_u32_e32 v138, s94, v141
	ds_read_b128 v[190:193], v138
	ds_read_b128 v[194:197], v138 offset:1024
	ds_read_b128 v[198:201], v138 offset:2048
	ds_read_b128 v[202:205], v138 offset:3072
	v_lshl_add_u64 v[138:139], s[26:27], 0, v[136:137]
	s_add_i32 m0, s37, 0xc000
	ds_read_b128 v[206:209], v143
	ds_read_b128 v[210:213], v143 offset:1024
	ds_read_b128 v[214:217], v143 offset:2048
	ds_read_b128 v[218:221], v143 offset:3072
	ds_read_b128 v[222:225], v143 offset:4096
	ds_read_b128 v[226:229], v143 offset:5120
	ds_read_b128 v[230:233], v143 offset:6144
	ds_read_b128 v[234:237], v143 offset:7168
	global_load_lds_dwordx4 v[138:139], off
	v_lshl_add_u64 v[138:139], s[26:27], 0, v[134:135]
	s_add_i32 m0, s37, 0xe000
	s_nop 0
	global_load_lds_dwordx4 v[138:139], off
	s_waitcnt vmcnt(8)
	s_barrier
	s_setprio 1
	s_waitcnt lgkmcnt(0)
	v_mfma_f32_16x16x32_bf16 v[120:123], v[154:157], v[206:209], v[120:123]
	v_mfma_f32_16x16x32_bf16 v[124:127], v[162:165], v[206:209], v[124:127]
	v_mfma_f32_16x16x32_bf16 v[108:111], v[154:157], v[214:217], v[108:111]
	v_mfma_f32_16x16x32_bf16 v[104:107], v[162:165], v[214:217], v[104:107]
	v_mfma_f32_16x16x32_bf16 v[92:95], v[154:157], v[222:225], v[92:95]
	v_mfma_f32_16x16x32_bf16 v[88:91], v[162:165], v[222:225], v[88:91]
	v_mfma_f32_16x16x32_bf16 v[76:79], v[154:157], v[230:233], v[76:79]
	v_mfma_f32_16x16x32_bf16 v[72:75], v[162:165], v[230:233], v[72:75]
	v_mfma_f32_16x16x32_bf16 v[120:123], v[158:161], v[210:213], v[120:123]
	v_mfma_f32_16x16x32_bf16 v[124:127], v[186:189], v[210:213], v[124:127]
	v_mfma_f32_16x16x32_bf16 v[108:111], v[158:161], v[218:221], v[108:111]
	v_mfma_f32_16x16x32_bf16 v[104:107], v[186:189], v[218:221], v[104:107]
	v_mfma_f32_16x16x32_bf16 v[92:95], v[158:161], v[226:229], v[92:95]
	v_mfma_f32_16x16x32_bf16 v[88:91], v[186:189], v[226:229], v[88:91]
	v_mfma_f32_16x16x32_bf16 v[76:79], v[158:161], v[234:237], v[76:79]
	v_mfma_f32_16x16x32_bf16 v[72:75], v[186:189], v[234:237], v[72:75]
	s_setprio 0
	s_setprio 1
	v_mfma_f32_16x16x32_bf16 v[116:119], v[190:193], v[206:209], v[116:119]
	v_mfma_f32_16x16x32_bf16 v[112:115], v[198:201], v[206:209], v[112:115]
	v_mfma_f32_16x16x32_bf16 v[100:103], v[190:193], v[214:217], v[100:103]
	v_mfma_f32_16x16x32_bf16 v[96:99], v[198:201], v[214:217], v[96:99]
	v_mfma_f32_16x16x32_bf16 v[84:87], v[190:193], v[222:225], v[84:87]
	v_mfma_f32_16x16x32_bf16 v[80:83], v[198:201], v[222:225], v[80:83]
	v_mfma_f32_16x16x32_bf16 v[68:71], v[190:193], v[230:233], v[68:71]
	v_mfma_f32_16x16x32_bf16 v[64:67], v[198:201], v[230:233], v[64:67]
	v_mfma_f32_16x16x32_bf16 v[116:119], v[194:197], v[210:213], v[116:119]
	v_mfma_f32_16x16x32_bf16 v[112:115], v[202:205], v[210:213], v[112:115]
	v_mfma_f32_16x16x32_bf16 v[100:103], v[194:197], v[218:221], v[100:103]
	v_mfma_f32_16x16x32_bf16 v[96:99], v[202:205], v[218:221], v[96:99]
	v_mfma_f32_16x16x32_bf16 v[84:87], v[194:197], v[226:229], v[84:87]
	v_mfma_f32_16x16x32_bf16 v[80:83], v[202:205], v[226:229], v[80:83]
	v_mfma_f32_16x16x32_bf16 v[68:71], v[194:197], v[234:237], v[68:71]
	v_mfma_f32_16x16x32_bf16 v[64:67], v[202:205], v[234:237], v[64:67]
	s_setprio 0
	s_barrier
	s_add_i32 s92, s92, s35
	v_lshl_add_u64 v[138:139], s[56:57], 0, v[144:145]
	s_mov_b32 m0, s92
	ds_read_b128 v[206:209], v143 offset:16384
	ds_read_b128 v[210:213], v143 offset:17408
	ds_read_b128 v[214:217], v143 offset:18432
	ds_read_b128 v[218:221], v143 offset:19456
	ds_read_b128 v[222:225], v143 offset:20480
	ds_read_b128 v[226:229], v143 offset:21504
	ds_read_b128 v[230:233], v143 offset:22528
	ds_read_b128 v[234:237], v143 offset:23552
	global_load_lds_dwordx4 v[138:139], off
	s_add_i32 m0, s92, 0x2000
	v_lshl_add_u64 v[166:167], s[56:57], 0, v[128:129]
	s_add_u32 s56, s56, s8
	s_addc_u32 s57, s57, s9
	s_add_i32 s92, s94, s35
	global_load_lds_dwordx4 v[166:167], off
	v_lshl_add_u64 v[238:239], s[56:57], 0, v[144:145]
	s_mov_b32 m0, s92
	v_lshl_add_u64 v[240:241], s[56:57], 0, v[128:129]
	global_load_lds_dwordx4 v[238:239], off
	s_add_i32 m0, s92, 0x2000
	v_lshl_add_u64 v[242:243], s[28:29], 0, v[132:133]
	global_load_lds_dwordx4 v[240:241], off
	s_mov_b32 m0, s37
	v_lshl_add_u64 v[244:245], s[28:29], 0, v[130:131]
	global_load_lds_dwordx4 v[242:243], off
	s_mov_b32 m0, s39
	s_nop 0
	global_load_lds_dwordx4 v[244:245], off
	s_waitcnt vmcnt(8)
	s_barrier
; #define PG8_STAGE(bufoff, gbase, voff) do { _Pragma("unroll") for (int _i = 0; _i < 2; ++_i) \
;         __builtin_amdgcn_global_load_lds((const unsigned*)((const char*)(gbase) + (voff)[_i]), (PG8_LAS unsigned*)(lds + (bufoff) + ldsw + _i * 8192), 16, 0, 0); } while (0)
; #define PG8_LDA(dst, b, h) do { _Pragma("unroll") for (int m = 0; m < 4; ++m) _Pragma("unroll") for (int k = 0; k < 2; ++k) dst[m][k] = *(const PG8_LAS bf16x8*)(lds + PG8_SA(b, h) + aoff + m * 2048 + k * 1024); } while (0)
; #define PG8_LDB(dst, b, h) do { _Pragma("unroll") for (int n = 0; n < 2; ++n) _Pragma("unroll") for (int k = 0; k < 2; ++k) dst[n][k] = *(const PG8_LAS bf16x8*)(lds + PG8_SB(b, h) + boff + n * 2048 + k * 1024); } while (0)
; #define PG8_MMA(ai, bj, At, Bt) do { __builtin_amdgcn_s_setprio(1); _Pragma("unroll") for (int m = 0; m < 4; ++m) _Pragma("unroll") for (int n = 0; n < 2; ++n) _Pragma("unroll") for (int k = 0; k < 2; ++k) \
;         acc[ai][bj][m][n] = __builtin_amdgcn_mfma_f32_16x16x32_bf16(Bt[n][k], At[m][k], acc[ai][bj][m][n], 0, 0, 0); __builtin_amdgcn_s_setprio(0); } while (0)
; #define PG8_WAIT_V(n) asm volatile("s_waitcnt vmcnt(" #n ")" ::: "memory")
; #define PG8_WAIT_L(n) asm volatile("s_waitcnt lgkmcnt(" #n ")" ::: "memory")
; #define PG8_BAR __builtin_amdgcn_s_barrier()
; #define PG8_SCHED __builtin_amdgcn_sched_barrier(0)
; template <class Epi, class Sched>
; __device__ __forceinline__ void gemm_phase(int wid_s, PG8_LAS unsigned char* lds, const Gemm g, const Sched& S, const Epi& E) {
;     ...
;             PG8_WAIT_V(8); PG8_WAIT_L(0); PG8_BAR; PG8_MMA(1, 0, At, B0); PG8_MMA(1, 1, At, B1); PG8_BAR; PG8_SCHED;
;             PG8_LDB(B0, 1, 0); PG8_LDB(B1, 1, 1); PG8_SCHED; PG8_LDA(At, 1, 0); PG8_STAGE(PG8_SA(0, 1), a2 + hstepA, voffA);
;             PG8_WAIT_V(8); PG8_WAIT_L(0); PG8_BAR; PG8_MMA(0, 0, At, B0); PG8_MMA(0, 1, At, B1); PG8_BAR; PG8_SCHED;
	s_setprio 1
	s_waitcnt lgkmcnt(0)
	v_mfma_f32_16x16x32_bf16 v[60:63], v[154:157], v[206:209], v[60:63]
	v_mfma_f32_16x16x32_bf16 v[56:59], v[162:165], v[206:209], v[56:59]
	v_mfma_f32_16x16x32_bf16 v[44:47], v[154:157], v[214:217], v[44:47]
	v_mfma_f32_16x16x32_bf16 v[40:43], v[162:165], v[214:217], v[40:43]
	v_mfma_f32_16x16x32_bf16 v[28:31], v[154:157], v[222:225], v[28:31]
	v_mfma_f32_16x16x32_bf16 v[24:27], v[162:165], v[222:225], v[24:27]
	v_mfma_f32_16x16x32_bf16 v[12:15], v[154:157], v[230:233], v[12:15]
	v_mfma_f32_16x16x32_bf16 v[8:11], v[162:165], v[230:233], v[8:11]
	v_mfma_f32_16x16x32_bf16 v[60:63], v[158:161], v[210:213], v[60:63]
	v_mfma_f32_16x16x32_bf16 v[56:59], v[186:189], v[210:213], v[56:59]
	v_mfma_f32_16x16x32_bf16 v[44:47], v[158:161], v[218:221], v[44:47]
	v_mfma_f32_16x16x32_bf16 v[40:43], v[186:189], v[218:221], v[40:43]
	v_mfma_f32_16x16x32_bf16 v[28:31], v[158:161], v[226:229], v[28:31]
	v_mfma_f32_16x16x32_bf16 v[24:27], v[186:189], v[226:229], v[24:27]
	v_mfma_f32_16x16x32_bf16 v[12:15], v[158:161], v[234:237], v[12:15]
	v_mfma_f32_16x16x32_bf16 v[8:11], v[186:189], v[234:237], v[8:11]
	s_setprio 0
	s_setprio 1
	v_mfma_f32_16x16x32_bf16 v[52:55], v[190:193], v[206:209], v[52:55]
	v_mfma_f32_16x16x32_bf16 v[48:51], v[198:201], v[206:209], v[48:51]
	v_mfma_f32_16x16x32_bf16 v[36:39], v[190:193], v[214:217], v[36:39]
	v_mfma_f32_16x16x32_bf16 v[32:35], v[198:201], v[214:217], v[32:35]
	v_mfma_f32_16x16x32_bf16 v[20:23], v[190:193], v[222:225], v[20:23]
	v_mfma_f32_16x16x32_bf16 v[16:19], v[198:201], v[222:225], v[16:19]
	v_mfma_f32_16x16x32_bf16 v[4:7], v[190:193], v[230:233], v[4:7]
	v_mfma_f32_16x16x32_bf16 v[0:3], v[198:201], v[230:233], v[0:3]
	v_mfma_f32_16x16x32_bf16 v[52:55], v[194:197], v[210:213], v[52:55]
	v_mfma_f32_16x16x32_bf16 v[48:51], v[202:205], v[210:213], v[48:51]
	v_mfma_f32_16x16x32_bf16 v[36:39], v[194:197], v[218:221], v[36:39]
	v_mfma_f32_16x16x32_bf16 v[32:35], v[202:205], v[218:221], v[32:35]
	v_mfma_f32_16x16x32_bf16 v[20:23], v[194:197], v[226:229], v[20:23]
	v_mfma_f32_16x16x32_bf16 v[16:19], v[202:205], v[226:229], v[16:19]
	v_mfma_f32_16x16x32_bf16 v[4:7], v[194:197], v[234:237], v[4:7]
	v_mfma_f32_16x16x32_bf16 v[0:3], v[202:205], v[234:237], v[0:3]
	s_setprio 0
	s_barrier
	s_add_i32 s56, 0, 0x18000
	v_add_u32_e32 v185, s56, v141
	s_add_i32 s57, 0, 0x1c000
	ds_read_b128 v[154:157], v185
	ds_read_b128 v[158:161], v185 offset:1024
	ds_read_b128 v[162:165], v185 offset:2048
	ds_read_b128 v[186:189], v185 offset:3072
	v_add_u32_e32 v185, s57, v141
	ds_read_b128 v[190:193], v185
	ds_read_b128 v[194:197], v185 offset:1024
	ds_read_b128 v[198:201], v185 offset:2048
	ds_read_b128 v[202:205], v185 offset:3072
	s_add_u32 s28, s28, s6
	s_addc_u32 s29, s29, s7
	s_mov_b32 m0, s40
	v_lshl_add_u64 v[246:247], s[28:29], 0, v[132:133]
	ds_read_b128 v[206:209], v143 offset:32768
	ds_read_b128 v[210:213], v143 offset:33792
	ds_read_b128 v[214:217], v143 offset:34816
	ds_read_b128 v[218:221], v143 offset:35840
	ds_read_b128 v[222:225], v143 offset:36864
	ds_read_b128 v[226:229], v143 offset:37888
	ds_read_b128 v[230:233], v143 offset:38912
	ds_read_b128 v[234:237], v143 offset:39936
	global_load_lds_dwordx4 v[246:247], off
	v_lshl_add_u64 v[246:247], s[28:29], 0, v[130:131]
	s_mov_b32 m0, s41
	s_nop 0
	global_load_lds_dwordx4 v[246:247], off
	s_waitcnt vmcnt(8)
	s_barrier
	s_setprio 1
	s_waitcnt lgkmcnt(0)
	v_mfma_f32_16x16x32_bf16 v[120:123], v[154:157], v[206:209], v[120:123]
	v_mfma_f32_16x16x32_bf16 v[124:127], v[162:165], v[206:209], v[124:127]
	v_mfma_f32_16x16x32_bf16 v[108:111], v[154:157], v[214:217], v[108:111]
	v_mfma_f32_16x16x32_bf16 v[104:107], v[162:165], v[214:217], v[104:107]
	v_mfma_f32_16x16x32_bf16 v[92:95], v[154:157], v[222:225], v[92:95]
	v_mfma_f32_16x16x32_bf16 v[88:91], v[162:165], v[222:225], v[88:91]
	v_mfma_f32_16x16x32_bf16 v[76:79], v[154:157], v[230:233], v[76:79]
	v_mfma_f32_16x16x32_bf16 v[72:75], v[162:165], v[230:233], v[72:75]
	v_mfma_f32_16x16x32_bf16 v[120:123], v[158:161], v[210:213], v[120:123]
	v_mfma_f32_16x16x32_bf16 v[124:127], v[186:189], v[210:213], v[124:127]
	v_mfma_f32_16x16x32_bf16 v[108:111], v[158:161], v[218:221], v[108:111]
	v_mfma_f32_16x16x32_bf16 v[104:107], v[186:189], v[218:221], v[104:107]
	v_mfma_f32_16x16x32_bf16 v[92:95], v[158:161], v[226:229], v[92:95]
	v_mfma_f32_16x16x32_bf16 v[88:91], v[186:189], v[226:229], v[88:91]
	v_mfma_f32_16x16x32_bf16 v[76:79], v[158:161], v[234:237], v[76:79]
	v_mfma_f32_16x16x32_bf16 v[72:75], v[186:189], v[234:237], v[72:75]
	s_setprio 0
	s_setprio 1
	v_mfma_f32_16x16x32_bf16 v[116:119], v[190:193], v[206:209], v[116:119]
	v_mfma_f32_16x16x32_bf16 v[112:115], v[198:201], v[206:209], v[112:115]
	v_mfma_f32_16x16x32_bf16 v[100:103], v[190:193], v[214:217], v[100:103]
	v_mfma_f32_16x16x32_bf16 v[96:99], v[198:201], v[214:217], v[96:99]
	v_mfma_f32_16x16x32_bf16 v[84:87], v[190:193], v[222:225], v[84:87]
	v_mfma_f32_16x16x32_bf16 v[80:83], v[198:201], v[222:225], v[80:83]
	v_mfma_f32_16x16x32_bf16 v[68:71], v[190:193], v[230:233], v[68:71]
	v_mfma_f32_16x16x32_bf16 v[64:67], v[198:201], v[230:233], v[64:67]
	v_mfma_f32_16x16x32_bf16 v[116:119], v[194:197], v[210:213], v[116:119]
	v_mfma_f32_16x16x32_bf16 v[112:115], v[202:205], v[210:213], v[112:115]
	v_mfma_f32_16x16x32_bf16 v[100:103], v[194:197], v[218:221], v[100:103]
	v_mfma_f32_16x16x32_bf16 v[96:99], v[202:205], v[218:221], v[96:99]
	v_mfma_f32_16x16x32_bf16 v[84:87], v[194:197], v[226:229], v[84:87]
	v_mfma_f32_16x16x32_bf16 v[80:83], v[202:205], v[226:229], v[80:83]
	v_mfma_f32_16x16x32_bf16 v[68:71], v[194:197], v[234:237], v[68:71]
	v_mfma_f32_16x16x32_bf16 v[64:67], v[202:205], v[234:237], v[64:67]
	s_setprio 0
	s_barrier
; #define PG8_STAGE(bufoff, gbase, voff) do { _Pragma("unroll") for (int _i = 0; _i < 2; ++_i) \
;         __builtin_amdgcn_global_load_lds((const unsigned*)((const char*)(gbase) + (voff)[_i]), (PG8_LAS unsigned*)(lds + (bufoff) + ldsw + _i * 8192), 16, 0, 0); } while (0)
; #define PG8_LDA(dst, b, h) do { _Pragma("unroll") for (int m = 0; m < 4; ++m) _Pragma("unroll") for (int k = 0; k < 2; ++k) dst[m][k] = *(const PG8_LAS bf16x8*)(lds + PG8_SA(b, h) + aoff + m * 2048 + k * 1024); } while (0)
; #define PG8_MMA(ai, bj, At, Bt) do { __builtin_amdgcn_s_setprio(1); _Pragma("unroll") for (int m = 0; m < 4; ++m) _Pragma("unroll") for (int n = 0; n < 2; ++n) _Pragma("unroll") for (int k = 0; k < 2; ++k) \
;         acc[ai][bj][m][n] = __builtin_amdgcn_mfma_f32_16x16x32_bf16(Bt[n][k], At[m][k], acc[ai][bj][m][n], 0, 0, 0); __builtin_amdgcn_s_setprio(0); } while (0)
; #define PG8_WAIT_V(n) asm volatile("s_waitcnt vmcnt(" #n ")" ::: "memory")
; #define PG8_WAIT_L(n) asm volatile("s_waitcnt lgkmcnt(" #n ")" ::: "memory")
; #define PG8_BAR __builtin_amdgcn_s_barrier()
; #define PG8_SCHED __builtin_amdgcn_sched_barrier(0)
; template <class Epi, class Sched>
; __device__ __forceinline__ void gemm_phase(int wid_s, PG8_LAS unsigned char* lds, const Gemm g, const Sched& S, const Epi& E) {
;     ...
;         for (int t = 0; t < nt; t += 2) {
;             const bool last = (t == nt - 2);
;             const char* a1 = cA + (size_t)(t + 1) * kstep;
;             const char* a2 = last ? nA : cA + (size_t)(t + 2) * kstep; const char* b2 = last ? nB : cB + (size_t)(t + 2) * kstep;
;             const char* a3 = a2 + kstep; const char* b3 = b2 + kstep;
;     ...
;             PG8_LDA(At, 1, 1); PG8_STAGE(PG8_SB(1, 0), b3, voffB); PG8_STAGE(PG8_SB(1, 1), b3 + hstepB, voffB); PG8_STAGE(PG8_SA(1, 0), a3, voffA);
;             PG8_WAIT_V(8); PG8_WAIT_L(0); PG8_BAR; PG8_MMA(1, 0, At, B0); PG8_MMA(1, 1, At, B1); PG8_BAR; PG8_SCHED;
	s_add_i32 s28, s56, s35
	v_lshl_add_u64 v[138:139], v[138:139], 0, s[96:97]
	s_mov_b32 m0, s28
	ds_read_b128 v[206:209], v143 offset:49152
	ds_read_b128 v[210:213], v143 offset:50176
	ds_read_b128 v[214:217], v143 offset:51200
	ds_read_b128 v[218:221], v143 offset:52224
	ds_read_b128 v[222:225], v143 offset:53248
	ds_read_b128 v[226:229], v143 offset:54272
	ds_read_b128 v[230:233], v143 offset:55296
	ds_read_b128 v[234:237], v143 offset:56320
	global_load_lds_dwordx4 v[138:139], off
	v_lshl_add_u64 v[138:139], v[166:167], 0, s[96:97]
	s_add_i32 m0, s28, 0x2000
	s_add_i32 s28, s57, s35
	global_load_lds_dwordx4 v[138:139], off
	v_lshl_add_u64 v[138:139], v[238:239], 0, s[96:97]
	s_mov_b32 m0, s28
	s_nop 0
	global_load_lds_dwordx4 v[138:139], off
	v_lshl_add_u64 v[138:139], v[240:241], 0, s[96:97]
	s_add_i32 m0, s28, 0x2000
	s_nop 0
	global_load_lds_dwordx4 v[138:139], off
	v_lshl_add_u64 v[138:139], v[242:243], 0, s[96:97]
	s_mov_b32 m0, s44
	s_nop 0
	global_load_lds_dwordx4 v[138:139], off
	v_lshl_add_u64 v[138:139], v[244:245], 0, s[96:97]
	s_mov_b32 m0, s45
	s_nop 0
	global_load_lds_dwordx4 v[138:139], off
	s_waitcnt vmcnt(8)
	s_barrier
	s_setprio 1
	s_waitcnt lgkmcnt(0)
	v_mfma_f32_16x16x32_bf16 v[60:63], v[154:157], v[206:209], v[60:63]
	v_mfma_f32_16x16x32_bf16 v[56:59], v[162:165], v[206:209], v[56:59]
	v_mfma_f32_16x16x32_bf16 v[44:47], v[154:157], v[214:217], v[44:47]
	v_mfma_f32_16x16x32_bf16 v[40:43], v[162:165], v[214:217], v[40:43]
	v_mfma_f32_16x16x32_bf16 v[28:31], v[154:157], v[222:225], v[28:31]
	v_mfma_f32_16x16x32_bf16 v[24:27], v[162:165], v[222:225], v[24:27]
	v_mfma_f32_16x16x32_bf16 v[12:15], v[154:157], v[230:233], v[12:15]
	v_mfma_f32_16x16x32_bf16 v[8:11], v[162:165], v[230:233], v[8:11]
	v_mfma_f32_16x16x32_bf16 v[60:63], v[158:161], v[210:213], v[60:63]
	v_mfma_f32_16x16x32_bf16 v[56:59], v[186:189], v[210:213], v[56:59]
	v_mfma_f32_16x16x32_bf16 v[44:47], v[158:161], v[218:221], v[44:47]
	v_mfma_f32_16x16x32_bf16 v[40:43], v[186:189], v[218:221], v[40:43]
	v_mfma_f32_16x16x32_bf16 v[28:31], v[158:161], v[226:229], v[28:31]
	v_mfma_f32_16x16x32_bf16 v[24:27], v[186:189], v[226:229], v[24:27]
	v_mfma_f32_16x16x32_bf16 v[12:15], v[158:161], v[234:237], v[12:15]
	v_mfma_f32_16x16x32_bf16 v[8:11], v[186:189], v[234:237], v[8:11]
	s_setprio 0
	s_setprio 1
	v_mfma_f32_16x16x32_bf16 v[52:55], v[190:193], v[206:209], v[52:55]
	v_mfma_f32_16x16x32_bf16 v[48:51], v[198:201], v[206:209], v[48:51]
	v_mfma_f32_16x16x32_bf16 v[36:39], v[190:193], v[214:217], v[36:39]
	v_mfma_f32_16x16x32_bf16 v[32:35], v[198:201], v[214:217], v[32:35]
	v_mfma_f32_16x16x32_bf16 v[20:23], v[190:193], v[222:225], v[20:23]
	v_mfma_f32_16x16x32_bf16 v[16:19], v[198:201], v[222:225], v[16:19]
	v_mfma_f32_16x16x32_bf16 v[4:7], v[190:193], v[230:233], v[4:7]
	v_mfma_f32_16x16x32_bf16 v[0:3], v[198:201], v[230:233], v[0:3]
	v_mfma_f32_16x16x32_bf16 v[52:55], v[194:197], v[210:213], v[52:55]
	v_mfma_f32_16x16x32_bf16 v[48:51], v[202:205], v[210:213], v[48:51]
	v_mfma_f32_16x16x32_bf16 v[36:39], v[194:197], v[218:221], v[36:39]
	v_mfma_f32_16x16x32_bf16 v[32:35], v[202:205], v[218:221], v[32:35]
	v_mfma_f32_16x16x32_bf16 v[20:23], v[194:197], v[226:229], v[20:23]
	v_mfma_f32_16x16x32_bf16 v[16:19], v[202:205], v[226:229], v[16:19]
	v_mfma_f32_16x16x32_bf16 v[4:7], v[194:197], v[234:237], v[4:7]
	v_mfma_f32_16x16x32_bf16 v[0:3], v[202:205], v[234:237], v[0:3]
	s_setprio 0
	s_barrier
	s_add_u32 s33, s33, 0x100
	s_addc_u32 s54, s54, 0
	s_add_u32 s26, s26, 0x100
	s_addc_u32 s27, s27, 0
	s_cmp_ge_i32 s55, s42
	s_mov_b32 s28, s55
	s_cbranch_scc0 .LBB0_1061
	v_readlane_b32 s54, v254, 52
	v_readlane_b32 s55, v254, 53
	v_readlane_b32 s92, v254, 54
	v_readlane_b32 s94, v254, 55
	s_movk_i32 s33, 0x300

; #define PG8_STAGE(bufoff, gbase, voff) do { _Pragma("unroll") for (int _i = 0; _i < 2; ++_i) \
;         __builtin_amdgcn_global_load_lds((const unsigned*)((const char*)(gbase) + (voff)[_i]), (PG8_LAS unsigned*)(lds + (bufoff) + ldsw + _i * 8192), 16, 0, 0); } while (0)
; #define PG8_LDA(dst, b, h) do { _Pragma("unroll") for (int m = 0; m < 4; ++m) _Pragma("unroll") for (int k = 0; k < 2; ++k) dst[m][k] = *(const PG8_LAS bf16x8*)(lds + PG8_SA(b, h) + aoff + m * 2048 + k * 1024); } while (0)
; #define PG8_LDB(dst, b, h) do { _Pragma("unroll") for (int n = 0; n < 2; ++n) _Pragma("unroll") for (int k = 0; k < 2; ++k) dst[n][k] = *(const PG8_LAS bf16x8*)(lds + PG8_SB(b, h) + boff + n * 2048 + k * 1024); } while (0)
; #define PG8_MMA(ai, bj, At, Bt) do { __builtin_amdgcn_s_setprio(1); _Pragma("unroll") for (int m = 0; m < 4; ++m) _Pragma("unroll") for (int n = 0; n < 2; ++n) _Pragma("unroll") for (int k = 0; k < 2; ++k) \
;         acc[ai][bj][m][n] = __builtin_amdgcn_mfma_f32_16x16x32_bf16(Bt[n][k], At[m][k], acc[ai][bj][m][n], 0, 0, 0); __builtin_amdgcn_s_setprio(0); } while (0)
; #define PG8_WAIT_V(n) asm volatile("s_waitcnt vmcnt(" #n ")" ::: "memory")
; #define PG8_WAIT_L(n) asm volatile("s_waitcnt lgkmcnt(" #n ")" ::: "memory")
; #define PG8_BAR __builtin_amdgcn_s_barrier()
; #define PG8_SCHED __builtin_amdgcn_sched_barrier(0)
; template <class Epi, class Sched>
; __device__ __forceinline__ void gemm_phase(int wid_s, PG8_LAS unsigned char* lds, const Gemm g, const Sched& S, const Epi& E) {
;     ...
;         for (int t = 0; t < nt; t += 2) {
;             const bool last = (t == nt - 2);
;             const char* a1 = cA + (size_t)(t + 1) * kstep;
;             const char* a2 = last ? nA : cA + (size_t)(t + 2) * kstep; const char* b2 = last ? nB : cB + (size_t)(t + 2) * kstep;
;             const char* a3 = a2 + kstep; const char* b3 = b2 + kstep;
;             PG8_LDB(B0, 0, 0); PG8_LDB(B1, 0, 1); PG8_SCHED; PG8_LDA(At, 0, 0); PG8_STAGE(PG8_SA(1, 1), a1 + hstepA, voffA);
;             PG8_WAIT_V(8); PG8_WAIT_L(0); PG8_BAR; PG8_MMA(0, 0, At, B0); PG8_MMA(0, 1, At, B1); PG8_BAR; PG8_SCHED;
;             PG8_LDA(At, 0, 1); PG8_STAGE(PG8_SB(0, 0), b2, voffB); PG8_STAGE(PG8_SB(0, 1), b2 + hstepB, voffB); PG8_STAGE(PG8_SA(0, 0), a2, voffA);
.LBB0_1093:
	s_add_i32 s33, s30, 2
	s_add_u32 s34, s4, 0x80
	s_addc_u32 s31, s5, 0
	s_add_i32 s50, 0, 0x10000
	s_cmp_eq_u32 s94, s30
	s_cselect_b32 s31, s27, s31
	s_cselect_b32 s30, s26, s34
	v_add_u32_e32 v144, s50, v162
	s_cselect_b32 s35, s29, s15
	s_cselect_b32 s34, s28, s14
	s_add_i32 s51, 0, 0x14000
	ds_read_b128 v[154:157], v144
	ds_read_b128 v[158:161], v144 offset:1024
	ds_read_b128 v[164:167], v144 offset:2048
	ds_read_b128 v[186:189], v144 offset:3072
	v_add_u32_e32 v144, s51, v162
	ds_read_b128 v[190:193], v144
	ds_read_b128 v[194:197], v144 offset:1024
	ds_read_b128 v[198:201], v144 offset:2048
	ds_read_b128 v[202:205], v144 offset:3072
	v_lshl_add_u64 v[238:239], s[4:5], 0, v[142:143]
	s_add_i32 m0, s46, 0xc000
	ds_read_b128 v[206:209], v163
	ds_read_b128 v[210:213], v163 offset:1024
	ds_read_b128 v[214:217], v163 offset:2048
	ds_read_b128 v[218:221], v163 offset:3072
	ds_read_b128 v[222:225], v163 offset:4096
	ds_read_b128 v[226:229], v163 offset:5120
	ds_read_b128 v[230:233], v163 offset:6144
	ds_read_b128 v[234:237], v163 offset:7168
	global_load_lds_dwordx4 v[238:239], off
	v_lshl_add_u64 v[238:239], s[4:5], 0, v[140:141]
	s_add_i32 m0, s46, 0xe000
	s_nop 0
	global_load_lds_dwordx4 v[238:239], off
	s_waitcnt vmcnt(8)
	s_barrier
	s_setprio 1
	s_waitcnt lgkmcnt(0)
	v_mfma_f32_16x16x32_bf16 v[120:123], v[154:157], v[206:209], v[120:123]
	v_mfma_f32_16x16x32_bf16 v[124:127], v[164:167], v[206:209], v[124:127]
	v_mfma_f32_16x16x32_bf16 v[108:111], v[154:157], v[214:217], v[108:111]
	v_mfma_f32_16x16x32_bf16 v[104:107], v[164:167], v[214:217], v[104:107]
	v_mfma_f32_16x16x32_bf16 v[92:95], v[154:157], v[222:225], v[92:95]
	v_mfma_f32_16x16x32_bf16 v[88:91], v[164:167], v[222:225], v[88:91]
	v_mfma_f32_16x16x32_bf16 v[76:79], v[154:157], v[230:233], v[76:79]
	v_mfma_f32_16x16x32_bf16 v[72:75], v[164:167], v[230:233], v[72:75]
	v_mfma_f32_16x16x32_bf16 v[120:123], v[158:161], v[210:213], v[120:123]
	v_mfma_f32_16x16x32_bf16 v[124:127], v[186:189], v[210:213], v[124:127]
	v_mfma_f32_16x16x32_bf16 v[108:111], v[158:161], v[218:221], v[108:111]
	v_mfma_f32_16x16x32_bf16 v[104:107], v[186:189], v[218:221], v[104:107]
	v_mfma_f32_16x16x32_bf16 v[92:95], v[158:161], v[226:229], v[92:95]
	v_mfma_f32_16x16x32_bf16 v[88:91], v[186:189], v[226:229], v[88:91]
	v_mfma_f32_16x16x32_bf16 v[76:79], v[158:161], v[234:237], v[76:79]
	v_mfma_f32_16x16x32_bf16 v[72:75], v[186:189], v[234:237], v[72:75]
	s_setprio 0
	s_setprio 1
	v_mfma_f32_16x16x32_bf16 v[116:119], v[190:193], v[206:209], v[116:119]
	v_mfma_f32_16x16x32_bf16 v[112:115], v[198:201], v[206:209], v[112:115]
	v_mfma_f32_16x16x32_bf16 v[100:103], v[190:193], v[214:217], v[100:103]
	v_mfma_f32_16x16x32_bf16 v[96:99], v[198:201], v[214:217], v[96:99]
	v_mfma_f32_16x16x32_bf16 v[84:87], v[190:193], v[222:225], v[84:87]
	v_mfma_f32_16x16x32_bf16 v[80:83], v[198:201], v[222:225], v[80:83]
	v_mfma_f32_16x16x32_bf16 v[68:71], v[190:193], v[230:233], v[68:71]
	v_mfma_f32_16x16x32_bf16 v[64:67], v[198:201], v[230:233], v[64:67]
	v_mfma_f32_16x16x32_bf16 v[116:119], v[194:197], v[210:213], v[116:119]
	v_mfma_f32_16x16x32_bf16 v[112:115], v[202:205], v[210:213], v[112:115]
	v_mfma_f32_16x16x32_bf16 v[100:103], v[194:197], v[218:221], v[100:103]
	v_mfma_f32_16x16x32_bf16 v[96:99], v[202:205], v[218:221], v[96:99]
	v_mfma_f32_16x16x32_bf16 v[84:87], v[194:197], v[226:229], v[84:87]
	v_mfma_f32_16x16x32_bf16 v[80:83], v[202:205], v[226:229], v[80:83]
	v_mfma_f32_16x16x32_bf16 v[68:71], v[194:197], v[234:237], v[68:71]
	v_mfma_f32_16x16x32_bf16 v[64:67], v[202:205], v[234:237], v[64:67]
	s_setprio 0
	s_barrier
	s_add_i32 s50, s50, s41
	v_lshl_add_u64 v[238:239], s[34:35], 0, v[130:131]
	s_mov_b32 m0, s50
	ds_read_b128 v[206:209], v163 offset:16384
	ds_read_b128 v[210:213], v163 offset:17408
	ds_read_b128 v[214:217], v163 offset:18432
	ds_read_b128 v[218:221], v163 offset:19456
	ds_read_b128 v[222:225], v163 offset:20480
	ds_read_b128 v[226:229], v163 offset:21504
	ds_read_b128 v[230:233], v163 offset:22528
	ds_read_b128 v[234:237], v163 offset:23552
	global_load_lds_dwordx4 v[238:239], off
	s_add_i32 m0, s50, 0x2000
	v_lshl_add_u64 v[240:241], s[34:35], 0, v[134:135]
	s_add_u32 s34, s34, s8
	s_addc_u32 s35, s35, s9
	s_add_i32 s50, s51, s41
	global_load_lds_dwordx4 v[240:241], off
	v_lshl_add_u64 v[242:243], s[34:35], 0, v[130:131]
	s_mov_b32 m0, s50
	v_lshl_add_u64 v[244:245], s[34:35], 0, v[134:135]
	global_load_lds_dwordx4 v[242:243], off
	s_add_i32 m0, s50, 0x2000
	v_lshl_add_u64 v[246:247], s[30:31], 0, v[128:129]
	global_load_lds_dwordx4 v[244:245], off
	s_mov_b32 m0, s46
	v_lshl_add_u64 v[248:249], s[30:31], 0, v[132:133]
	global_load_lds_dwordx4 v[246:247], off
	s_mov_b32 m0, s47
	s_nop 0
	global_load_lds_dwordx4 v[248:249], off
	s_waitcnt vmcnt(8)
	s_barrier
; #define PG8_STAGE(bufoff, gbase, voff) do { _Pragma("unroll") for (int _i = 0; _i < 2; ++_i) \
;         __builtin_amdgcn_global_load_lds((const unsigned*)((const char*)(gbase) + (voff)[_i]), (PG8_LAS unsigned*)(lds + (bufoff) + ldsw + _i * 8192), 16, 0, 0); } while (0)
; #define PG8_LDA(dst, b, h) do { _Pragma("unroll") for (int m = 0; m < 4; ++m) _Pragma("unroll") for (int k = 0; k < 2; ++k) dst[m][k] = *(const PG8_LAS bf16x8*)(lds + PG8_SA(b, h) + aoff + m * 2048 + k * 1024); } while (0)
; #define PG8_LDB(dst, b, h) do { _Pragma("unroll") for (int n = 0; n < 2; ++n) _Pragma("unroll") for (int k = 0; k < 2; ++k) dst[n][k] = *(const PG8_LAS bf16x8*)(lds + PG8_SB(b, h) + boff + n * 2048 + k * 1024); } while (0)
; #define PG8_MMA(ai, bj, At, Bt) do { __builtin_amdgcn_s_setprio(1); _Pragma("unroll") for (int m = 0; m < 4; ++m) _Pragma("unroll") for (int n = 0; n < 2; ++n) _Pragma("unroll") for (int k = 0; k < 2; ++k) \
;         acc[ai][bj][m][n] = __builtin_amdgcn_mfma_f32_16x16x32_bf16(Bt[n][k], At[m][k], acc[ai][bj][m][n], 0, 0, 0); __builtin_amdgcn_s_setprio(0); } while (0)
; #define PG8_WAIT_V(n) asm volatile("s_waitcnt vmcnt(" #n ")" ::: "memory")
; #define PG8_WAIT_L(n) asm volatile("s_waitcnt lgkmcnt(" #n ")" ::: "memory")
; #define PG8_BAR __builtin_amdgcn_s_barrier()
; #define PG8_SCHED __builtin_amdgcn_sched_barrier(0)
; template <class Epi, class Sched>
; __device__ __forceinline__ void gemm_phase(int wid_s, PG8_LAS unsigned char* lds, const Gemm g, const Sched& S, const Epi& E) {
;     ...
;             PG8_WAIT_V(8); PG8_WAIT_L(0); PG8_BAR; PG8_MMA(1, 0, At, B0); PG8_MMA(1, 1, At, B1); PG8_BAR; PG8_SCHED;
;             PG8_LDB(B0, 1, 0); PG8_LDB(B1, 1, 1); PG8_SCHED; PG8_LDA(At, 1, 0); PG8_STAGE(PG8_SA(0, 1), a2 + hstepA, voffA);
;             PG8_WAIT_V(8); PG8_WAIT_L(0); PG8_BAR; PG8_MMA(0, 0, At, B0); PG8_MMA(0, 1, At, B1); PG8_BAR; PG8_SCHED;
	s_setprio 1
	s_waitcnt lgkmcnt(0)
	v_mfma_f32_16x16x32_bf16 v[60:63], v[154:157], v[206:209], v[60:63]
	v_mfma_f32_16x16x32_bf16 v[56:59], v[164:167], v[206:209], v[56:59]
	v_mfma_f32_16x16x32_bf16 v[44:47], v[154:157], v[214:217], v[44:47]
	v_mfma_f32_16x16x32_bf16 v[40:43], v[164:167], v[214:217], v[40:43]
	v_mfma_f32_16x16x32_bf16 v[28:31], v[154:157], v[222:225], v[28:31]
	v_mfma_f32_16x16x32_bf16 v[24:27], v[164:167], v[222:225], v[24:27]
	v_mfma_f32_16x16x32_bf16 v[12:15], v[154:157], v[230:233], v[12:15]
	v_mfma_f32_16x16x32_bf16 v[8:11], v[164:167], v[230:233], v[8:11]
	v_mfma_f32_16x16x32_bf16 v[60:63], v[158:161], v[210:213], v[60:63]
	v_mfma_f32_16x16x32_bf16 v[56:59], v[186:189], v[210:213], v[56:59]
	v_mfma_f32_16x16x32_bf16 v[44:47], v[158:161], v[218:221], v[44:47]
	v_mfma_f32_16x16x32_bf16 v[40:43], v[186:189], v[218:221], v[40:43]
	v_mfma_f32_16x16x32_bf16 v[28:31], v[158:161], v[226:229], v[28:31]
	v_mfma_f32_16x16x32_bf16 v[24:27], v[186:189], v[226:229], v[24:27]
	v_mfma_f32_16x16x32_bf16 v[12:15], v[158:161], v[234:237], v[12:15]
	v_mfma_f32_16x16x32_bf16 v[8:11], v[186:189], v[234:237], v[8:11]
	s_setprio 0
	s_setprio 1
	v_mfma_f32_16x16x32_bf16 v[52:55], v[190:193], v[206:209], v[52:55]
	v_mfma_f32_16x16x32_bf16 v[48:51], v[198:201], v[206:209], v[48:51]
	v_mfma_f32_16x16x32_bf16 v[36:39], v[190:193], v[214:217], v[36:39]
	v_mfma_f32_16x16x32_bf16 v[32:35], v[198:201], v[214:217], v[32:35]
	v_mfma_f32_16x16x32_bf16 v[20:23], v[190:193], v[222:225], v[20:23]
	v_mfma_f32_16x16x32_bf16 v[16:19], v[198:201], v[222:225], v[16:19]
	v_mfma_f32_16x16x32_bf16 v[4:7], v[190:193], v[230:233], v[4:7]
	v_mfma_f32_16x16x32_bf16 v[0:3], v[198:201], v[230:233], v[0:3]
	v_mfma_f32_16x16x32_bf16 v[52:55], v[194:197], v[210:213], v[52:55]
	v_mfma_f32_16x16x32_bf16 v[48:51], v[202:205], v[210:213], v[48:51]
	v_mfma_f32_16x16x32_bf16 v[36:39], v[194:197], v[218:221], v[36:39]
	v_mfma_f32_16x16x32_bf16 v[32:35], v[202:205], v[218:221], v[32:35]
	v_mfma_f32_16x16x32_bf16 v[20:23], v[194:197], v[226:229], v[20:23]
	v_mfma_f32_16x16x32_bf16 v[16:19], v[202:205], v[226:229], v[16:19]
	v_mfma_f32_16x16x32_bf16 v[4:7], v[194:197], v[234:237], v[4:7]
	v_mfma_f32_16x16x32_bf16 v[0:3], v[202:205], v[234:237], v[0:3]
	s_setprio 0
	s_barrier
	s_add_i32 s34, 0, 0x18000
	v_add_u32_e32 v144, s34, v162
	s_add_i32 s35, 0, 0x1c000
	ds_read_b128 v[154:157], v144
	ds_read_b128 v[158:161], v144 offset:1024
	ds_read_b128 v[164:167], v144 offset:2048
	ds_read_b128 v[186:189], v144 offset:3072
	v_add_u32_e32 v144, s35, v162
	ds_read_b128 v[190:193], v144
	ds_read_b128 v[194:197], v144 offset:1024
	ds_read_b128 v[198:201], v144 offset:2048
	ds_read_b128 v[202:205], v144 offset:3072
	s_add_u32 s30, s30, s6
	s_addc_u32 s31, s31, s7
	s_mov_b32 m0, s53
	v_lshl_add_u64 v[250:251], s[30:31], 0, v[128:129]
	ds_read_b128 v[206:209], v163 offset:32768
	ds_read_b128 v[210:213], v163 offset:33792
	ds_read_b128 v[214:217], v163 offset:34816
	ds_read_b128 v[218:221], v163 offset:35840
	ds_read_b128 v[222:225], v163 offset:36864
	ds_read_b128 v[226:229], v163 offset:37888
	ds_read_b128 v[230:233], v163 offset:38912
	ds_read_b128 v[234:237], v163 offset:39936
	global_load_lds_dwordx4 v[250:251], off
	v_lshl_add_u64 v[250:251], s[30:31], 0, v[132:133]
	s_mov_b32 m0, s54
	s_nop 0
	global_load_lds_dwordx4 v[250:251], off
	s_waitcnt vmcnt(8)
	s_barrier
	s_setprio 1
	s_waitcnt lgkmcnt(0)
	v_mfma_f32_16x16x32_bf16 v[120:123], v[154:157], v[206:209], v[120:123]
	v_mfma_f32_16x16x32_bf16 v[124:127], v[164:167], v[206:209], v[124:127]
	v_mfma_f32_16x16x32_bf16 v[108:111], v[154:157], v[214:217], v[108:111]
	v_mfma_f32_16x16x32_bf16 v[104:107], v[164:167], v[214:217], v[104:107]
	v_mfma_f32_16x16x32_bf16 v[92:95], v[154:157], v[222:225], v[92:95]
	v_mfma_f32_16x16x32_bf16 v[88:91], v[164:167], v[222:225], v[88:91]
	v_mfma_f32_16x16x32_bf16 v[76:79], v[154:157], v[230:233], v[76:79]
	v_mfma_f32_16x16x32_bf16 v[72:75], v[164:167], v[230:233], v[72:75]
	v_mfma_f32_16x16x32_bf16 v[120:123], v[158:161], v[210:213], v[120:123]
	v_mfma_f32_16x16x32_bf16 v[124:127], v[186:189], v[210:213], v[124:127]
	v_mfma_f32_16x16x32_bf16 v[108:111], v[158:161], v[218:221], v[108:111]
	v_mfma_f32_16x16x32_bf16 v[104:107], v[186:189], v[218:221], v[104:107]
	v_mfma_f32_16x16x32_bf16 v[92:95], v[158:161], v[226:229], v[92:95]
	v_mfma_f32_16x16x32_bf16 v[88:91], v[186:189], v[226:229], v[88:91]
	v_mfma_f32_16x16x32_bf16 v[76:79], v[158:161], v[234:237], v[76:79]
	v_mfma_f32_16x16x32_bf16 v[72:75], v[186:189], v[234:237], v[72:75]
	s_setprio 0
	s_setprio 1
	v_mfma_f32_16x16x32_bf16 v[116:119], v[190:193], v[206:209], v[116:119]
	v_mfma_f32_16x16x32_bf16 v[112:115], v[198:201], v[206:209], v[112:115]
	v_mfma_f32_16x16x32_bf16 v[100:103], v[190:193], v[214:217], v[100:103]
	v_mfma_f32_16x16x32_bf16 v[96:99], v[198:201], v[214:217], v[96:99]
	v_mfma_f32_16x16x32_bf16 v[84:87], v[190:193], v[222:225], v[84:87]
	v_mfma_f32_16x16x32_bf16 v[80:83], v[198:201], v[222:225], v[80:83]
	v_mfma_f32_16x16x32_bf16 v[68:71], v[190:193], v[230:233], v[68:71]
	v_mfma_f32_16x16x32_bf16 v[64:67], v[198:201], v[230:233], v[64:67]
	v_mfma_f32_16x16x32_bf16 v[116:119], v[194:197], v[210:213], v[116:119]
	v_mfma_f32_16x16x32_bf16 v[112:115], v[202:205], v[210:213], v[112:115]
	v_mfma_f32_16x16x32_bf16 v[100:103], v[194:197], v[218:221], v[100:103]
	v_mfma_f32_16x16x32_bf16 v[96:99], v[202:205], v[218:221], v[96:99]
	v_mfma_f32_16x16x32_bf16 v[84:87], v[194:197], v[226:229], v[84:87]
	v_mfma_f32_16x16x32_bf16 v[80:83], v[202:205], v[226:229], v[80:83]
	v_mfma_f32_16x16x32_bf16 v[68:71], v[194:197], v[234:237], v[68:71]
	v_mfma_f32_16x16x32_bf16 v[64:67], v[202:205], v[234:237], v[64:67]
	s_setprio 0
	s_barrier
; #define PG8_STAGE(bufoff, gbase, voff) do { _Pragma("unroll") for (int _i = 0; _i < 2; ++_i) \
;         __builtin_amdgcn_global_load_lds((const unsigned*)((const char*)(gbase) + (voff)[_i]), (PG8_LAS unsigned*)(lds + (bufoff) + ldsw + _i * 8192), 16, 0, 0); } while (0)
; #define PG8_LDA(dst, b, h) do { _Pragma("unroll") for (int m = 0; m < 4; ++m) _Pragma("unroll") for (int k = 0; k < 2; ++k) dst[m][k] = *(const PG8_LAS bf16x8*)(lds + PG8_SA(b, h) + aoff + m * 2048 + k * 1024); } while (0)
; #define PG8_MMA(ai, bj, At, Bt) do { __builtin_amdgcn_s_setprio(1); _Pragma("unroll") for (int m = 0; m < 4; ++m) _Pragma("unroll") for (int n = 0; n < 2; ++n) _Pragma("unroll") for (int k = 0; k < 2; ++k) \
;         acc[ai][bj][m][n] = __builtin_amdgcn_mfma_f32_16x16x32_bf16(Bt[n][k], At[m][k], acc[ai][bj][m][n], 0, 0, 0); __builtin_amdgcn_s_setprio(0); } while (0)
; #define PG8_WAIT_V(n) asm volatile("s_waitcnt vmcnt(" #n ")" ::: "memory")
; #define PG8_WAIT_L(n) asm volatile("s_waitcnt lgkmcnt(" #n ")" ::: "memory")
; #define PG8_BAR __builtin_amdgcn_s_barrier()
; #define PG8_SCHED __builtin_amdgcn_sched_barrier(0)
; template <class Epi, class Sched>
; __device__ __forceinline__ void gemm_phase(int wid_s, PG8_LAS unsigned char* lds, const Gemm g, const Sched& S, const Epi& E) {
;     ...
;             PG8_LDA(At, 1, 1); PG8_STAGE(PG8_SB(1, 0), b3, voffB); PG8_STAGE(PG8_SB(1, 1), b3 + hstepB, voffB); PG8_STAGE(PG8_SA(1, 0), a3, voffA);
;             PG8_WAIT_V(8); PG8_WAIT_L(0); PG8_BAR; PG8_MMA(1, 0, At, B0); PG8_MMA(1, 1, At, B1); PG8_BAR; PG8_SCHED;
;         }
	s_add_i32 s30, s34, s41
	v_lshl_add_u64 v[238:239], v[238:239], 0, s[96:97]
	s_mov_b32 m0, s30
	ds_read_b128 v[206:209], v163 offset:49152
	ds_read_b128 v[210:213], v163 offset:50176
	ds_read_b128 v[214:217], v163 offset:51200
	ds_read_b128 v[218:221], v163 offset:52224
	ds_read_b128 v[222:225], v163 offset:53248
	ds_read_b128 v[226:229], v163 offset:54272
	ds_read_b128 v[230:233], v163 offset:55296
	ds_read_b128 v[234:237], v163 offset:56320
	global_load_lds_dwordx4 v[238:239], off
	v_lshl_add_u64 v[238:239], v[240:241], 0, s[96:97]
	s_add_i32 m0, s30, 0x2000
	s_add_i32 s30, s35, s41
	global_load_lds_dwordx4 v[238:239], off
	v_lshl_add_u64 v[238:239], v[242:243], 0, s[96:97]
	s_mov_b32 m0, s30
	s_nop 0
	global_load_lds_dwordx4 v[238:239], off
	v_lshl_add_u64 v[238:239], v[244:245], 0, s[96:97]
	s_add_i32 m0, s30, 0x2000
	s_nop 0
	global_load_lds_dwordx4 v[238:239], off
	v_lshl_add_u64 v[238:239], v[246:247], 0, s[96:97]
	s_mov_b32 m0, s55
	s_nop 0
	global_load_lds_dwordx4 v[238:239], off
	v_lshl_add_u64 v[238:239], v[248:249], 0, s[96:97]
	s_mov_b32 m0, s56
	s_nop 0
	global_load_lds_dwordx4 v[238:239], off
	s_waitcnt vmcnt(8)
	s_barrier
	s_setprio 1
	s_waitcnt lgkmcnt(0)
	v_mfma_f32_16x16x32_bf16 v[60:63], v[154:157], v[206:209], v[60:63]
	v_mfma_f32_16x16x32_bf16 v[56:59], v[164:167], v[206:209], v[56:59]
	v_mfma_f32_16x16x32_bf16 v[44:47], v[154:157], v[214:217], v[44:47]
	v_mfma_f32_16x16x32_bf16 v[40:43], v[164:167], v[214:217], v[40:43]
	v_mfma_f32_16x16x32_bf16 v[28:31], v[154:157], v[222:225], v[28:31]
	v_mfma_f32_16x16x32_bf16 v[24:27], v[164:167], v[222:225], v[24:27]
	v_mfma_f32_16x16x32_bf16 v[12:15], v[154:157], v[230:233], v[12:15]
	v_mfma_f32_16x16x32_bf16 v[8:11], v[164:167], v[230:233], v[8:11]
	v_mfma_f32_16x16x32_bf16 v[60:63], v[158:161], v[210:213], v[60:63]
	v_mfma_f32_16x16x32_bf16 v[56:59], v[186:189], v[210:213], v[56:59]
	v_mfma_f32_16x16x32_bf16 v[44:47], v[158:161], v[218:221], v[44:47]
	v_mfma_f32_16x16x32_bf16 v[40:43], v[186:189], v[218:221], v[40:43]
	v_mfma_f32_16x16x32_bf16 v[28:31], v[158:161], v[226:229], v[28:31]
	v_mfma_f32_16x16x32_bf16 v[24:27], v[186:189], v[226:229], v[24:27]
	v_mfma_f32_16x16x32_bf16 v[12:15], v[158:161], v[234:237], v[12:15]
	v_mfma_f32_16x16x32_bf16 v[8:11], v[186:189], v[234:237], v[8:11]
	s_setprio 0
	s_setprio 1
	v_mfma_f32_16x16x32_bf16 v[52:55], v[190:193], v[206:209], v[52:55]
	v_mfma_f32_16x16x32_bf16 v[48:51], v[198:201], v[206:209], v[48:51]
	v_mfma_f32_16x16x32_bf16 v[36:39], v[190:193], v[214:217], v[36:39]
	v_mfma_f32_16x16x32_bf16 v[32:35], v[198:201], v[214:217], v[32:35]
	v_mfma_f32_16x16x32_bf16 v[20:23], v[190:193], v[222:225], v[20:23]
	v_mfma_f32_16x16x32_bf16 v[16:19], v[198:201], v[222:225], v[16:19]
	v_mfma_f32_16x16x32_bf16 v[4:7], v[190:193], v[230:233], v[4:7]
	v_mfma_f32_16x16x32_bf16 v[0:3], v[198:201], v[230:233], v[0:3]
	v_mfma_f32_16x16x32_bf16 v[52:55], v[194:197], v[210:213], v[52:55]
	v_mfma_f32_16x16x32_bf16 v[48:51], v[202:205], v[210:213], v[48:51]
	v_mfma_f32_16x16x32_bf16 v[36:39], v[194:197], v[218:221], v[36:39]
	v_mfma_f32_16x16x32_bf16 v[32:35], v[202:205], v[218:221], v[32:35]
	v_mfma_f32_16x16x32_bf16 v[20:23], v[194:197], v[226:229], v[20:23]
	v_mfma_f32_16x16x32_bf16 v[16:19], v[202:205], v[226:229], v[16:19]
	v_mfma_f32_16x16x32_bf16 v[4:7], v[194:197], v[234:237], v[4:7]
	v_mfma_f32_16x16x32_bf16 v[0:3], v[202:205], v[234:237], v[0:3]
	s_setprio 0
	s_barrier
	s_add_u32 s14, s14, 0x100
	s_addc_u32 s15, s15, 0
	s_add_u32 s4, s4, 0x100
	s_addc_u32 s5, s5, 0
	s_cmp_ge_i32 s33, s57
	s_mov_b32 s30, s33
	s_cbranch_scc0 .LBB0_1093
	s_movk_i32 s51, 0x1000

; #define PG8_STAGE(bufoff, gbase, voff) do { _Pragma("unroll") for (int _i = 0; _i < 2; ++_i) \
;         __builtin_amdgcn_global_load_lds((const unsigned*)((const char*)(gbase) + (voff)[_i]), (PG8_LAS unsigned*)(lds + (bufoff) + ldsw + _i * 8192), 16, 0, 0); } while (0)
; #define PG8_LDA(dst, b, h) do { _Pragma("unroll") for (int m = 0; m < 4; ++m) _Pragma("unroll") for (int k = 0; k < 2; ++k) dst[m][k] = *(const PG8_LAS bf16x8*)(lds + PG8_SA(b, h) + aoff + m * 2048 + k * 1024); } while (0)
; #define PG8_LDB(dst, b, h) do { _Pragma("unroll") for (int n = 0; n < 2; ++n) _Pragma("unroll") for (int k = 0; k < 2; ++k) dst[n][k] = *(const PG8_LAS bf16x8*)(lds + PG8_SB(b, h) + boff + n * 2048 + k * 1024); } while (0)
; #define PG8_MMA(ai, bj, At, Bt) do { __builtin_amdgcn_s_setprio(1); _Pragma("unroll") for (int m = 0; m < 4; ++m) _Pragma("unroll") for (int n = 0; n < 2; ++n) _Pragma("unroll") for (int k = 0; k < 2; ++k) \
;         acc[ai][bj][m][n] = __builtin_amdgcn_mfma_f32_16x16x32_bf16(Bt[n][k], At[m][k], acc[ai][bj][m][n], 0, 0, 0); __builtin_amdgcn_s_setprio(0); } while (0)
; #define PG8_WAIT_V(n) asm volatile("s_waitcnt vmcnt(" #n ")" ::: "memory")
; #define PG8_WAIT_L(n) asm volatile("s_waitcnt lgkmcnt(" #n ")" ::: "memory")
; #define PG8_BAR __builtin_amdgcn_s_barrier()
; #define PG8_SCHED __builtin_amdgcn_sched_barrier(0)
; template <class Epi, class Sched>
; __device__ __forceinline__ void gemm_phase(int wid_s, PG8_LAS unsigned char* lds, const Gemm g, const Sched& S, const Epi& E) {
;     ...
;             const bool last = (t == nt - 2);
;             const char* a1 = cA + (size_t)(t + 1) * kstep;
;             const char* a2 = last ? nA : cA + (size_t)(t + 2) * kstep; const char* b2 = last ? nB : cB + (size_t)(t + 2) * kstep;
;             const char* a3 = a2 + kstep; const char* b3 = b2 + kstep;
;             PG8_LDB(B0, 0, 0); PG8_LDB(B1, 0, 1); PG8_SCHED; PG8_LDA(At, 0, 0); PG8_STAGE(PG8_SA(1, 1), a1 + hstepA, voffA);
;             PG8_WAIT_V(8); PG8_WAIT_L(0); PG8_BAR; PG8_MMA(0, 0, At, B0); PG8_MMA(0, 1, At, B1); PG8_BAR; PG8_SCHED;
;             PG8_LDA(At, 0, 1); PG8_STAGE(PG8_SB(0, 0), b2, voffB); PG8_STAGE(PG8_SB(0, 1), b2 + hstepB, voffB); PG8_STAGE(PG8_SA(0, 0), a2, voffA);
.LBB0_1229:
	s_add_i32 s55, s26, 2
	s_add_u32 s56, s24, 0x80
	s_addc_u32 s27, s25, 0
	s_add_i32 s92, 0, 0x10000
	s_cmp_eq_u32 s48, s26
	s_cselect_b32 s27, s5, s27
	s_cselect_b32 s26, s4, s56
	v_add_u32_e32 v142, s92, v139
	s_cselect_b32 s57, s23, s54
	s_cselect_b32 s56, s22, s33
	s_add_i32 s94, 0, 0x14000
	ds_read_b128 v[154:157], v142
	ds_read_b128 v[158:161], v142 offset:1024
	ds_read_b128 v[162:165], v142 offset:2048
	ds_read_b128 v[186:189], v142 offset:3072
	v_add_u32_e32 v142, s94, v139
	ds_read_b128 v[190:193], v142
	ds_read_b128 v[194:197], v142 offset:1024
	ds_read_b128 v[198:201], v142 offset:2048
	ds_read_b128 v[202:205], v142 offset:3072
	v_lshl_add_u64 v[142:143], s[24:25], 0, v[136:137]
	s_add_i32 m0, s36, 0xc000
	ds_read_b128 v[206:209], v141
	ds_read_b128 v[210:213], v141 offset:1024
	ds_read_b128 v[214:217], v141 offset:2048
	ds_read_b128 v[218:221], v141 offset:3072
	ds_read_b128 v[222:225], v141 offset:4096
	ds_read_b128 v[226:229], v141 offset:5120
	ds_read_b128 v[230:233], v141 offset:6144
	ds_read_b128 v[234:237], v141 offset:7168
	global_load_lds_dwordx4 v[142:143], off
	v_lshl_add_u64 v[142:143], s[24:25], 0, v[134:135]
	s_add_i32 m0, s36, 0xe000
	s_nop 0
	global_load_lds_dwordx4 v[142:143], off
	s_waitcnt vmcnt(8)
	s_barrier
	s_setprio 1
	s_waitcnt lgkmcnt(0)
	v_mfma_f32_16x16x32_bf16 v[120:123], v[154:157], v[206:209], v[120:123]
	v_mfma_f32_16x16x32_bf16 v[124:127], v[162:165], v[206:209], v[124:127]
	v_mfma_f32_16x16x32_bf16 v[108:111], v[154:157], v[214:217], v[108:111]
	v_mfma_f32_16x16x32_bf16 v[104:107], v[162:165], v[214:217], v[104:107]
	v_mfma_f32_16x16x32_bf16 v[92:95], v[154:157], v[222:225], v[92:95]
	v_mfma_f32_16x16x32_bf16 v[88:91], v[162:165], v[222:225], v[88:91]
	v_mfma_f32_16x16x32_bf16 v[76:79], v[154:157], v[230:233], v[76:79]
	v_mfma_f32_16x16x32_bf16 v[72:75], v[162:165], v[230:233], v[72:75]
	v_mfma_f32_16x16x32_bf16 v[120:123], v[158:161], v[210:213], v[120:123]
	v_mfma_f32_16x16x32_bf16 v[124:127], v[186:189], v[210:213], v[124:127]
	v_mfma_f32_16x16x32_bf16 v[108:111], v[158:161], v[218:221], v[108:111]
	v_mfma_f32_16x16x32_bf16 v[104:107], v[186:189], v[218:221], v[104:107]
	v_mfma_f32_16x16x32_bf16 v[92:95], v[158:161], v[226:229], v[92:95]
	v_mfma_f32_16x16x32_bf16 v[88:91], v[186:189], v[226:229], v[88:91]
	v_mfma_f32_16x16x32_bf16 v[76:79], v[158:161], v[234:237], v[76:79]
	v_mfma_f32_16x16x32_bf16 v[72:75], v[186:189], v[234:237], v[72:75]
	s_setprio 0
	s_setprio 1
	v_mfma_f32_16x16x32_bf16 v[116:119], v[190:193], v[206:209], v[116:119]
	v_mfma_f32_16x16x32_bf16 v[112:115], v[198:201], v[206:209], v[112:115]
	v_mfma_f32_16x16x32_bf16 v[100:103], v[190:193], v[214:217], v[100:103]
	v_mfma_f32_16x16x32_bf16 v[96:99], v[198:201], v[214:217], v[96:99]
	v_mfma_f32_16x16x32_bf16 v[84:87], v[190:193], v[222:225], v[84:87]
	v_mfma_f32_16x16x32_bf16 v[80:83], v[198:201], v[222:225], v[80:83]
	v_mfma_f32_16x16x32_bf16 v[68:71], v[190:193], v[230:233], v[68:71]
	v_mfma_f32_16x16x32_bf16 v[64:67], v[198:201], v[230:233], v[64:67]
	v_mfma_f32_16x16x32_bf16 v[116:119], v[194:197], v[210:213], v[116:119]
	v_mfma_f32_16x16x32_bf16 v[112:115], v[202:205], v[210:213], v[112:115]
	v_mfma_f32_16x16x32_bf16 v[100:103], v[194:197], v[218:221], v[100:103]
	v_mfma_f32_16x16x32_bf16 v[96:99], v[202:205], v[218:221], v[96:99]
	v_mfma_f32_16x16x32_bf16 v[84:87], v[194:197], v[226:229], v[84:87]
	v_mfma_f32_16x16x32_bf16 v[80:83], v[202:205], v[226:229], v[80:83]
	v_mfma_f32_16x16x32_bf16 v[68:71], v[194:197], v[234:237], v[68:71]
	v_mfma_f32_16x16x32_bf16 v[64:67], v[202:205], v[234:237], v[64:67]
	s_setprio 0
	s_barrier
	s_add_i32 s92, s92, s34
	v_lshl_add_u64 v[142:143], s[56:57], 0, v[144:145]
	s_mov_b32 m0, s92
	ds_read_b128 v[206:209], v141 offset:16384
	ds_read_b128 v[210:213], v141 offset:17408
	ds_read_b128 v[214:217], v141 offset:18432
	ds_read_b128 v[218:221], v141 offset:19456
	ds_read_b128 v[222:225], v141 offset:20480
	ds_read_b128 v[226:229], v141 offset:21504
	ds_read_b128 v[230:233], v141 offset:22528
	ds_read_b128 v[234:237], v141 offset:23552
	global_load_lds_dwordx4 v[142:143], off
	s_add_i32 m0, s92, 0x2000
	v_lshl_add_u64 v[166:167], s[56:57], 0, v[128:129]
	s_add_u32 s56, s56, s8
	s_addc_u32 s57, s57, s9
	s_add_i32 s92, s94, s34
	global_load_lds_dwordx4 v[166:167], off
	v_lshl_add_u64 v[238:239], s[56:57], 0, v[144:145]
	s_mov_b32 m0, s92
	v_lshl_add_u64 v[240:241], s[56:57], 0, v[128:129]
	global_load_lds_dwordx4 v[238:239], off
	s_add_i32 m0, s92, 0x2000
	v_lshl_add_u64 v[242:243], s[26:27], 0, v[132:133]
	global_load_lds_dwordx4 v[240:241], off
	s_mov_b32 m0, s36
	v_lshl_add_u64 v[244:245], s[26:27], 0, v[130:131]
	global_load_lds_dwordx4 v[242:243], off
	s_mov_b32 m0, s37
	s_nop 0
	global_load_lds_dwordx4 v[244:245], off
	s_waitcnt vmcnt(8)
	s_barrier
; #define PG8_STAGE(bufoff, gbase, voff) do { _Pragma("unroll") for (int _i = 0; _i < 2; ++_i) \
;         __builtin_amdgcn_global_load_lds((const unsigned*)((const char*)(gbase) + (voff)[_i]), (PG8_LAS unsigned*)(lds + (bufoff) + ldsw + _i * 8192), 16, 0, 0); } while (0)
; #define PG8_LDA(dst, b, h) do { _Pragma("unroll") for (int m = 0; m < 4; ++m) _Pragma("unroll") for (int k = 0; k < 2; ++k) dst[m][k] = *(const PG8_LAS bf16x8*)(lds + PG8_SA(b, h) + aoff + m * 2048 + k * 1024); } while (0)
; #define PG8_LDB(dst, b, h) do { _Pragma("unroll") for (int n = 0; n < 2; ++n) _Pragma("unroll") for (int k = 0; k < 2; ++k) dst[n][k] = *(const PG8_LAS bf16x8*)(lds + PG8_SB(b, h) + boff + n * 2048 + k * 1024); } while (0)
; #define PG8_MMA(ai, bj, At, Bt) do { __builtin_amdgcn_s_setprio(1); _Pragma("unroll") for (int m = 0; m < 4; ++m) _Pragma("unroll") for (int n = 0; n < 2; ++n) _Pragma("unroll") for (int k = 0; k < 2; ++k) \
;         acc[ai][bj][m][n] = __builtin_amdgcn_mfma_f32_16x16x32_bf16(Bt[n][k], At[m][k], acc[ai][bj][m][n], 0, 0, 0); __builtin_amdgcn_s_setprio(0); } while (0)
; #define PG8_WAIT_V(n) asm volatile("s_waitcnt vmcnt(" #n ")" ::: "memory")
; #define PG8_WAIT_L(n) asm volatile("s_waitcnt lgkmcnt(" #n ")" ::: "memory")
; #define PG8_BAR __builtin_amdgcn_s_barrier()
; #define PG8_SCHED __builtin_amdgcn_sched_barrier(0)
; template <class Epi, class Sched>
; __device__ __forceinline__ void gemm_phase(int wid_s, PG8_LAS unsigned char* lds, const Gemm g, const Sched& S, const Epi& E) {
;     ...
;             PG8_WAIT_V(8); PG8_WAIT_L(0); PG8_BAR; PG8_MMA(1, 0, At, B0); PG8_MMA(1, 1, At, B1); PG8_BAR; PG8_SCHED;
;             PG8_LDB(B0, 1, 0); PG8_LDB(B1, 1, 1); PG8_SCHED; PG8_LDA(At, 1, 0); PG8_STAGE(PG8_SA(0, 1), a2 + hstepA, voffA);
;             PG8_WAIT_V(8); PG8_WAIT_L(0); PG8_BAR; PG8_MMA(0, 0, At, B0); PG8_MMA(0, 1, At, B1); PG8_BAR; PG8_SCHED;
	s_setprio 1
	s_waitcnt lgkmcnt(0)
	v_mfma_f32_16x16x32_bf16 v[60:63], v[154:157], v[206:209], v[60:63]
	v_mfma_f32_16x16x32_bf16 v[56:59], v[162:165], v[206:209], v[56:59]
	v_mfma_f32_16x16x32_bf16 v[44:47], v[154:157], v[214:217], v[44:47]
	v_mfma_f32_16x16x32_bf16 v[40:43], v[162:165], v[214:217], v[40:43]
	v_mfma_f32_16x16x32_bf16 v[28:31], v[154:157], v[222:225], v[28:31]
	v_mfma_f32_16x16x32_bf16 v[24:27], v[162:165], v[222:225], v[24:27]
	v_mfma_f32_16x16x32_bf16 v[12:15], v[154:157], v[230:233], v[12:15]
	v_mfma_f32_16x16x32_bf16 v[8:11], v[162:165], v[230:233], v[8:11]
	v_mfma_f32_16x16x32_bf16 v[60:63], v[158:161], v[210:213], v[60:63]
	v_mfma_f32_16x16x32_bf16 v[56:59], v[186:189], v[210:213], v[56:59]
	v_mfma_f32_16x16x32_bf16 v[44:47], v[158:161], v[218:221], v[44:47]
	v_mfma_f32_16x16x32_bf16 v[40:43], v[186:189], v[218:221], v[40:43]
	v_mfma_f32_16x16x32_bf16 v[28:31], v[158:161], v[226:229], v[28:31]
	v_mfma_f32_16x16x32_bf16 v[24:27], v[186:189], v[226:229], v[24:27]
	v_mfma_f32_16x16x32_bf16 v[12:15], v[158:161], v[234:237], v[12:15]
	v_mfma_f32_16x16x32_bf16 v[8:11], v[186:189], v[234:237], v[8:11]
	s_setprio 0
	s_setprio 1
	v_mfma_f32_16x16x32_bf16 v[52:55], v[190:193], v[206:209], v[52:55]
	v_mfma_f32_16x16x32_bf16 v[48:51], v[198:201], v[206:209], v[48:51]
	v_mfma_f32_16x16x32_bf16 v[36:39], v[190:193], v[214:217], v[36:39]
	v_mfma_f32_16x16x32_bf16 v[32:35], v[198:201], v[214:217], v[32:35]
	v_mfma_f32_16x16x32_bf16 v[20:23], v[190:193], v[222:225], v[20:23]
	v_mfma_f32_16x16x32_bf16 v[16:19], v[198:201], v[222:225], v[16:19]
	v_mfma_f32_16x16x32_bf16 v[4:7], v[190:193], v[230:233], v[4:7]
	v_mfma_f32_16x16x32_bf16 v[0:3], v[198:201], v[230:233], v[0:3]
	v_mfma_f32_16x16x32_bf16 v[52:55], v[194:197], v[210:213], v[52:55]
	v_mfma_f32_16x16x32_bf16 v[48:51], v[202:205], v[210:213], v[48:51]
	v_mfma_f32_16x16x32_bf16 v[36:39], v[194:197], v[218:221], v[36:39]
	v_mfma_f32_16x16x32_bf16 v[32:35], v[202:205], v[218:221], v[32:35]
	v_mfma_f32_16x16x32_bf16 v[20:23], v[194:197], v[226:229], v[20:23]
	v_mfma_f32_16x16x32_bf16 v[16:19], v[202:205], v[226:229], v[16:19]
	v_mfma_f32_16x16x32_bf16 v[4:7], v[194:197], v[234:237], v[4:7]
	v_mfma_f32_16x16x32_bf16 v[0:3], v[202:205], v[234:237], v[0:3]
	s_setprio 0
	s_barrier
	s_add_i32 s56, 0, 0x18000
	v_add_u32_e32 v185, s56, v139
	s_add_i32 s57, 0, 0x1c000
	ds_read_b128 v[154:157], v185
	ds_read_b128 v[158:161], v185 offset:1024
	ds_read_b128 v[162:165], v185 offset:2048
	ds_read_b128 v[186:189], v185 offset:3072
	v_add_u32_e32 v185, s57, v139
	ds_read_b128 v[190:193], v185
	ds_read_b128 v[194:197], v185 offset:1024
	ds_read_b128 v[198:201], v185 offset:2048
	ds_read_b128 v[202:205], v185 offset:3072
	s_add_u32 s26, s26, s6
	s_addc_u32 s27, s27, s7
	s_mov_b32 m0, s39
	v_lshl_add_u64 v[246:247], s[26:27], 0, v[132:133]
	ds_read_b128 v[206:209], v141 offset:32768
	ds_read_b128 v[210:213], v141 offset:33792
	ds_read_b128 v[214:217], v141 offset:34816
	ds_read_b128 v[218:221], v141 offset:35840
	ds_read_b128 v[222:225], v141 offset:36864
	ds_read_b128 v[226:229], v141 offset:37888
	ds_read_b128 v[230:233], v141 offset:38912
	ds_read_b128 v[234:237], v141 offset:39936
	global_load_lds_dwordx4 v[246:247], off
	v_lshl_add_u64 v[246:247], s[26:27], 0, v[130:131]
	s_mov_b32 m0, s40
	s_nop 0
	global_load_lds_dwordx4 v[246:247], off
	s_waitcnt vmcnt(8)
	s_barrier
	s_setprio 1
	s_waitcnt lgkmcnt(0)
	v_mfma_f32_16x16x32_bf16 v[120:123], v[154:157], v[206:209], v[120:123]
	v_mfma_f32_16x16x32_bf16 v[124:127], v[162:165], v[206:209], v[124:127]
	v_mfma_f32_16x16x32_bf16 v[108:111], v[154:157], v[214:217], v[108:111]
	v_mfma_f32_16x16x32_bf16 v[104:107], v[162:165], v[214:217], v[104:107]
	v_mfma_f32_16x16x32_bf16 v[92:95], v[154:157], v[222:225], v[92:95]
	v_mfma_f32_16x16x32_bf16 v[88:91], v[162:165], v[222:225], v[88:91]
	v_mfma_f32_16x16x32_bf16 v[76:79], v[154:157], v[230:233], v[76:79]
	v_mfma_f32_16x16x32_bf16 v[72:75], v[162:165], v[230:233], v[72:75]
	v_mfma_f32_16x16x32_bf16 v[120:123], v[158:161], v[210:213], v[120:123]
	v_mfma_f32_16x16x32_bf16 v[124:127], v[186:189], v[210:213], v[124:127]
	v_mfma_f32_16x16x32_bf16 v[108:111], v[158:161], v[218:221], v[108:111]
	v_mfma_f32_16x16x32_bf16 v[104:107], v[186:189], v[218:221], v[104:107]
	v_mfma_f32_16x16x32_bf16 v[92:95], v[158:161], v[226:229], v[92:95]
	v_mfma_f32_16x16x32_bf16 v[88:91], v[186:189], v[226:229], v[88:91]
	v_mfma_f32_16x16x32_bf16 v[76:79], v[158:161], v[234:237], v[76:79]
	v_mfma_f32_16x16x32_bf16 v[72:75], v[186:189], v[234:237], v[72:75]
	s_setprio 0
	s_setprio 1
	v_mfma_f32_16x16x32_bf16 v[116:119], v[190:193], v[206:209], v[116:119]
	v_mfma_f32_16x16x32_bf16 v[112:115], v[198:201], v[206:209], v[112:115]
	v_mfma_f32_16x16x32_bf16 v[100:103], v[190:193], v[214:217], v[100:103]
	v_mfma_f32_16x16x32_bf16 v[96:99], v[198:201], v[214:217], v[96:99]
	v_mfma_f32_16x16x32_bf16 v[84:87], v[190:193], v[222:225], v[84:87]
	v_mfma_f32_16x16x32_bf16 v[80:83], v[198:201], v[222:225], v[80:83]
	v_mfma_f32_16x16x32_bf16 v[68:71], v[190:193], v[230:233], v[68:71]
	v_mfma_f32_16x16x32_bf16 v[64:67], v[198:201], v[230:233], v[64:67]
	v_mfma_f32_16x16x32_bf16 v[116:119], v[194:197], v[210:213], v[116:119]
	v_mfma_f32_16x16x32_bf16 v[112:115], v[202:205], v[210:213], v[112:115]
	v_mfma_f32_16x16x32_bf16 v[100:103], v[194:197], v[218:221], v[100:103]
	v_mfma_f32_16x16x32_bf16 v[96:99], v[202:205], v[218:221], v[96:99]
	v_mfma_f32_16x16x32_bf16 v[84:87], v[194:197], v[226:229], v[84:87]
	v_mfma_f32_16x16x32_bf16 v[80:83], v[202:205], v[226:229], v[80:83]
	v_mfma_f32_16x16x32_bf16 v[68:71], v[194:197], v[234:237], v[68:71]
	v_mfma_f32_16x16x32_bf16 v[64:67], v[202:205], v[234:237], v[64:67]
	s_setprio 0
	s_barrier
; #define PG8_STAGE(bufoff, gbase, voff) do { _Pragma("unroll") for (int _i = 0; _i < 2; ++_i) \
;         __builtin_amdgcn_global_load_lds((const unsigned*)((const char*)(gbase) + (voff)[_i]), (PG8_LAS unsigned*)(lds + (bufoff) + ldsw + _i * 8192), 16, 0, 0); } while (0)
; #define PG8_LDA(dst, b, h) do { _Pragma("unroll") for (int m = 0; m < 4; ++m) _Pragma("unroll") for (int k = 0; k < 2; ++k) dst[m][k] = *(const PG8_LAS bf16x8*)(lds + PG8_SA(b, h) + aoff + m * 2048 + k * 1024); } while (0)
; #define PG8_MMA(ai, bj, At, Bt) do { __builtin_amdgcn_s_setprio(1); _Pragma("unroll") for (int m = 0; m < 4; ++m) _Pragma("unroll") for (int n = 0; n < 2; ++n) _Pragma("unroll") for (int k = 0; k < 2; ++k) \
;         acc[ai][bj][m][n] = __builtin_amdgcn_mfma_f32_16x16x32_bf16(Bt[n][k], At[m][k], acc[ai][bj][m][n], 0, 0, 0); __builtin_amdgcn_s_setprio(0); } while (0)
; #define PG8_WAIT_V(n) asm volatile("s_waitcnt vmcnt(" #n ")" ::: "memory")
; #define PG8_WAIT_L(n) asm volatile("s_waitcnt lgkmcnt(" #n ")" ::: "memory")
; #define PG8_BAR __builtin_amdgcn_s_barrier()
; #define PG8_SCHED __builtin_amdgcn_sched_barrier(0)
; template <class Epi, class Sched>
; __device__ __forceinline__ void gemm_phase(int wid_s, PG8_LAS unsigned char* lds, const Gemm g, const Sched& S, const Epi& E) {
;     ...
;             PG8_LDA(At, 1, 1); PG8_STAGE(PG8_SB(1, 0), b3, voffB); PG8_STAGE(PG8_SB(1, 1), b3 + hstepB, voffB); PG8_STAGE(PG8_SA(1, 0), a3, voffA);
;             PG8_WAIT_V(8); PG8_WAIT_L(0); PG8_BAR; PG8_MMA(1, 0, At, B0); PG8_MMA(1, 1, At, B1); PG8_BAR; PG8_SCHED;
;         }
	s_add_i32 s26, s56, s34
	v_lshl_add_u64 v[142:143], v[142:143], 0, s[96:97]
	s_mov_b32 m0, s26
	ds_read_b128 v[206:209], v141 offset:49152
	ds_read_b128 v[210:213], v141 offset:50176
	ds_read_b128 v[214:217], v141 offset:51200
	ds_read_b128 v[218:221], v141 offset:52224
	ds_read_b128 v[222:225], v141 offset:53248
	ds_read_b128 v[226:229], v141 offset:54272
	ds_read_b128 v[230:233], v141 offset:55296
	ds_read_b128 v[234:237], v141 offset:56320
	global_load_lds_dwordx4 v[142:143], off
	v_lshl_add_u64 v[142:143], v[166:167], 0, s[96:97]
	s_add_i32 m0, s26, 0x2000
	s_add_i32 s26, s57, s34
	global_load_lds_dwordx4 v[142:143], off
	v_lshl_add_u64 v[142:143], v[238:239], 0, s[96:97]
	s_mov_b32 m0, s26
	s_nop 0
	global_load_lds_dwordx4 v[142:143], off
	v_lshl_add_u64 v[142:143], v[240:241], 0, s[96:97]
	s_add_i32 m0, s26, 0x2000
	s_nop 0
	global_load_lds_dwordx4 v[142:143], off
	v_lshl_add_u64 v[142:143], v[242:243], 0, s[96:97]
	s_mov_b32 m0, s46
	s_nop 0
	global_load_lds_dwordx4 v[142:143], off
	v_lshl_add_u64 v[142:143], v[244:245], 0, s[96:97]
	s_mov_b32 m0, s47
	s_nop 0
	global_load_lds_dwordx4 v[142:143], off
	s_waitcnt vmcnt(8)
	s_barrier
	s_setprio 1
	s_waitcnt lgkmcnt(0)
	v_mfma_f32_16x16x32_bf16 v[60:63], v[154:157], v[206:209], v[60:63]
	v_mfma_f32_16x16x32_bf16 v[56:59], v[162:165], v[206:209], v[56:59]
	v_mfma_f32_16x16x32_bf16 v[44:47], v[154:157], v[214:217], v[44:47]
	v_mfma_f32_16x16x32_bf16 v[40:43], v[162:165], v[214:217], v[40:43]
	v_mfma_f32_16x16x32_bf16 v[28:31], v[154:157], v[222:225], v[28:31]
	v_mfma_f32_16x16x32_bf16 v[24:27], v[162:165], v[222:225], v[24:27]
	v_mfma_f32_16x16x32_bf16 v[12:15], v[154:157], v[230:233], v[12:15]
	v_mfma_f32_16x16x32_bf16 v[8:11], v[162:165], v[230:233], v[8:11]
	v_mfma_f32_16x16x32_bf16 v[60:63], v[158:161], v[210:213], v[60:63]
	v_mfma_f32_16x16x32_bf16 v[56:59], v[186:189], v[210:213], v[56:59]
	v_mfma_f32_16x16x32_bf16 v[44:47], v[158:161], v[218:221], v[44:47]
	v_mfma_f32_16x16x32_bf16 v[40:43], v[186:189], v[218:221], v[40:43]
	v_mfma_f32_16x16x32_bf16 v[28:31], v[158:161], v[226:229], v[28:31]
	v_mfma_f32_16x16x32_bf16 v[24:27], v[186:189], v[226:229], v[24:27]
	v_mfma_f32_16x16x32_bf16 v[12:15], v[158:161], v[234:237], v[12:15]
	v_mfma_f32_16x16x32_bf16 v[8:11], v[186:189], v[234:237], v[8:11]
	s_setprio 0
	s_setprio 1
	v_mfma_f32_16x16x32_bf16 v[52:55], v[190:193], v[206:209], v[52:55]
	v_mfma_f32_16x16x32_bf16 v[48:51], v[198:201], v[206:209], v[48:51]
	v_mfma_f32_16x16x32_bf16 v[36:39], v[190:193], v[214:217], v[36:39]
	v_mfma_f32_16x16x32_bf16 v[32:35], v[198:201], v[214:217], v[32:35]
	v_mfma_f32_16x16x32_bf16 v[20:23], v[190:193], v[222:225], v[20:23]
	v_mfma_f32_16x16x32_bf16 v[16:19], v[198:201], v[222:225], v[16:19]
	v_mfma_f32_16x16x32_bf16 v[4:7], v[190:193], v[230:233], v[4:7]
	v_mfma_f32_16x16x32_bf16 v[0:3], v[198:201], v[230:233], v[0:3]
	v_mfma_f32_16x16x32_bf16 v[52:55], v[194:197], v[210:213], v[52:55]
	v_mfma_f32_16x16x32_bf16 v[48:51], v[202:205], v[210:213], v[48:51]
	v_mfma_f32_16x16x32_bf16 v[36:39], v[194:197], v[218:221], v[36:39]
	v_mfma_f32_16x16x32_bf16 v[32:35], v[202:205], v[218:221], v[32:35]
	v_mfma_f32_16x16x32_bf16 v[20:23], v[194:197], v[226:229], v[20:23]
	v_mfma_f32_16x16x32_bf16 v[16:19], v[202:205], v[226:229], v[16:19]
	v_mfma_f32_16x16x32_bf16 v[4:7], v[194:197], v[234:237], v[4:7]
	v_mfma_f32_16x16x32_bf16 v[0:3], v[202:205], v[234:237], v[0:3]
	s_setprio 0
	s_barrier
	s_add_u32 s33, s33, 0x100
	s_addc_u32 s54, s54, 0
	s_add_u32 s24, s24, 0x100
	s_addc_u32 s25, s25, 0
	s_cmp_ge_i32 s55, s41
	s_mov_b32 s26, s55
	s_cbranch_scc0 .LBB0_1229
	v_readlane_b32 s54, v254, 52
	v_readlane_b32 s55, v254, 53
	v_readlane_b32 s92, v254, 54
	v_readlane_b32 s94, v254, 55
	s_movk_i32 s33, 0xc00

; #define PG8_STAGE(bufoff, gbase, voff) do { _Pragma("unroll") for (int _i = 0; _i < 2; ++_i) \
;         __builtin_amdgcn_global_load_lds((const unsigned*)((const char*)(gbase) + (voff)[_i]), (PG8_LAS unsigned*)(lds + (bufoff) + ldsw + _i * 8192), 16, 0, 0); } while (0)
; #define PG8_LDA(dst, b, h) do { _Pragma("unroll") for (int m = 0; m < 4; ++m) _Pragma("unroll") for (int k = 0; k < 2; ++k) dst[m][k] = *(const PG8_LAS bf16x8*)(lds + PG8_SA(b, h) + aoff + m * 2048 + k * 1024); } while (0)
; #define PG8_LDB(dst, b, h) do { _Pragma("unroll") for (int n = 0; n < 2; ++n) _Pragma("unroll") for (int k = 0; k < 2; ++k) dst[n][k] = *(const PG8_LAS bf16x8*)(lds + PG8_SB(b, h) + boff + n * 2048 + k * 1024); } while (0)
; #define PG8_MMA(ai, bj, At, Bt) do { __builtin_amdgcn_s_setprio(1); _Pragma("unroll") for (int m = 0; m < 4; ++m) _Pragma("unroll") for (int n = 0; n < 2; ++n) _Pragma("unroll") for (int k = 0; k < 2; ++k) \
;         acc[ai][bj][m][n] = __builtin_amdgcn_mfma_f32_16x16x32_bf16(Bt[n][k], At[m][k], acc[ai][bj][m][n], 0, 0, 0); __builtin_amdgcn_s_setprio(0); } while (0)
; #define PG8_WAIT_V(n) asm volatile("s_waitcnt vmcnt(" #n ")" ::: "memory")
; #define PG8_WAIT_L(n) asm volatile("s_waitcnt lgkmcnt(" #n ")" ::: "memory")
; #define PG8_BAR __builtin_amdgcn_s_barrier()
; #define PG8_SCHED __builtin_amdgcn_sched_barrier(0)
; template <class Epi, class Sched>
; __device__ __forceinline__ void gemm_phase(int wid_s, PG8_LAS unsigned char* lds, const Gemm g, const Sched& S, const Epi& E) {
;     ...
;             const bool last = (t == nt - 2);
;             const char* a1 = cA + (size_t)(t + 1) * kstep;
;             const char* a2 = last ? nA : cA + (size_t)(t + 2) * kstep; const char* b2 = last ? nB : cB + (size_t)(t + 2) * kstep;
;             const char* a3 = a2 + kstep; const char* b3 = b2 + kstep;
;             PG8_LDB(B0, 0, 0); PG8_LDB(B1, 0, 1); PG8_SCHED; PG8_LDA(At, 0, 0); PG8_STAGE(PG8_SA(1, 1), a1 + hstepA, voffA);
;             PG8_WAIT_V(8); PG8_WAIT_L(0); PG8_BAR; PG8_MMA(0, 0, At, B0); PG8_MMA(0, 1, At, B1); PG8_BAR; PG8_SCHED;
;             PG8_LDA(At, 0, 1); PG8_STAGE(PG8_SB(0, 0), b2, voffB); PG8_STAGE(PG8_SB(0, 1), b2 + hstepB, voffB); PG8_STAGE(PG8_SA(0, 0), a2, voffA);
.LBB0_1366:
	s_add_i32 s55, s28, 2
	s_add_u32 s92, s26, 0x80
	s_addc_u32 s29, s27, 0
	s_add_i32 vcc_lo, 0, 0x10000
	s_cmp_eq_u32 s47, s28
	s_cselect_b32 s29, s23, s29
	s_cselect_b32 s28, s22, s92
	v_add_u32_e32 v166, vcc_lo, v141
	s_cselect_b32 s95, s25, s54
	s_cselect_b32 s94, s24, s33
	s_add_i32 s92, 0, 0x14000
	ds_read_b128 v[154:157], v166
	ds_read_b128 v[158:161], v166 offset:1024
	ds_read_b128 v[162:165], v166 offset:2048
	ds_read_b128 v[186:189], v166 offset:3072
	v_add_u32_e32 v166, s92, v141
	ds_read_b128 v[190:193], v166
	ds_read_b128 v[194:197], v166 offset:1024
	ds_read_b128 v[198:201], v166 offset:2048
	ds_read_b128 v[202:205], v166 offset:3072
	v_lshl_add_u64 v[166:167], s[26:27], 0, v[136:137]
	s_add_i32 m0, s37, 0xc000
	ds_read_b128 v[206:209], v143
	ds_read_b128 v[210:213], v143 offset:1024
	ds_read_b128 v[214:217], v143 offset:2048
	ds_read_b128 v[218:221], v143 offset:3072
	ds_read_b128 v[222:225], v143 offset:4096
	ds_read_b128 v[226:229], v143 offset:5120
	ds_read_b128 v[230:233], v143 offset:6144
	ds_read_b128 v[234:237], v143 offset:7168
	global_load_lds_dwordx4 v[166:167], off
	v_lshl_add_u64 v[166:167], s[26:27], 0, v[134:135]
	s_add_i32 m0, s37, 0xe000
	s_nop 0
	global_load_lds_dwordx4 v[166:167], off
	s_waitcnt vmcnt(8)
	s_barrier
	s_setprio 1
	s_waitcnt lgkmcnt(0)
	v_mfma_f32_16x16x32_bf16 v[120:123], v[154:157], v[206:209], v[120:123]
	v_mfma_f32_16x16x32_bf16 v[124:127], v[162:165], v[206:209], v[124:127]
	v_mfma_f32_16x16x32_bf16 v[108:111], v[154:157], v[214:217], v[108:111]
	v_mfma_f32_16x16x32_bf16 v[104:107], v[162:165], v[214:217], v[104:107]
	v_mfma_f32_16x16x32_bf16 v[92:95], v[154:157], v[222:225], v[92:95]
	v_mfma_f32_16x16x32_bf16 v[88:91], v[162:165], v[222:225], v[88:91]
	v_mfma_f32_16x16x32_bf16 v[76:79], v[154:157], v[230:233], v[76:79]
	v_mfma_f32_16x16x32_bf16 v[72:75], v[162:165], v[230:233], v[72:75]
	v_mfma_f32_16x16x32_bf16 v[120:123], v[158:161], v[210:213], v[120:123]
	v_mfma_f32_16x16x32_bf16 v[124:127], v[186:189], v[210:213], v[124:127]
	v_mfma_f32_16x16x32_bf16 v[108:111], v[158:161], v[218:221], v[108:111]
	v_mfma_f32_16x16x32_bf16 v[104:107], v[186:189], v[218:221], v[104:107]
	v_mfma_f32_16x16x32_bf16 v[92:95], v[158:161], v[226:229], v[92:95]
	v_mfma_f32_16x16x32_bf16 v[88:91], v[186:189], v[226:229], v[88:91]
	v_mfma_f32_16x16x32_bf16 v[76:79], v[158:161], v[234:237], v[76:79]
	v_mfma_f32_16x16x32_bf16 v[72:75], v[186:189], v[234:237], v[72:75]
	s_setprio 0
	s_setprio 1
	v_mfma_f32_16x16x32_bf16 v[116:119], v[190:193], v[206:209], v[116:119]
	v_mfma_f32_16x16x32_bf16 v[112:115], v[198:201], v[206:209], v[112:115]
	v_mfma_f32_16x16x32_bf16 v[100:103], v[190:193], v[214:217], v[100:103]
	v_mfma_f32_16x16x32_bf16 v[96:99], v[198:201], v[214:217], v[96:99]
	v_mfma_f32_16x16x32_bf16 v[84:87], v[190:193], v[222:225], v[84:87]
	v_mfma_f32_16x16x32_bf16 v[80:83], v[198:201], v[222:225], v[80:83]
	v_mfma_f32_16x16x32_bf16 v[68:71], v[190:193], v[230:233], v[68:71]
	v_mfma_f32_16x16x32_bf16 v[64:67], v[198:201], v[230:233], v[64:67]
	v_mfma_f32_16x16x32_bf16 v[116:119], v[194:197], v[210:213], v[116:119]
	v_mfma_f32_16x16x32_bf16 v[112:115], v[202:205], v[210:213], v[112:115]
	v_mfma_f32_16x16x32_bf16 v[100:103], v[194:197], v[218:221], v[100:103]
	v_mfma_f32_16x16x32_bf16 v[96:99], v[202:205], v[218:221], v[96:99]
	v_mfma_f32_16x16x32_bf16 v[84:87], v[194:197], v[226:229], v[84:87]
	v_mfma_f32_16x16x32_bf16 v[80:83], v[202:205], v[226:229], v[80:83]
	v_mfma_f32_16x16x32_bf16 v[68:71], v[194:197], v[234:237], v[68:71]
	v_mfma_f32_16x16x32_bf16 v[64:67], v[202:205], v[234:237], v[64:67]
	s_setprio 0
	s_barrier
	s_add_i32 vcc_lo, vcc_lo, s35
	v_lshl_add_u64 v[166:167], s[94:95], 0, v[144:145]
	s_mov_b32 m0, vcc_lo
	ds_read_b128 v[206:209], v143 offset:16384
	ds_read_b128 v[210:213], v143 offset:17408
	ds_read_b128 v[214:217], v143 offset:18432
	ds_read_b128 v[218:221], v143 offset:19456
	ds_read_b128 v[222:225], v143 offset:20480
	ds_read_b128 v[226:229], v143 offset:21504
	ds_read_b128 v[230:233], v143 offset:22528
	ds_read_b128 v[234:237], v143 offset:23552
	global_load_lds_dwordx4 v[166:167], off
	s_add_i32 m0, vcc_lo, 0x2000
	v_lshl_add_u64 v[238:239], s[94:95], 0, v[128:129]
	s_add_u32 s94, s94, s6
	s_addc_u32 s95, s95, s7
	s_add_i32 s92, s92, s35
	global_load_lds_dwordx4 v[238:239], off
	v_lshl_add_u64 v[240:241], s[94:95], 0, v[144:145]
	s_mov_b32 m0, s92
	v_lshl_add_u64 v[242:243], s[94:95], 0, v[128:129]
	global_load_lds_dwordx4 v[240:241], off
	s_add_i32 m0, s92, 0x2000
	v_lshl_add_u64 v[244:245], s[28:29], 0, v[132:133]
	global_load_lds_dwordx4 v[242:243], off
	s_mov_b32 m0, s37
	v_lshl_add_u64 v[246:247], s[28:29], 0, v[130:131]
	global_load_lds_dwordx4 v[244:245], off
	s_mov_b32 m0, s39
	s_nop 0
	global_load_lds_dwordx4 v[246:247], off
	s_waitcnt vmcnt(8)
	s_barrier
; #define PG8_STAGE(bufoff, gbase, voff) do { _Pragma("unroll") for (int _i = 0; _i < 2; ++_i) \
;         __builtin_amdgcn_global_load_lds((const unsigned*)((const char*)(gbase) + (voff)[_i]), (PG8_LAS unsigned*)(lds + (bufoff) + ldsw + _i * 8192), 16, 0, 0); } while (0)
; #define PG8_LDA(dst, b, h) do { _Pragma("unroll") for (int m = 0; m < 4; ++m) _Pragma("unroll") for (int k = 0; k < 2; ++k) dst[m][k] = *(const PG8_LAS bf16x8*)(lds + PG8_SA(b, h) + aoff + m * 2048 + k * 1024); } while (0)
; #define PG8_LDB(dst, b, h) do { _Pragma("unroll") for (int n = 0; n < 2; ++n) _Pragma("unroll") for (int k = 0; k < 2; ++k) dst[n][k] = *(const PG8_LAS bf16x8*)(lds + PG8_SB(b, h) + boff + n * 2048 + k * 1024); } while (0)
; #define PG8_MMA(ai, bj, At, Bt) do { __builtin_amdgcn_s_setprio(1); _Pragma("unroll") for (int m = 0; m < 4; ++m) _Pragma("unroll") for (int n = 0; n < 2; ++n) _Pragma("unroll") for (int k = 0; k < 2; ++k) \
;         acc[ai][bj][m][n] = __builtin_amdgcn_mfma_f32_16x16x32_bf16(Bt[n][k], At[m][k], acc[ai][bj][m][n], 0, 0, 0); __builtin_amdgcn_s_setprio(0); } while (0)
; #define PG8_WAIT_V(n) asm volatile("s_waitcnt vmcnt(" #n ")" ::: "memory")
; #define PG8_WAIT_L(n) asm volatile("s_waitcnt lgkmcnt(" #n ")" ::: "memory")
; #define PG8_BAR __builtin_amdgcn_s_barrier()
; #define PG8_SCHED __builtin_amdgcn_sched_barrier(0)
; template <class Epi, class Sched>
; __device__ __forceinline__ void gemm_phase(int wid_s, PG8_LAS unsigned char* lds, const Gemm g, const Sched& S, const Epi& E) {
;     ...
;             PG8_WAIT_V(8); PG8_WAIT_L(0); PG8_BAR; PG8_MMA(1, 0, At, B0); PG8_MMA(1, 1, At, B1); PG8_BAR; PG8_SCHED;
;             PG8_LDB(B0, 1, 0); PG8_LDB(B1, 1, 1); PG8_SCHED; PG8_LDA(At, 1, 0); PG8_STAGE(PG8_SA(0, 1), a2 + hstepA, voffA);
;             PG8_WAIT_V(8); PG8_WAIT_L(0); PG8_BAR; PG8_MMA(0, 0, At, B0); PG8_MMA(0, 1, At, B1); PG8_BAR; PG8_SCHED;
	s_setprio 1
	s_waitcnt lgkmcnt(0)
	v_mfma_f32_16x16x32_bf16 v[60:63], v[154:157], v[206:209], v[60:63]
	v_mfma_f32_16x16x32_bf16 v[56:59], v[162:165], v[206:209], v[56:59]
	v_mfma_f32_16x16x32_bf16 v[44:47], v[154:157], v[214:217], v[44:47]
	v_mfma_f32_16x16x32_bf16 v[40:43], v[162:165], v[214:217], v[40:43]
	v_mfma_f32_16x16x32_bf16 v[28:31], v[154:157], v[222:225], v[28:31]
	v_mfma_f32_16x16x32_bf16 v[24:27], v[162:165], v[222:225], v[24:27]
	v_mfma_f32_16x16x32_bf16 v[12:15], v[154:157], v[230:233], v[12:15]
	v_mfma_f32_16x16x32_bf16 v[8:11], v[162:165], v[230:233], v[8:11]
	v_mfma_f32_16x16x32_bf16 v[60:63], v[158:161], v[210:213], v[60:63]
	v_mfma_f32_16x16x32_bf16 v[56:59], v[186:189], v[210:213], v[56:59]
	v_mfma_f32_16x16x32_bf16 v[44:47], v[158:161], v[218:221], v[44:47]
	v_mfma_f32_16x16x32_bf16 v[40:43], v[186:189], v[218:221], v[40:43]
	v_mfma_f32_16x16x32_bf16 v[28:31], v[158:161], v[226:229], v[28:31]
	v_mfma_f32_16x16x32_bf16 v[24:27], v[186:189], v[226:229], v[24:27]
	v_mfma_f32_16x16x32_bf16 v[12:15], v[158:161], v[234:237], v[12:15]
	v_mfma_f32_16x16x32_bf16 v[8:11], v[186:189], v[234:237], v[8:11]
	s_setprio 0
	s_setprio 1
	v_mfma_f32_16x16x32_bf16 v[52:55], v[190:193], v[206:209], v[52:55]
	v_mfma_f32_16x16x32_bf16 v[48:51], v[198:201], v[206:209], v[48:51]
	v_mfma_f32_16x16x32_bf16 v[36:39], v[190:193], v[214:217], v[36:39]
	v_mfma_f32_16x16x32_bf16 v[32:35], v[198:201], v[214:217], v[32:35]
	v_mfma_f32_16x16x32_bf16 v[20:23], v[190:193], v[222:225], v[20:23]
	v_mfma_f32_16x16x32_bf16 v[16:19], v[198:201], v[222:225], v[16:19]
	v_mfma_f32_16x16x32_bf16 v[4:7], v[190:193], v[230:233], v[4:7]
	v_mfma_f32_16x16x32_bf16 v[0:3], v[198:201], v[230:233], v[0:3]
	v_mfma_f32_16x16x32_bf16 v[52:55], v[194:197], v[210:213], v[52:55]
	v_mfma_f32_16x16x32_bf16 v[48:51], v[202:205], v[210:213], v[48:51]
	v_mfma_f32_16x16x32_bf16 v[36:39], v[194:197], v[218:221], v[36:39]
	v_mfma_f32_16x16x32_bf16 v[32:35], v[202:205], v[218:221], v[32:35]
	v_mfma_f32_16x16x32_bf16 v[20:23], v[194:197], v[226:229], v[20:23]
	v_mfma_f32_16x16x32_bf16 v[16:19], v[202:205], v[226:229], v[16:19]
	v_mfma_f32_16x16x32_bf16 v[4:7], v[194:197], v[234:237], v[4:7]
	v_mfma_f32_16x16x32_bf16 v[0:3], v[202:205], v[234:237], v[0:3]
	s_setprio 0
	s_barrier
	s_add_i32 s92, 0, 0x18000
	v_add_u32_e32 v185, s92, v141
	s_add_i32 s94, 0, 0x1c000
	ds_read_b128 v[154:157], v185
	ds_read_b128 v[158:161], v185 offset:1024
	ds_read_b128 v[162:165], v185 offset:2048
	ds_read_b128 v[186:189], v185 offset:3072
	v_add_u32_e32 v185, s94, v141
	ds_read_b128 v[190:193], v185
	ds_read_b128 v[194:197], v185 offset:1024
	ds_read_b128 v[198:201], v185 offset:2048
	ds_read_b128 v[202:205], v185 offset:3072
	s_add_u32 s28, s28, s4
	s_addc_u32 s29, s29, s5
	s_mov_b32 m0, s40
	v_lshl_add_u64 v[248:249], s[28:29], 0, v[132:133]
	ds_read_b128 v[206:209], v143 offset:32768
	ds_read_b128 v[210:213], v143 offset:33792
	ds_read_b128 v[214:217], v143 offset:34816
	ds_read_b128 v[218:221], v143 offset:35840
	ds_read_b128 v[222:225], v143 offset:36864
	ds_read_b128 v[226:229], v143 offset:37888
	ds_read_b128 v[230:233], v143 offset:38912
	ds_read_b128 v[234:237], v143 offset:39936
	global_load_lds_dwordx4 v[248:249], off
	v_lshl_add_u64 v[248:249], s[28:29], 0, v[130:131]
	s_mov_b32 m0, s41
	s_nop 0
	global_load_lds_dwordx4 v[248:249], off
	s_waitcnt vmcnt(8)
	s_barrier
	s_setprio 1
	s_waitcnt lgkmcnt(0)
	v_mfma_f32_16x16x32_bf16 v[120:123], v[154:157], v[206:209], v[120:123]
	v_mfma_f32_16x16x32_bf16 v[124:127], v[162:165], v[206:209], v[124:127]
	v_mfma_f32_16x16x32_bf16 v[108:111], v[154:157], v[214:217], v[108:111]
	v_mfma_f32_16x16x32_bf16 v[104:107], v[162:165], v[214:217], v[104:107]
	v_mfma_f32_16x16x32_bf16 v[92:95], v[154:157], v[222:225], v[92:95]
	v_mfma_f32_16x16x32_bf16 v[88:91], v[162:165], v[222:225], v[88:91]
	v_mfma_f32_16x16x32_bf16 v[76:79], v[154:157], v[230:233], v[76:79]
	v_mfma_f32_16x16x32_bf16 v[72:75], v[162:165], v[230:233], v[72:75]
	v_mfma_f32_16x16x32_bf16 v[120:123], v[158:161], v[210:213], v[120:123]
	v_mfma_f32_16x16x32_bf16 v[124:127], v[186:189], v[210:213], v[124:127]
	v_mfma_f32_16x16x32_bf16 v[108:111], v[158:161], v[218:221], v[108:111]
	v_mfma_f32_16x16x32_bf16 v[104:107], v[186:189], v[218:221], v[104:107]
	v_mfma_f32_16x16x32_bf16 v[92:95], v[158:161], v[226:229], v[92:95]
	v_mfma_f32_16x16x32_bf16 v[88:91], v[186:189], v[226:229], v[88:91]
	v_mfma_f32_16x16x32_bf16 v[76:79], v[158:161], v[234:237], v[76:79]
	v_mfma_f32_16x16x32_bf16 v[72:75], v[186:189], v[234:237], v[72:75]
	s_setprio 0
	s_setprio 1
	v_mfma_f32_16x16x32_bf16 v[116:119], v[190:193], v[206:209], v[116:119]
	v_mfma_f32_16x16x32_bf16 v[112:115], v[198:201], v[206:209], v[112:115]
	v_mfma_f32_16x16x32_bf16 v[100:103], v[190:193], v[214:217], v[100:103]
	v_mfma_f32_16x16x32_bf16 v[96:99], v[198:201], v[214:217], v[96:99]
	v_mfma_f32_16x16x32_bf16 v[84:87], v[190:193], v[222:225], v[84:87]
	v_mfma_f32_16x16x32_bf16 v[80:83], v[198:201], v[222:225], v[80:83]
	v_mfma_f32_16x16x32_bf16 v[68:71], v[190:193], v[230:233], v[68:71]
	v_mfma_f32_16x16x32_bf16 v[64:67], v[198:201], v[230:233], v[64:67]
	v_mfma_f32_16x16x32_bf16 v[116:119], v[194:197], v[210:213], v[116:119]
	v_mfma_f32_16x16x32_bf16 v[112:115], v[202:205], v[210:213], v[112:115]
	v_mfma_f32_16x16x32_bf16 v[100:103], v[194:197], v[218:221], v[100:103]
	v_mfma_f32_16x16x32_bf16 v[96:99], v[202:205], v[218:221], v[96:99]
	v_mfma_f32_16x16x32_bf16 v[84:87], v[194:197], v[226:229], v[84:87]
	v_mfma_f32_16x16x32_bf16 v[80:83], v[202:205], v[226:229], v[80:83]
	v_mfma_f32_16x16x32_bf16 v[68:71], v[194:197], v[234:237], v[68:71]
	v_mfma_f32_16x16x32_bf16 v[64:67], v[202:205], v[234:237], v[64:67]
	s_setprio 0
	s_barrier
; #define PG8_STAGE(bufoff, gbase, voff) do { _Pragma("unroll") for (int _i = 0; _i < 2; ++_i) \
;         __builtin_amdgcn_global_load_lds((const unsigned*)((const char*)(gbase) + (voff)[_i]), (PG8_LAS unsigned*)(lds + (bufoff) + ldsw + _i * 8192), 16, 0, 0); } while (0)
; #define PG8_LDA(dst, b, h) do { _Pragma("unroll") for (int m = 0; m < 4; ++m) _Pragma("unroll") for (int k = 0; k < 2; ++k) dst[m][k] = *(const PG8_LAS bf16x8*)(lds + PG8_SA(b, h) + aoff + m * 2048 + k * 1024); } while (0)
; #define PG8_MMA(ai, bj, At, Bt) do { __builtin_amdgcn_s_setprio(1); _Pragma("unroll") for (int m = 0; m < 4; ++m) _Pragma("unroll") for (int n = 0; n < 2; ++n) _Pragma("unroll") for (int k = 0; k < 2; ++k) \
;         acc[ai][bj][m][n] = __builtin_amdgcn_mfma_f32_16x16x32_bf16(Bt[n][k], At[m][k], acc[ai][bj][m][n], 0, 0, 0); __builtin_amdgcn_s_setprio(0); } while (0)
; #define PG8_WAIT_V(n) asm volatile("s_waitcnt vmcnt(" #n ")" ::: "memory")
; #define PG8_WAIT_L(n) asm volatile("s_waitcnt lgkmcnt(" #n ")" ::: "memory")
; #define PG8_BAR __builtin_amdgcn_s_barrier()
; #define PG8_SCHED __builtin_amdgcn_sched_barrier(0)
; template <class Epi, class Sched>
; __device__ __forceinline__ void gemm_phase(int wid_s, PG8_LAS unsigned char* lds, const Gemm g, const Sched& S, const Epi& E) {
;     ...
;             PG8_LDA(At, 1, 1); PG8_STAGE(PG8_SB(1, 0), b3, voffB); PG8_STAGE(PG8_SB(1, 1), b3 + hstepB, voffB); PG8_STAGE(PG8_SA(1, 0), a3, voffA);
;             PG8_WAIT_V(8); PG8_WAIT_L(0); PG8_BAR; PG8_MMA(1, 0, At, B0); PG8_MMA(1, 1, At, B1); PG8_BAR; PG8_SCHED;
;         }
	s_add_i32 s28, s92, s35
	v_lshl_add_u64 v[166:167], v[166:167], 0, s[96:97]
	s_mov_b32 m0, s28
	ds_read_b128 v[206:209], v143 offset:49152
	ds_read_b128 v[210:213], v143 offset:50176
	ds_read_b128 v[214:217], v143 offset:51200
	ds_read_b128 v[218:221], v143 offset:52224
	ds_read_b128 v[222:225], v143 offset:53248
	ds_read_b128 v[226:229], v143 offset:54272
	ds_read_b128 v[230:233], v143 offset:55296
	ds_read_b128 v[234:237], v143 offset:56320
	global_load_lds_dwordx4 v[166:167], off
	v_lshl_add_u64 v[166:167], v[238:239], 0, s[96:97]
	s_add_i32 m0, s28, 0x2000
	s_add_i32 s28, s94, s35
	global_load_lds_dwordx4 v[166:167], off
	v_lshl_add_u64 v[166:167], v[240:241], 0, s[96:97]
	s_mov_b32 m0, s28
	s_nop 0
	global_load_lds_dwordx4 v[166:167], off
	v_lshl_add_u64 v[166:167], v[242:243], 0, s[96:97]
	s_add_i32 m0, s28, 0x2000
	s_nop 0
	global_load_lds_dwordx4 v[166:167], off
	v_lshl_add_u64 v[166:167], v[244:245], 0, s[96:97]
	s_mov_b32 m0, s45
	s_nop 0
	global_load_lds_dwordx4 v[166:167], off
	v_lshl_add_u64 v[166:167], v[246:247], 0, s[96:97]
	s_mov_b32 m0, s46
	s_nop 0
	global_load_lds_dwordx4 v[166:167], off
	s_waitcnt vmcnt(8)
	s_barrier
	s_setprio 1
	s_waitcnt lgkmcnt(0)
	v_mfma_f32_16x16x32_bf16 v[60:63], v[154:157], v[206:209], v[60:63]
	v_mfma_f32_16x16x32_bf16 v[56:59], v[162:165], v[206:209], v[56:59]
	v_mfma_f32_16x16x32_bf16 v[44:47], v[154:157], v[214:217], v[44:47]
	v_mfma_f32_16x16x32_bf16 v[40:43], v[162:165], v[214:217], v[40:43]
	v_mfma_f32_16x16x32_bf16 v[28:31], v[154:157], v[222:225], v[28:31]
	v_mfma_f32_16x16x32_bf16 v[24:27], v[162:165], v[222:225], v[24:27]
	v_mfma_f32_16x16x32_bf16 v[12:15], v[154:157], v[230:233], v[12:15]
	v_mfma_f32_16x16x32_bf16 v[8:11], v[162:165], v[230:233], v[8:11]
	v_mfma_f32_16x16x32_bf16 v[60:63], v[158:161], v[210:213], v[60:63]
	v_mfma_f32_16x16x32_bf16 v[56:59], v[186:189], v[210:213], v[56:59]
	v_mfma_f32_16x16x32_bf16 v[44:47], v[158:161], v[218:221], v[44:47]
	v_mfma_f32_16x16x32_bf16 v[40:43], v[186:189], v[218:221], v[40:43]
	v_mfma_f32_16x16x32_bf16 v[28:31], v[158:161], v[226:229], v[28:31]
	v_mfma_f32_16x16x32_bf16 v[24:27], v[186:189], v[226:229], v[24:27]
	v_mfma_f32_16x16x32_bf16 v[12:15], v[158:161], v[234:237], v[12:15]
	v_mfma_f32_16x16x32_bf16 v[8:11], v[186:189], v[234:237], v[8:11]
	s_setprio 0
	s_setprio 1
	v_mfma_f32_16x16x32_bf16 v[52:55], v[190:193], v[206:209], v[52:55]
	v_mfma_f32_16x16x32_bf16 v[48:51], v[198:201], v[206:209], v[48:51]
	v_mfma_f32_16x16x32_bf16 v[36:39], v[190:193], v[214:217], v[36:39]
	v_mfma_f32_16x16x32_bf16 v[32:35], v[198:201], v[214:217], v[32:35]
	v_mfma_f32_16x16x32_bf16 v[20:23], v[190:193], v[222:225], v[20:23]
	v_mfma_f32_16x16x32_bf16 v[16:19], v[198:201], v[222:225], v[16:19]
	v_mfma_f32_16x16x32_bf16 v[4:7], v[190:193], v[230:233], v[4:7]
	v_mfma_f32_16x16x32_bf16 v[0:3], v[198:201], v[230:233], v[0:3]
	v_mfma_f32_16x16x32_bf16 v[52:55], v[194:197], v[210:213], v[52:55]
	v_mfma_f32_16x16x32_bf16 v[48:51], v[202:205], v[210:213], v[48:51]
	v_mfma_f32_16x16x32_bf16 v[36:39], v[194:197], v[218:221], v[36:39]
	v_mfma_f32_16x16x32_bf16 v[32:35], v[202:205], v[218:221], v[32:35]
	v_mfma_f32_16x16x32_bf16 v[20:23], v[194:197], v[226:229], v[20:23]
	v_mfma_f32_16x16x32_bf16 v[16:19], v[202:205], v[226:229], v[16:19]
	v_mfma_f32_16x16x32_bf16 v[4:7], v[194:197], v[234:237], v[4:7]
	v_mfma_f32_16x16x32_bf16 v[0:3], v[202:205], v[234:237], v[0:3]
	s_setprio 0
	s_barrier
	s_add_u32 s33, s33, 0x100
	s_addc_u32 s54, s54, 0
	s_add_u32 s26, s26, 0x100
	s_addc_u32 s27, s27, 0
	s_cmp_ge_i32 s55, s42
	s_mov_b32 s28, s55
	s_cbranch_scc0 .LBB0_1366
	v_readlane_b32 s54, v254, 52
	v_readlane_b32 s95, v254, 51
	v_readlane_b32 s55, v254, 53
	v_readlane_b32 s92, v254, 54
	v_readlane_b32 s94, v254, 55
	s_movk_i32 s33, 0x300

; #define PG8_STAGE(bufoff, gbase, voff) do { _Pragma("unroll") for (int _i = 0; _i < 2; ++_i) \
;         __builtin_amdgcn_global_load_lds((const unsigned*)((const char*)(gbase) + (voff)[_i]), (PG8_LAS unsigned*)(lds + (bufoff) + ldsw + _i * 8192), 16, 0, 0); } while (0)
; #define PG8_LDA(dst, b, h) do { _Pragma("unroll") for (int m = 0; m < 4; ++m) _Pragma("unroll") for (int k = 0; k < 2; ++k) dst[m][k] = *(const PG8_LAS bf16x8*)(lds + PG8_SA(b, h) + aoff + m * 2048 + k * 1024); } while (0)
; #define PG8_LDB(dst, b, h) do { _Pragma("unroll") for (int n = 0; n < 2; ++n) _Pragma("unroll") for (int k = 0; k < 2; ++k) dst[n][k] = *(const PG8_LAS bf16x8*)(lds + PG8_SB(b, h) + boff + n * 2048 + k * 1024); } while (0)
; #define PG8_MMA(ai, bj, At, Bt) do { __builtin_amdgcn_s_setprio(1); _Pragma("unroll") for (int m = 0; m < 4; ++m) _Pragma("unroll") for (int n = 0; n < 2; ++n) _Pragma("unroll") for (int k = 0; k < 2; ++k) \
;         acc[ai][bj][m][n] = __builtin_amdgcn_mfma_f32_16x16x32_bf16(Bt[n][k], At[m][k], acc[ai][bj][m][n], 0, 0, 0); __builtin_amdgcn_s_setprio(0); } while (0)
; #define PG8_WAIT_V(n) asm volatile("s_waitcnt vmcnt(" #n ")" ::: "memory")
; #define PG8_WAIT_L(n) asm volatile("s_waitcnt lgkmcnt(" #n ")" ::: "memory")
; #define PG8_BAR __builtin_amdgcn_s_barrier()
; #define PG8_SCHED __builtin_amdgcn_sched_barrier(0)
; template <class Epi, class Sched>
; __device__ __forceinline__ void gemm_phase(int wid_s, PG8_LAS unsigned char* lds, const Gemm g, const Sched& S, const Epi& E) {
;     ...
;             const bool last = (t == nt - 2);
;             const char* a1 = cA + (size_t)(t + 1) * kstep;
;             const char* a2 = last ? nA : cA + (size_t)(t + 2) * kstep; const char* b2 = last ? nB : cB + (size_t)(t + 2) * kstep;
;             const char* a3 = a2 + kstep; const char* b3 = b2 + kstep;
;             PG8_LDB(B0, 0, 0); PG8_LDB(B1, 0, 1); PG8_SCHED; PG8_LDA(At, 0, 0); PG8_STAGE(PG8_SA(1, 1), a1 + hstepA, voffA);
;             PG8_WAIT_V(8); PG8_WAIT_L(0); PG8_BAR; PG8_MMA(0, 0, At, B0); PG8_MMA(0, 1, At, B1); PG8_BAR; PG8_SCHED;
;             PG8_LDA(At, 0, 1); PG8_STAGE(PG8_SB(0, 0), b2, voffB); PG8_STAGE(PG8_SB(0, 1), b2 + hstepB, voffB); PG8_STAGE(PG8_SA(0, 0), a2, voffA);
.LBB0_1574:
	s_add_i32 s37, s28, 2
	s_add_u32 s39, s26, 0x80
	s_addc_u32 s29, s27, 0
	s_add_i32 s48, 0, 0x10000
	s_cmp_eq_u32 s45, s28
	s_cselect_b32 s29, s25, s29
	s_cselect_b32 s28, s24, s39
	s_cselect_b32 s41, s3, s36
	s_cselect_b32 s40, s2, s33
	s_add_i32 s39, 0, 0x14000
	v_add_u32_e32 v44, s48, v193
	v_add_u32_e32 v188, s39, v193
	ds_read_b128 v[24:27], v44
	ds_read_b128 v[28:31], v44 offset:1024
	ds_read_b128 v[40:43], v44 offset:2048
	ds_read_b128 v[44:47], v44 offset:3072
	ds_read_b128 v[164:167], v188
	ds_read_b128 v[196:199], v188 offset:1024
	ds_read_b128 v[200:203], v188 offset:2048
	ds_read_b128 v[204:207], v188 offset:3072
	v_lshl_add_u64 v[240:241], s[26:27], 0, v[162:163]
	s_add_i32 m0, s35, 0xc000
	ds_read_b128 v[208:211], v195
	ds_read_b128 v[212:215], v195 offset:1024
	ds_read_b128 v[216:219], v195 offset:2048
	ds_read_b128 v[220:223], v195 offset:3072
	ds_read_b128 v[224:227], v195 offset:4096
	ds_read_b128 v[228:231], v195 offset:5120
	ds_read_b128 v[232:235], v195 offset:6144
	ds_read_b128 v[236:239], v195 offset:7168
	global_load_lds_dwordx4 v[240:241], off
	v_lshl_add_u64 v[240:241], s[26:27], 0, v[160:161]
	s_add_i32 m0, s35, 0xe000
	s_nop 0
	global_load_lds_dwordx4 v[240:241], off
	s_waitcnt vmcnt(8)
	s_barrier
	s_setprio 1
	s_waitcnt lgkmcnt(0)
	v_mfma_f32_16x16x32_bf16 v[140:143], v[24:27], v[208:211], v[140:143]
	v_mfma_f32_16x16x32_bf16 v[136:139], v[40:43], v[208:211], v[136:139]
	v_mfma_f32_16x16x32_bf16 v[124:127], v[24:27], v[216:219], v[124:127]
	v_mfma_f32_16x16x32_bf16 v[120:123], v[40:43], v[216:219], v[120:123]
	v_mfma_f32_16x16x32_bf16 v[108:111], v[24:27], v[224:227], v[108:111]
	v_mfma_f32_16x16x32_bf16 v[104:107], v[40:43], v[224:227], v[104:107]
	v_mfma_f32_16x16x32_bf16 v[92:95], v[24:27], v[232:235], v[92:95]
	v_mfma_f32_16x16x32_bf16 v[88:91], v[40:43], v[232:235], v[88:91]
	v_mfma_f32_16x16x32_bf16 v[140:143], v[28:31], v[212:215], v[140:143]
	v_mfma_f32_16x16x32_bf16 v[136:139], v[44:47], v[212:215], v[136:139]
	v_mfma_f32_16x16x32_bf16 v[124:127], v[28:31], v[220:223], v[124:127]
	v_mfma_f32_16x16x32_bf16 v[120:123], v[44:47], v[220:223], v[120:123]
	v_mfma_f32_16x16x32_bf16 v[108:111], v[28:31], v[228:231], v[108:111]
	v_mfma_f32_16x16x32_bf16 v[104:107], v[44:47], v[228:231], v[104:107]
	v_mfma_f32_16x16x32_bf16 v[92:95], v[28:31], v[236:239], v[92:95]
	v_mfma_f32_16x16x32_bf16 v[88:91], v[44:47], v[236:239], v[88:91]
	s_setprio 0
	s_setprio 1
	v_mfma_f32_16x16x32_bf16 v[132:135], v[164:167], v[208:211], v[132:135]
	v_mfma_f32_16x16x32_bf16 v[128:131], v[200:203], v[208:211], v[128:131]
	v_mfma_f32_16x16x32_bf16 v[116:119], v[164:167], v[216:219], v[116:119]
	v_mfma_f32_16x16x32_bf16 v[112:115], v[200:203], v[216:219], v[112:115]
	v_mfma_f32_16x16x32_bf16 v[100:103], v[164:167], v[224:227], v[100:103]
	v_mfma_f32_16x16x32_bf16 v[96:99], v[200:203], v[224:227], v[96:99]
	v_mfma_f32_16x16x32_bf16 v[84:87], v[164:167], v[232:235], v[84:87]
	v_mfma_f32_16x16x32_bf16 v[80:83], v[200:203], v[232:235], v[80:83]
	v_mfma_f32_16x16x32_bf16 v[132:135], v[196:199], v[212:215], v[132:135]
	v_mfma_f32_16x16x32_bf16 v[128:131], v[204:207], v[212:215], v[128:131]
	v_mfma_f32_16x16x32_bf16 v[116:119], v[196:199], v[220:223], v[116:119]
	v_mfma_f32_16x16x32_bf16 v[112:115], v[204:207], v[220:223], v[112:115]
	v_mfma_f32_16x16x32_bf16 v[100:103], v[196:199], v[228:231], v[100:103]
	v_mfma_f32_16x16x32_bf16 v[96:99], v[204:207], v[228:231], v[96:99]
	v_mfma_f32_16x16x32_bf16 v[84:87], v[196:199], v[236:239], v[84:87]
	v_mfma_f32_16x16x32_bf16 v[80:83], v[204:207], v[236:239], v[80:83]
	s_setprio 0
	s_barrier
	s_add_i32 s48, s48, s34
	v_lshl_add_u64 v[240:241], s[40:41], 0, v[144:145]
	s_mov_b32 m0, s48
	ds_read_b128 v[208:211], v195 offset:16384
	ds_read_b128 v[212:215], v195 offset:17408
	ds_read_b128 v[216:219], v195 offset:18432
	ds_read_b128 v[220:223], v195 offset:19456
	ds_read_b128 v[224:227], v195 offset:20480
	ds_read_b128 v[228:231], v195 offset:21504
	ds_read_b128 v[232:235], v195 offset:22528
	ds_read_b128 v[236:239], v195 offset:23552
	global_load_lds_dwordx4 v[240:241], off
	s_add_i32 m0, s48, 0x2000
	v_lshl_add_u64 v[242:243], s[40:41], 0, v[158:159]
	s_add_u32 s40, s40, s6
	s_addc_u32 s41, s41, s7
	s_add_i32 s39, s39, s34
	global_load_lds_dwordx4 v[242:243], off
	v_lshl_add_u64 v[244:245], s[40:41], 0, v[144:145]
	s_mov_b32 m0, s39
	v_lshl_add_u64 v[246:247], s[40:41], 0, v[158:159]
	global_load_lds_dwordx4 v[244:245], off
	s_add_i32 m0, s39, 0x2000
	v_lshl_add_u64 v[248:249], s[28:29], 0, v[154:155]
	global_load_lds_dwordx4 v[246:247], off
	s_mov_b32 m0, s35
	v_lshl_add_u64 v[250:251], s[28:29], 0, v[156:157]
	global_load_lds_dwordx4 v[248:249], off
	s_mov_b32 m0, s42
	s_nop 0
	global_load_lds_dwordx4 v[250:251], off
	s_waitcnt vmcnt(8)
	s_barrier
; #define PG8_STAGE(bufoff, gbase, voff) do { _Pragma("unroll") for (int _i = 0; _i < 2; ++_i) \
;         __builtin_amdgcn_global_load_lds((const unsigned*)((const char*)(gbase) + (voff)[_i]), (PG8_LAS unsigned*)(lds + (bufoff) + ldsw + _i * 8192), 16, 0, 0); } while (0)
; #define PG8_LDA(dst, b, h) do { _Pragma("unroll") for (int m = 0; m < 4; ++m) _Pragma("unroll") for (int k = 0; k < 2; ++k) dst[m][k] = *(const PG8_LAS bf16x8*)(lds + PG8_SA(b, h) + aoff + m * 2048 + k * 1024); } while (0)
; #define PG8_LDB(dst, b, h) do { _Pragma("unroll") for (int n = 0; n < 2; ++n) _Pragma("unroll") for (int k = 0; k < 2; ++k) dst[n][k] = *(const PG8_LAS bf16x8*)(lds + PG8_SB(b, h) + boff + n * 2048 + k * 1024); } while (0)
; #define PG8_MMA(ai, bj, At, Bt) do { __builtin_amdgcn_s_setprio(1); _Pragma("unroll") for (int m = 0; m < 4; ++m) _Pragma("unroll") for (int n = 0; n < 2; ++n) _Pragma("unroll") for (int k = 0; k < 2; ++k) \
;         acc[ai][bj][m][n] = __builtin_amdgcn_mfma_f32_16x16x32_bf16(Bt[n][k], At[m][k], acc[ai][bj][m][n], 0, 0, 0); __builtin_amdgcn_s_setprio(0); } while (0)
; #define PG8_WAIT_V(n) asm volatile("s_waitcnt vmcnt(" #n ")" ::: "memory")
; #define PG8_WAIT_L(n) asm volatile("s_waitcnt lgkmcnt(" #n ")" ::: "memory")
; #define PG8_BAR __builtin_amdgcn_s_barrier()
; #define PG8_SCHED __builtin_amdgcn_sched_barrier(0)
; template <class Epi, class Sched>
; __device__ __forceinline__ void gemm_phase(int wid_s, PG8_LAS unsigned char* lds, const Gemm g, const Sched& S, const Epi& E) {
;     ...
;             PG8_WAIT_V(8); PG8_WAIT_L(0); PG8_BAR; PG8_MMA(1, 0, At, B0); PG8_MMA(1, 1, At, B1); PG8_BAR; PG8_SCHED;
;             PG8_LDB(B0, 1, 0); PG8_LDB(B1, 1, 1); PG8_SCHED; PG8_LDA(At, 1, 0); PG8_STAGE(PG8_SA(0, 1), a2 + hstepA, voffA);
;             PG8_WAIT_V(8); PG8_WAIT_L(0); PG8_BAR; PG8_MMA(0, 0, At, B0); PG8_MMA(0, 1, At, B1); PG8_BAR; PG8_SCHED;
	s_setprio 1
	s_waitcnt lgkmcnt(0)
	v_mfma_f32_16x16x32_bf16 v[76:79], v[24:27], v[208:211], v[76:79]
	v_mfma_f32_16x16x32_bf16 v[72:75], v[40:43], v[208:211], v[72:75]
	v_mfma_f32_16x16x32_bf16 v[60:63], v[24:27], v[216:219], v[60:63]
	v_mfma_f32_16x16x32_bf16 v[56:59], v[40:43], v[216:219], v[56:59]
	v_mfma_f32_16x16x32_bf16 v[36:39], v[24:27], v[224:227], v[36:39]
	v_mfma_f32_16x16x32_bf16 v[32:35], v[40:43], v[224:227], v[32:35]
	v_mfma_f32_16x16x32_bf16 v[12:15], v[24:27], v[232:235], v[12:15]
	v_mfma_f32_16x16x32_bf16 v[8:11], v[40:43], v[232:235], v[8:11]
	v_mfma_f32_16x16x32_bf16 v[76:79], v[28:31], v[212:215], v[76:79]
	v_mfma_f32_16x16x32_bf16 v[72:75], v[44:47], v[212:215], v[72:75]
	v_mfma_f32_16x16x32_bf16 v[60:63], v[28:31], v[220:223], v[60:63]
	v_mfma_f32_16x16x32_bf16 v[56:59], v[44:47], v[220:223], v[56:59]
	v_mfma_f32_16x16x32_bf16 v[36:39], v[28:31], v[228:231], v[36:39]
	v_mfma_f32_16x16x32_bf16 v[32:35], v[44:47], v[228:231], v[32:35]
	v_mfma_f32_16x16x32_bf16 v[12:15], v[28:31], v[236:239], v[12:15]
	v_mfma_f32_16x16x32_bf16 v[8:11], v[44:47], v[236:239], v[8:11]
	s_setprio 0
	s_setprio 1
	v_mfma_f32_16x16x32_bf16 v[20:23], v[164:167], v[224:227], v[20:23]
	v_mfma_f32_16x16x32_bf16 v[16:19], v[200:203], v[224:227], v[16:19]
	v_mfma_f32_16x16x32_bf16 v[4:7], v[164:167], v[232:235], v[4:7]
	v_mfma_f32_16x16x32_bf16 v[0:3], v[200:203], v[232:235], v[0:3]
	v_mfma_f32_16x16x32_bf16 v[24:27], v[164:167], v[208:211], v[68:71]
	v_mfma_f32_16x16x32_bf16 v[28:31], v[200:203], v[208:211], v[64:67]
	v_mfma_f32_16x16x32_bf16 v[40:43], v[164:167], v[216:219], v[52:55]
	v_mfma_f32_16x16x32_bf16 v[44:47], v[200:203], v[216:219], v[48:51]
	v_mfma_f32_16x16x32_bf16 v[20:23], v[196:199], v[228:231], v[20:23]
	v_mfma_f32_16x16x32_bf16 v[16:19], v[204:207], v[228:231], v[16:19]
	v_mfma_f32_16x16x32_bf16 v[4:7], v[196:199], v[236:239], v[4:7]
	v_mfma_f32_16x16x32_bf16 v[0:3], v[204:207], v[236:239], v[0:3]
	v_mfma_f32_16x16x32_bf16 v[24:27], v[196:199], v[212:215], v[24:27]
	v_mfma_f32_16x16x32_bf16 v[28:31], v[204:207], v[212:215], v[28:31]
	v_mfma_f32_16x16x32_bf16 v[40:43], v[196:199], v[220:223], v[40:43]
	v_mfma_f32_16x16x32_bf16 v[44:47], v[204:207], v[220:223], v[44:47]
	s_setprio 0
	s_barrier
	s_add_i32 s39, 0, 0x18000
	s_add_i32 s40, 0, 0x1c000
	v_add_u32_e32 v68, s39, v193
	v_add_u32_e32 v188, s40, v193
	ds_read_b128 v[48:51], v68
	ds_read_b128 v[52:55], v68 offset:1024
	ds_read_b128 v[64:67], v68 offset:2048
	ds_read_b128 v[68:71], v68 offset:3072
	ds_read_b128 v[164:167], v188
	ds_read_b128 v[196:199], v188 offset:1024
	ds_read_b128 v[200:203], v188 offset:2048
	ds_read_b128 v[204:207], v188 offset:3072
	s_add_u32 s28, s28, s4
	s_addc_u32 s29, s29, s5
	s_mov_b32 m0, s46
	v_lshl_add_u64 v[252:253], s[28:29], 0, v[154:155]
	ds_read_b128 v[208:211], v195 offset:32768
	ds_read_b128 v[212:215], v195 offset:33792
	ds_read_b128 v[216:219], v195 offset:34816
	ds_read_b128 v[220:223], v195 offset:35840
	ds_read_b128 v[224:227], v195 offset:36864
	ds_read_b128 v[228:231], v195 offset:37888
	ds_read_b128 v[232:235], v195 offset:38912
	ds_read_b128 v[236:239], v195 offset:39936
	global_load_lds_dwordx4 v[252:253], off
	v_lshl_add_u64 v[252:253], s[28:29], 0, v[156:157]
	s_mov_b32 m0, s47
	s_nop 0
	global_load_lds_dwordx4 v[252:253], off
	s_waitcnt vmcnt(8)
	s_barrier
	s_setprio 1
	s_waitcnt lgkmcnt(0)
	v_mfma_f32_16x16x32_bf16 v[140:143], v[48:51], v[208:211], v[140:143]
	v_mfma_f32_16x16x32_bf16 v[136:139], v[64:67], v[208:211], v[136:139]
	v_mfma_f32_16x16x32_bf16 v[124:127], v[48:51], v[216:219], v[124:127]
	v_mfma_f32_16x16x32_bf16 v[120:123], v[64:67], v[216:219], v[120:123]
	v_mfma_f32_16x16x32_bf16 v[108:111], v[48:51], v[224:227], v[108:111]
	v_mfma_f32_16x16x32_bf16 v[104:107], v[64:67], v[224:227], v[104:107]
	v_mfma_f32_16x16x32_bf16 v[92:95], v[48:51], v[232:235], v[92:95]
	v_mfma_f32_16x16x32_bf16 v[88:91], v[64:67], v[232:235], v[88:91]
	v_mfma_f32_16x16x32_bf16 v[140:143], v[52:55], v[212:215], v[140:143]
	v_mfma_f32_16x16x32_bf16 v[136:139], v[68:71], v[212:215], v[136:139]
	v_mfma_f32_16x16x32_bf16 v[124:127], v[52:55], v[220:223], v[124:127]
	v_mfma_f32_16x16x32_bf16 v[120:123], v[68:71], v[220:223], v[120:123]
	v_mfma_f32_16x16x32_bf16 v[108:111], v[52:55], v[228:231], v[108:111]
	v_mfma_f32_16x16x32_bf16 v[104:107], v[68:71], v[228:231], v[104:107]
	v_mfma_f32_16x16x32_bf16 v[92:95], v[52:55], v[236:239], v[92:95]
	v_mfma_f32_16x16x32_bf16 v[88:91], v[68:71], v[236:239], v[88:91]
	s_setprio 0
	s_setprio 1
	v_mfma_f32_16x16x32_bf16 v[132:135], v[164:167], v[208:211], v[132:135]
	v_mfma_f32_16x16x32_bf16 v[128:131], v[200:203], v[208:211], v[128:131]
	v_mfma_f32_16x16x32_bf16 v[116:119], v[164:167], v[216:219], v[116:119]
	v_mfma_f32_16x16x32_bf16 v[112:115], v[200:203], v[216:219], v[112:115]
	v_mfma_f32_16x16x32_bf16 v[100:103], v[164:167], v[224:227], v[100:103]
	v_mfma_f32_16x16x32_bf16 v[96:99], v[200:203], v[224:227], v[96:99]
	v_mfma_f32_16x16x32_bf16 v[84:87], v[164:167], v[232:235], v[84:87]
	v_mfma_f32_16x16x32_bf16 v[80:83], v[200:203], v[232:235], v[80:83]
	v_mfma_f32_16x16x32_bf16 v[132:135], v[196:199], v[212:215], v[132:135]
	v_mfma_f32_16x16x32_bf16 v[128:131], v[204:207], v[212:215], v[128:131]
	v_mfma_f32_16x16x32_bf16 v[116:119], v[196:199], v[220:223], v[116:119]
	v_mfma_f32_16x16x32_bf16 v[112:115], v[204:207], v[220:223], v[112:115]
	v_mfma_f32_16x16x32_bf16 v[100:103], v[196:199], v[228:231], v[100:103]
	v_mfma_f32_16x16x32_bf16 v[96:99], v[204:207], v[228:231], v[96:99]
	v_mfma_f32_16x16x32_bf16 v[84:87], v[196:199], v[236:239], v[84:87]
	v_mfma_f32_16x16x32_bf16 v[80:83], v[204:207], v[236:239], v[80:83]
	s_setprio 0
	s_barrier
; #define PG8_STAGE(bufoff, gbase, voff) do { _Pragma("unroll") for (int _i = 0; _i < 2; ++_i) \
;         __builtin_amdgcn_global_load_lds((const unsigned*)((const char*)(gbase) + (voff)[_i]), (PG8_LAS unsigned*)(lds + (bufoff) + ldsw + _i * 8192), 16, 0, 0); } while (0)
; #define PG8_LDA(dst, b, h) do { _Pragma("unroll") for (int m = 0; m < 4; ++m) _Pragma("unroll") for (int k = 0; k < 2; ++k) dst[m][k] = *(const PG8_LAS bf16x8*)(lds + PG8_SA(b, h) + aoff + m * 2048 + k * 1024); } while (0)
; #define PG8_MMA(ai, bj, At, Bt) do { __builtin_amdgcn_s_setprio(1); _Pragma("unroll") for (int m = 0; m < 4; ++m) _Pragma("unroll") for (int n = 0; n < 2; ++n) _Pragma("unroll") for (int k = 0; k < 2; ++k) \
;         acc[ai][bj][m][n] = __builtin_amdgcn_mfma_f32_16x16x32_bf16(Bt[n][k], At[m][k], acc[ai][bj][m][n], 0, 0, 0); __builtin_amdgcn_s_setprio(0); } while (0)
; #define PG8_WAIT_V(n) asm volatile("s_waitcnt vmcnt(" #n ")" ::: "memory")
; #define PG8_WAIT_L(n) asm volatile("s_waitcnt lgkmcnt(" #n ")" ::: "memory")
; #define PG8_BAR __builtin_amdgcn_s_barrier()
; #define PG8_SCHED __builtin_amdgcn_sched_barrier(0)
; template <class Epi, class Sched>
; __device__ __forceinline__ void gemm_phase(int wid_s, PG8_LAS unsigned char* lds, const Gemm g, const Sched& S, const Epi& E) {
;     ...
;             PG8_LDA(At, 1, 1); PG8_STAGE(PG8_SB(1, 0), b3, voffB); PG8_STAGE(PG8_SB(1, 1), b3 + hstepB, voffB); PG8_STAGE(PG8_SA(1, 0), a3, voffA);
;             PG8_WAIT_V(8); PG8_WAIT_L(0); PG8_BAR; PG8_MMA(1, 0, At, B0); PG8_MMA(1, 1, At, B1); PG8_BAR; PG8_SCHED;
;         }
	s_add_i32 s28, s39, s34
	v_lshl_add_u64 v[240:241], v[240:241], 0, s[96:97]
	s_mov_b32 m0, s28
	ds_read_b128 v[208:211], v195 offset:49152
	ds_read_b128 v[212:215], v195 offset:50176
	ds_read_b128 v[216:219], v195 offset:51200
	ds_read_b128 v[220:223], v195 offset:52224
	ds_read_b128 v[224:227], v195 offset:53248
	ds_read_b128 v[228:231], v195 offset:54272
	ds_read_b128 v[232:235], v195 offset:55296
	ds_read_b128 v[236:239], v195 offset:56320
	global_load_lds_dwordx4 v[240:241], off
	v_lshl_add_u64 v[240:241], v[242:243], 0, s[96:97]
	s_add_i32 m0, s28, 0x2000
	s_add_i32 s28, s40, s34
	global_load_lds_dwordx4 v[240:241], off
	v_lshl_add_u64 v[240:241], v[244:245], 0, s[96:97]
	s_mov_b32 m0, s28
	s_nop 0
	global_load_lds_dwordx4 v[240:241], off
	v_lshl_add_u64 v[240:241], v[246:247], 0, s[96:97]
	s_add_i32 m0, s28, 0x2000
	s_nop 0
	global_load_lds_dwordx4 v[240:241], off
	v_lshl_add_u64 v[240:241], v[248:249], 0, s[96:97]
	s_mov_b32 m0, s52
	s_nop 0
	global_load_lds_dwordx4 v[240:241], off
	v_lshl_add_u64 v[240:241], v[250:251], 0, s[96:97]
	s_mov_b32 m0, s53
	s_nop 0
	global_load_lds_dwordx4 v[240:241], off
	s_waitcnt vmcnt(8)
	s_barrier
	s_setprio 1
	s_waitcnt lgkmcnt(0)
	v_mfma_f32_16x16x32_bf16 v[76:79], v[48:51], v[208:211], v[76:79]
	v_mfma_f32_16x16x32_bf16 v[72:75], v[64:67], v[208:211], v[72:75]
	v_mfma_f32_16x16x32_bf16 v[60:63], v[48:51], v[216:219], v[60:63]
	v_mfma_f32_16x16x32_bf16 v[56:59], v[64:67], v[216:219], v[56:59]
	v_mfma_f32_16x16x32_bf16 v[36:39], v[48:51], v[224:227], v[36:39]
	v_mfma_f32_16x16x32_bf16 v[32:35], v[64:67], v[224:227], v[32:35]
	v_mfma_f32_16x16x32_bf16 v[12:15], v[48:51], v[232:235], v[12:15]
	v_mfma_f32_16x16x32_bf16 v[8:11], v[64:67], v[232:235], v[8:11]
	v_mfma_f32_16x16x32_bf16 v[76:79], v[52:55], v[212:215], v[76:79]
	v_mfma_f32_16x16x32_bf16 v[72:75], v[68:71], v[212:215], v[72:75]
	v_mfma_f32_16x16x32_bf16 v[60:63], v[52:55], v[220:223], v[60:63]
	v_mfma_f32_16x16x32_bf16 v[56:59], v[68:71], v[220:223], v[56:59]
	v_mfma_f32_16x16x32_bf16 v[36:39], v[52:55], v[228:231], v[36:39]
	v_mfma_f32_16x16x32_bf16 v[32:35], v[68:71], v[228:231], v[32:35]
	v_mfma_f32_16x16x32_bf16 v[12:15], v[52:55], v[236:239], v[12:15]
	v_mfma_f32_16x16x32_bf16 v[8:11], v[68:71], v[236:239], v[8:11]
	s_setprio 0
	s_setprio 1
	v_mfma_f32_16x16x32_bf16 v[24:27], v[164:167], v[208:211], v[24:27]
	v_mfma_f32_16x16x32_bf16 v[68:71], v[196:199], v[212:215], v[24:27]
	v_mfma_f32_16x16x32_bf16 v[24:27], v[200:203], v[208:211], v[28:31]
	v_mfma_f32_16x16x32_bf16 v[64:67], v[204:207], v[212:215], v[24:27]
	v_mfma_f32_16x16x32_bf16 v[24:27], v[164:167], v[216:219], v[40:43]
	v_mfma_f32_16x16x32_bf16 v[52:55], v[196:199], v[220:223], v[24:27]
	v_mfma_f32_16x16x32_bf16 v[24:27], v[200:203], v[216:219], v[44:47]
	v_mfma_f32_16x16x32_bf16 v[20:23], v[164:167], v[224:227], v[20:23]
	v_mfma_f32_16x16x32_bf16 v[16:19], v[200:203], v[224:227], v[16:19]
	v_mfma_f32_16x16x32_bf16 v[4:7], v[164:167], v[232:235], v[4:7]
	v_mfma_f32_16x16x32_bf16 v[0:3], v[200:203], v[232:235], v[0:3]
	v_mfma_f32_16x16x32_bf16 v[48:51], v[204:207], v[220:223], v[24:27]
	v_mfma_f32_16x16x32_bf16 v[20:23], v[196:199], v[228:231], v[20:23]
	v_mfma_f32_16x16x32_bf16 v[16:19], v[204:207], v[228:231], v[16:19]
	v_mfma_f32_16x16x32_bf16 v[4:7], v[196:199], v[236:239], v[4:7]
	v_mfma_f32_16x16x32_bf16 v[0:3], v[204:207], v[236:239], v[0:3]
	s_setprio 0
	s_barrier
	s_add_u32 s33, s33, 0x100
	s_addc_u32 s36, s36, 0
	s_add_u32 s26, s26, 0x100
	s_addc_u32 s27, s27, 0
	s_cmp_ge_i32 s37, s44
	s_mov_b32 s28, s37
	s_cbranch_scc0 .LBB0_1574
	s_movk_i32 s39, 0x7f
	s_movk_i32 s33, 0x300

; #define PG8_STAGE(bufoff, gbase, voff) do { _Pragma("unroll") for (int _i = 0; _i < 2; ++_i) \
;         __builtin_amdgcn_global_load_lds((const unsigned*)((const char*)(gbase) + (voff)[_i]), (PG8_LAS unsigned*)(lds + (bufoff) + ldsw + _i * 8192), 16, 0, 0); } while (0)
; #define PG8_LDA(dst, b, h) do { _Pragma("unroll") for (int m = 0; m < 4; ++m) _Pragma("unroll") for (int k = 0; k < 2; ++k) dst[m][k] = *(const PG8_LAS bf16x8*)(lds + PG8_SA(b, h) + aoff + m * 2048 + k * 1024); } while (0)
; #define PG8_LDB(dst, b, h) do { _Pragma("unroll") for (int n = 0; n < 2; ++n) _Pragma("unroll") for (int k = 0; k < 2; ++k) dst[n][k] = *(const PG8_LAS bf16x8*)(lds + PG8_SB(b, h) + boff + n * 2048 + k * 1024); } while (0)
; #define PG8_MMA(ai, bj, At, Bt) do { __builtin_amdgcn_s_setprio(1); _Pragma("unroll") for (int m = 0; m < 4; ++m) _Pragma("unroll") for (int n = 0; n < 2; ++n) _Pragma("unroll") for (int k = 0; k < 2; ++k) \
;         acc[ai][bj][m][n] = __builtin_amdgcn_mfma_f32_16x16x32_bf16(Bt[n][k], At[m][k], acc[ai][bj][m][n], 0, 0, 0); __builtin_amdgcn_s_setprio(0); } while (0)
; #define PG8_WAIT_V(n) asm volatile("s_waitcnt vmcnt(" #n ")" ::: "memory")
; #define PG8_WAIT_L(n) asm volatile("s_waitcnt lgkmcnt(" #n ")" ::: "memory")
; #define PG8_BAR __builtin_amdgcn_s_barrier()
; #define PG8_SCHED __builtin_amdgcn_sched_barrier(0)
; template <class Epi, class Sched>
; __device__ __forceinline__ void gemm_phase(int wid_s, PG8_LAS unsigned char* lds, const Gemm g, const Sched& S, const Epi& E) {
;     ...
;             const bool last = (t == nt - 2);
;             const char* a1 = cA + (size_t)(t + 1) * kstep;
;             const char* a2 = last ? nA : cA + (size_t)(t + 2) * kstep; const char* b2 = last ? nB : cB + (size_t)(t + 2) * kstep;
;             const char* a3 = a2 + kstep; const char* b3 = b2 + kstep;
;             PG8_LDB(B0, 0, 0); PG8_LDB(B1, 0, 1); PG8_SCHED; PG8_LDA(At, 0, 0); PG8_STAGE(PG8_SA(1, 1), a1 + hstepA, voffA);
;             PG8_WAIT_V(8); PG8_WAIT_L(0); PG8_BAR; PG8_MMA(0, 0, At, B0); PG8_MMA(0, 1, At, B1); PG8_BAR; PG8_SCHED;
;             PG8_LDA(At, 0, 1); PG8_STAGE(PG8_SB(0, 0), b2, voffB); PG8_STAGE(PG8_SB(0, 1), b2 + hstepB, voffB); PG8_STAGE(PG8_SA(0, 0), a2, voffA);
.LBB0_1602:
	s_add_i32 s51, s46, 2
	s_add_u32 s52, s2, 0x80
	s_addc_u32 s47, s3, 0
	s_add_i32 vcc_lo, 0, 0x10000
	s_cmp_eq_u32 s56, s46
	s_cselect_b32 s47, s29, s47
	s_cselect_b32 s46, s28, s52
	v_add_u32_e32 v142, vcc_lo, v157
	s_cselect_b32 s53, s31, s50
	s_cselect_b32 s52, s30, s33
	s_add_i32 vcc_hi, 0, 0x14000
	ds_read_b128 v[138:141], v142
	ds_read_b128 v[160:163], v142 offset:1024
	ds_read_b128 v[164:167], v142 offset:2048
	ds_read_b128 v[192:195], v142 offset:3072
	v_add_u32_e32 v142, vcc_hi, v157
	ds_read_b128 v[196:199], v142
	ds_read_b128 v[200:203], v142 offset:1024
	ds_read_b128 v[204:207], v142 offset:2048
	ds_read_b128 v[208:211], v142 offset:3072
	v_lshl_add_u64 v[142:143], s[2:3], 0, v[136:137]
	s_add_i32 m0, s36, 0xc000
	ds_read_b128 v[212:215], v159
	ds_read_b128 v[216:219], v159 offset:1024
	ds_read_b128 v[220:223], v159 offset:2048
	ds_read_b128 v[224:227], v159 offset:3072
	ds_read_b128 v[228:231], v159 offset:4096
	ds_read_b128 v[232:235], v159 offset:5120
	ds_read_b128 v[236:239], v159 offset:6144
	ds_read_b128 v[240:243], v159 offset:7168
	global_load_lds_dwordx4 v[142:143], off
	v_lshl_add_u64 v[142:143], s[2:3], 0, v[134:135]
	s_add_i32 m0, s36, 0xe000
	s_nop 0
	global_load_lds_dwordx4 v[142:143], off
	s_waitcnt vmcnt(8)
	s_barrier
	s_setprio 1
	s_waitcnt lgkmcnt(0)
	v_mfma_f32_16x16x32_bf16 v[124:127], v[138:141], v[212:215], v[124:127]
	v_mfma_f32_16x16x32_bf16 v[120:123], v[164:167], v[212:215], v[120:123]
	v_mfma_f32_16x16x32_bf16 v[108:111], v[138:141], v[220:223], v[108:111]
	v_mfma_f32_16x16x32_bf16 v[104:107], v[164:167], v[220:223], v[104:107]
	v_mfma_f32_16x16x32_bf16 v[92:95], v[138:141], v[228:231], v[92:95]
	v_mfma_f32_16x16x32_bf16 v[88:91], v[164:167], v[228:231], v[88:91]
	v_mfma_f32_16x16x32_bf16 v[76:79], v[138:141], v[236:239], v[76:79]
	v_mfma_f32_16x16x32_bf16 v[72:75], v[164:167], v[236:239], v[72:75]
	v_mfma_f32_16x16x32_bf16 v[124:127], v[160:163], v[216:219], v[124:127]
	v_mfma_f32_16x16x32_bf16 v[120:123], v[192:195], v[216:219], v[120:123]
	v_mfma_f32_16x16x32_bf16 v[108:111], v[160:163], v[224:227], v[108:111]
	v_mfma_f32_16x16x32_bf16 v[104:107], v[192:195], v[224:227], v[104:107]
	v_mfma_f32_16x16x32_bf16 v[92:95], v[160:163], v[232:235], v[92:95]
	v_mfma_f32_16x16x32_bf16 v[88:91], v[192:195], v[232:235], v[88:91]
	v_mfma_f32_16x16x32_bf16 v[76:79], v[160:163], v[240:243], v[76:79]
	v_mfma_f32_16x16x32_bf16 v[72:75], v[192:195], v[240:243], v[72:75]
	s_setprio 0
	s_setprio 1
	v_mfma_f32_16x16x32_bf16 v[116:119], v[196:199], v[212:215], v[116:119]
	v_mfma_f32_16x16x32_bf16 v[112:115], v[204:207], v[212:215], v[112:115]
	v_mfma_f32_16x16x32_bf16 v[100:103], v[196:199], v[220:223], v[100:103]
	v_mfma_f32_16x16x32_bf16 v[96:99], v[204:207], v[220:223], v[96:99]
	v_mfma_f32_16x16x32_bf16 v[84:87], v[196:199], v[228:231], v[84:87]
	v_mfma_f32_16x16x32_bf16 v[80:83], v[204:207], v[228:231], v[80:83]
	v_mfma_f32_16x16x32_bf16 v[68:71], v[196:199], v[236:239], v[68:71]
	v_mfma_f32_16x16x32_bf16 v[64:67], v[204:207], v[236:239], v[64:67]
	v_mfma_f32_16x16x32_bf16 v[116:119], v[200:203], v[216:219], v[116:119]
	v_mfma_f32_16x16x32_bf16 v[112:115], v[208:211], v[216:219], v[112:115]
	v_mfma_f32_16x16x32_bf16 v[100:103], v[200:203], v[224:227], v[100:103]
	v_mfma_f32_16x16x32_bf16 v[96:99], v[208:211], v[224:227], v[96:99]
	v_mfma_f32_16x16x32_bf16 v[84:87], v[200:203], v[232:235], v[84:87]
	v_mfma_f32_16x16x32_bf16 v[80:83], v[208:211], v[232:235], v[80:83]
	v_mfma_f32_16x16x32_bf16 v[68:71], v[200:203], v[240:243], v[68:71]
	v_mfma_f32_16x16x32_bf16 v[64:67], v[208:211], v[240:243], v[64:67]
	s_setprio 0
	s_barrier
	s_add_i32 vcc_lo, vcc_lo, s19
	v_lshl_add_u64 v[142:143], s[52:53], 0, v[144:145]
	s_mov_b32 m0, vcc_lo
	ds_read_b128 v[212:215], v159 offset:16384
	ds_read_b128 v[216:219], v159 offset:17408
	ds_read_b128 v[220:223], v159 offset:18432
	ds_read_b128 v[224:227], v159 offset:19456
	ds_read_b128 v[228:231], v159 offset:20480
	ds_read_b128 v[232:235], v159 offset:21504
	ds_read_b128 v[236:239], v159 offset:22528
	ds_read_b128 v[240:243], v159 offset:23552
	global_load_lds_dwordx4 v[142:143], off
	s_add_i32 m0, vcc_lo, 0x2000
	v_lshl_add_u64 v[154:155], s[52:53], 0, v[132:133]
	s_add_u32 s52, s52, s6
	s_addc_u32 s53, s53, s7
	s_add_i32 vcc_lo, vcc_hi, s19
	global_load_lds_dwordx4 v[154:155], off
	v_lshl_add_u64 v[244:245], s[52:53], 0, v[144:145]
	s_mov_b32 m0, vcc_lo
	v_lshl_add_u64 v[246:247], s[52:53], 0, v[132:133]
	global_load_lds_dwordx4 v[244:245], off
	s_add_i32 m0, vcc_lo, 0x2000
	v_lshl_add_u64 v[248:249], s[46:47], 0, v[128:129]
	global_load_lds_dwordx4 v[246:247], off
	s_mov_b32 m0, s36
	v_lshl_add_u64 v[250:251], s[46:47], 0, v[130:131]
	global_load_lds_dwordx4 v[248:249], off
	s_mov_b32 m0, s37
	s_nop 0
	global_load_lds_dwordx4 v[250:251], off
	s_waitcnt vmcnt(8)
	s_barrier
; #define PG8_STAGE(bufoff, gbase, voff) do { _Pragma("unroll") for (int _i = 0; _i < 2; ++_i) \
;         __builtin_amdgcn_global_load_lds((const unsigned*)((const char*)(gbase) + (voff)[_i]), (PG8_LAS unsigned*)(lds + (bufoff) + ldsw + _i * 8192), 16, 0, 0); } while (0)
; #define PG8_LDA(dst, b, h) do { _Pragma("unroll") for (int m = 0; m < 4; ++m) _Pragma("unroll") for (int k = 0; k < 2; ++k) dst[m][k] = *(const PG8_LAS bf16x8*)(lds + PG8_SA(b, h) + aoff + m * 2048 + k * 1024); } while (0)
; #define PG8_LDB(dst, b, h) do { _Pragma("unroll") for (int n = 0; n < 2; ++n) _Pragma("unroll") for (int k = 0; k < 2; ++k) dst[n][k] = *(const PG8_LAS bf16x8*)(lds + PG8_SB(b, h) + boff + n * 2048 + k * 1024); } while (0)
; #define PG8_MMA(ai, bj, At, Bt) do { __builtin_amdgcn_s_setprio(1); _Pragma("unroll") for (int m = 0; m < 4; ++m) _Pragma("unroll") for (int n = 0; n < 2; ++n) _Pragma("unroll") for (int k = 0; k < 2; ++k) \
;         acc[ai][bj][m][n] = __builtin_amdgcn_mfma_f32_16x16x32_bf16(Bt[n][k], At[m][k], acc[ai][bj][m][n], 0, 0, 0); __builtin_amdgcn_s_setprio(0); } while (0)
; #define PG8_WAIT_V(n) asm volatile("s_waitcnt vmcnt(" #n ")" ::: "memory")
; #define PG8_WAIT_L(n) asm volatile("s_waitcnt lgkmcnt(" #n ")" ::: "memory")
; #define PG8_BAR __builtin_amdgcn_s_barrier()
; #define PG8_SCHED __builtin_amdgcn_sched_barrier(0)
; template <class Epi, class Sched>
; __device__ __forceinline__ void gemm_phase(int wid_s, PG8_LAS unsigned char* lds, const Gemm g, const Sched& S, const Epi& E) {
;     ...
;             PG8_WAIT_V(8); PG8_WAIT_L(0); PG8_BAR; PG8_MMA(1, 0, At, B0); PG8_MMA(1, 1, At, B1); PG8_BAR; PG8_SCHED;
;             PG8_LDB(B0, 1, 0); PG8_LDB(B1, 1, 1); PG8_SCHED; PG8_LDA(At, 1, 0); PG8_STAGE(PG8_SA(0, 1), a2 + hstepA, voffA);
;             PG8_WAIT_V(8); PG8_WAIT_L(0); PG8_BAR; PG8_MMA(0, 0, At, B0); PG8_MMA(0, 1, At, B1); PG8_BAR; PG8_SCHED;
	s_setprio 1
	s_waitcnt lgkmcnt(0)
	v_mfma_f32_16x16x32_bf16 v[60:63], v[138:141], v[212:215], v[60:63]
	v_mfma_f32_16x16x32_bf16 v[56:59], v[164:167], v[212:215], v[56:59]
	v_mfma_f32_16x16x32_bf16 v[44:47], v[138:141], v[220:223], v[44:47]
	v_mfma_f32_16x16x32_bf16 v[40:43], v[164:167], v[220:223], v[40:43]
	v_mfma_f32_16x16x32_bf16 v[28:31], v[138:141], v[228:231], v[28:31]
	v_mfma_f32_16x16x32_bf16 v[24:27], v[164:167], v[228:231], v[24:27]
	v_mfma_f32_16x16x32_bf16 v[12:15], v[138:141], v[236:239], v[12:15]
	v_mfma_f32_16x16x32_bf16 v[8:11], v[164:167], v[236:239], v[8:11]
	v_mfma_f32_16x16x32_bf16 v[60:63], v[160:163], v[216:219], v[60:63]
	v_mfma_f32_16x16x32_bf16 v[56:59], v[192:195], v[216:219], v[56:59]
	v_mfma_f32_16x16x32_bf16 v[44:47], v[160:163], v[224:227], v[44:47]
	v_mfma_f32_16x16x32_bf16 v[40:43], v[192:195], v[224:227], v[40:43]
	v_mfma_f32_16x16x32_bf16 v[28:31], v[160:163], v[232:235], v[28:31]
	v_mfma_f32_16x16x32_bf16 v[24:27], v[192:195], v[232:235], v[24:27]
	v_mfma_f32_16x16x32_bf16 v[12:15], v[160:163], v[240:243], v[12:15]
	v_mfma_f32_16x16x32_bf16 v[8:11], v[192:195], v[240:243], v[8:11]
	s_setprio 0
	s_setprio 1
	v_mfma_f32_16x16x32_bf16 v[52:55], v[196:199], v[212:215], v[52:55]
	v_mfma_f32_16x16x32_bf16 v[48:51], v[204:207], v[212:215], v[48:51]
	v_mfma_f32_16x16x32_bf16 v[36:39], v[196:199], v[220:223], v[36:39]
	v_mfma_f32_16x16x32_bf16 v[32:35], v[204:207], v[220:223], v[32:35]
	v_mfma_f32_16x16x32_bf16 v[20:23], v[196:199], v[228:231], v[20:23]
	v_mfma_f32_16x16x32_bf16 v[16:19], v[204:207], v[228:231], v[16:19]
	v_mfma_f32_16x16x32_bf16 v[4:7], v[196:199], v[236:239], v[4:7]
	v_mfma_f32_16x16x32_bf16 v[0:3], v[204:207], v[236:239], v[0:3]
	v_mfma_f32_16x16x32_bf16 v[52:55], v[200:203], v[216:219], v[52:55]
	v_mfma_f32_16x16x32_bf16 v[48:51], v[208:211], v[216:219], v[48:51]
	v_mfma_f32_16x16x32_bf16 v[36:39], v[200:203], v[224:227], v[36:39]
	v_mfma_f32_16x16x32_bf16 v[32:35], v[208:211], v[224:227], v[32:35]
	v_mfma_f32_16x16x32_bf16 v[20:23], v[200:203], v[232:235], v[20:23]
	v_mfma_f32_16x16x32_bf16 v[16:19], v[208:211], v[232:235], v[16:19]
	v_mfma_f32_16x16x32_bf16 v[4:7], v[200:203], v[240:243], v[4:7]
	v_mfma_f32_16x16x32_bf16 v[0:3], v[208:211], v[240:243], v[0:3]
	s_setprio 0
	s_barrier
	s_add_i32 s52, 0, 0x18000
	v_add_u32_e32 v188, s52, v157
	s_add_i32 s53, 0, 0x1c000
	ds_read_b128 v[138:141], v188
	ds_read_b128 v[160:163], v188 offset:1024
	ds_read_b128 v[164:167], v188 offset:2048
	ds_read_b128 v[192:195], v188 offset:3072
	v_add_u32_e32 v188, s53, v157
	ds_read_b128 v[196:199], v188
	ds_read_b128 v[200:203], v188 offset:1024
	ds_read_b128 v[204:207], v188 offset:2048
	ds_read_b128 v[208:211], v188 offset:3072
	s_add_u32 s46, s46, s4
	s_addc_u32 s47, s47, s5
	s_mov_b32 m0, s39
	v_lshl_add_u64 v[252:253], s[46:47], 0, v[128:129]
	ds_read_b128 v[212:215], v159 offset:32768
	ds_read_b128 v[216:219], v159 offset:33792
	ds_read_b128 v[220:223], v159 offset:34816
	ds_read_b128 v[224:227], v159 offset:35840
	ds_read_b128 v[228:231], v159 offset:36864
	ds_read_b128 v[232:235], v159 offset:37888
	ds_read_b128 v[236:239], v159 offset:38912
	ds_read_b128 v[240:243], v159 offset:39936
	global_load_lds_dwordx4 v[252:253], off
	v_lshl_add_u64 v[252:253], s[46:47], 0, v[130:131]
	s_mov_b32 m0, s40
	s_nop 0
	global_load_lds_dwordx4 v[252:253], off
	s_waitcnt vmcnt(8)
	s_barrier
	s_setprio 1
	s_waitcnt lgkmcnt(0)
	v_mfma_f32_16x16x32_bf16 v[124:127], v[138:141], v[212:215], v[124:127]
	v_mfma_f32_16x16x32_bf16 v[120:123], v[164:167], v[212:215], v[120:123]
	v_mfma_f32_16x16x32_bf16 v[108:111], v[138:141], v[220:223], v[108:111]
	v_mfma_f32_16x16x32_bf16 v[104:107], v[164:167], v[220:223], v[104:107]
	v_mfma_f32_16x16x32_bf16 v[92:95], v[138:141], v[228:231], v[92:95]
	v_mfma_f32_16x16x32_bf16 v[88:91], v[164:167], v[228:231], v[88:91]
	v_mfma_f32_16x16x32_bf16 v[76:79], v[138:141], v[236:239], v[76:79]
	v_mfma_f32_16x16x32_bf16 v[72:75], v[164:167], v[236:239], v[72:75]
	v_mfma_f32_16x16x32_bf16 v[124:127], v[160:163], v[216:219], v[124:127]
	v_mfma_f32_16x16x32_bf16 v[120:123], v[192:195], v[216:219], v[120:123]
	v_mfma_f32_16x16x32_bf16 v[108:111], v[160:163], v[224:227], v[108:111]
	v_mfma_f32_16x16x32_bf16 v[104:107], v[192:195], v[224:227], v[104:107]
	v_mfma_f32_16x16x32_bf16 v[92:95], v[160:163], v[232:235], v[92:95]
	v_mfma_f32_16x16x32_bf16 v[88:91], v[192:195], v[232:235], v[88:91]
	v_mfma_f32_16x16x32_bf16 v[76:79], v[160:163], v[240:243], v[76:79]
	v_mfma_f32_16x16x32_bf16 v[72:75], v[192:195], v[240:243], v[72:75]
	s_setprio 0
	s_setprio 1
	v_mfma_f32_16x16x32_bf16 v[116:119], v[196:199], v[212:215], v[116:119]
	v_mfma_f32_16x16x32_bf16 v[112:115], v[204:207], v[212:215], v[112:115]
	v_mfma_f32_16x16x32_bf16 v[100:103], v[196:199], v[220:223], v[100:103]
	v_mfma_f32_16x16x32_bf16 v[96:99], v[204:207], v[220:223], v[96:99]
	v_mfma_f32_16x16x32_bf16 v[84:87], v[196:199], v[228:231], v[84:87]
	v_mfma_f32_16x16x32_bf16 v[80:83], v[204:207], v[228:231], v[80:83]
	v_mfma_f32_16x16x32_bf16 v[68:71], v[196:199], v[236:239], v[68:71]
	v_mfma_f32_16x16x32_bf16 v[64:67], v[204:207], v[236:239], v[64:67]
	v_mfma_f32_16x16x32_bf16 v[116:119], v[200:203], v[216:219], v[116:119]
	v_mfma_f32_16x16x32_bf16 v[112:115], v[208:211], v[216:219], v[112:115]
	v_mfma_f32_16x16x32_bf16 v[100:103], v[200:203], v[224:227], v[100:103]
	v_mfma_f32_16x16x32_bf16 v[96:99], v[208:211], v[224:227], v[96:99]
	v_mfma_f32_16x16x32_bf16 v[84:87], v[200:203], v[232:235], v[84:87]
	v_mfma_f32_16x16x32_bf16 v[80:83], v[208:211], v[232:235], v[80:83]
	v_mfma_f32_16x16x32_bf16 v[68:71], v[200:203], v[240:243], v[68:71]
	v_mfma_f32_16x16x32_bf16 v[64:67], v[208:211], v[240:243], v[64:67]
	s_setprio 0
	s_barrier
; #define PG8_STAGE(bufoff, gbase, voff) do { _Pragma("unroll") for (int _i = 0; _i < 2; ++_i) \
;         __builtin_amdgcn_global_load_lds((const unsigned*)((const char*)(gbase) + (voff)[_i]), (PG8_LAS unsigned*)(lds + (bufoff) + ldsw + _i * 8192), 16, 0, 0); } while (0)
; #define PG8_LDA(dst, b, h) do { _Pragma("unroll") for (int m = 0; m < 4; ++m) _Pragma("unroll") for (int k = 0; k < 2; ++k) dst[m][k] = *(const PG8_LAS bf16x8*)(lds + PG8_SA(b, h) + aoff + m * 2048 + k * 1024); } while (0)
; #define PG8_MMA(ai, bj, At, Bt) do { __builtin_amdgcn_s_setprio(1); _Pragma("unroll") for (int m = 0; m < 4; ++m) _Pragma("unroll") for (int n = 0; n < 2; ++n) _Pragma("unroll") for (int k = 0; k < 2; ++k) \
;         acc[ai][bj][m][n] = __builtin_amdgcn_mfma_f32_16x16x32_bf16(Bt[n][k], At[m][k], acc[ai][bj][m][n], 0, 0, 0); __builtin_amdgcn_s_setprio(0); } while (0)
; #define PG8_WAIT_V(n) asm volatile("s_waitcnt vmcnt(" #n ")" ::: "memory")
; #define PG8_WAIT_L(n) asm volatile("s_waitcnt lgkmcnt(" #n ")" ::: "memory")
; #define PG8_BAR __builtin_amdgcn_s_barrier()
; #define PG8_SCHED __builtin_amdgcn_sched_barrier(0)
; template <class Epi, class Sched>
; __device__ __forceinline__ void gemm_phase(int wid_s, PG8_LAS unsigned char* lds, const Gemm g, const Sched& S, const Epi& E) {
;     ...
;             PG8_LDA(At, 1, 1); PG8_STAGE(PG8_SB(1, 0), b3, voffB); PG8_STAGE(PG8_SB(1, 1), b3 + hstepB, voffB); PG8_STAGE(PG8_SA(1, 0), a3, voffA);
;             PG8_WAIT_V(8); PG8_WAIT_L(0); PG8_BAR; PG8_MMA(1, 0, At, B0); PG8_MMA(1, 1, At, B1); PG8_BAR; PG8_SCHED;
;         }
	s_add_i32 s46, s52, s19
	v_lshl_add_u64 v[142:143], v[142:143], 0, s[96:97]
	s_mov_b32 m0, s46
	ds_read_b128 v[212:215], v159 offset:49152
	ds_read_b128 v[216:219], v159 offset:50176
	ds_read_b128 v[220:223], v159 offset:51200
	ds_read_b128 v[224:227], v159 offset:52224
	ds_read_b128 v[228:231], v159 offset:53248
	ds_read_b128 v[232:235], v159 offset:54272
	ds_read_b128 v[236:239], v159 offset:55296
	ds_read_b128 v[240:243], v159 offset:56320
	global_load_lds_dwordx4 v[142:143], off
	v_lshl_add_u64 v[142:143], v[154:155], 0, s[96:97]
	s_add_i32 m0, s46, 0x2000
	s_add_i32 s46, s53, s19
	global_load_lds_dwordx4 v[142:143], off
	v_lshl_add_u64 v[142:143], v[244:245], 0, s[96:97]
	s_mov_b32 m0, s46
	s_nop 0
	global_load_lds_dwordx4 v[142:143], off
	v_lshl_add_u64 v[142:143], v[246:247], 0, s[96:97]
	s_add_i32 m0, s46, 0x2000
	s_nop 0
	global_load_lds_dwordx4 v[142:143], off
	v_lshl_add_u64 v[142:143], v[248:249], 0, s[96:97]
	s_mov_b32 m0, s54
	s_nop 0
	global_load_lds_dwordx4 v[142:143], off
	v_lshl_add_u64 v[142:143], v[250:251], 0, s[96:97]
	s_mov_b32 m0, s55
	s_nop 0
	global_load_lds_dwordx4 v[142:143], off
	s_waitcnt vmcnt(8)
	s_barrier
	s_setprio 1
	s_waitcnt lgkmcnt(0)
	v_mfma_f32_16x16x32_bf16 v[60:63], v[138:141], v[212:215], v[60:63]
	v_mfma_f32_16x16x32_bf16 v[56:59], v[164:167], v[212:215], v[56:59]
	v_mfma_f32_16x16x32_bf16 v[44:47], v[138:141], v[220:223], v[44:47]
	v_mfma_f32_16x16x32_bf16 v[40:43], v[164:167], v[220:223], v[40:43]
	v_mfma_f32_16x16x32_bf16 v[28:31], v[138:141], v[228:231], v[28:31]
	v_mfma_f32_16x16x32_bf16 v[24:27], v[164:167], v[228:231], v[24:27]
	v_mfma_f32_16x16x32_bf16 v[12:15], v[138:141], v[236:239], v[12:15]
	v_mfma_f32_16x16x32_bf16 v[8:11], v[164:167], v[236:239], v[8:11]
	v_mfma_f32_16x16x32_bf16 v[60:63], v[160:163], v[216:219], v[60:63]
	v_mfma_f32_16x16x32_bf16 v[56:59], v[192:195], v[216:219], v[56:59]
	v_mfma_f32_16x16x32_bf16 v[44:47], v[160:163], v[224:227], v[44:47]
	v_mfma_f32_16x16x32_bf16 v[40:43], v[192:195], v[224:227], v[40:43]
	v_mfma_f32_16x16x32_bf16 v[28:31], v[160:163], v[232:235], v[28:31]
	v_mfma_f32_16x16x32_bf16 v[24:27], v[192:195], v[232:235], v[24:27]
	v_mfma_f32_16x16x32_bf16 v[12:15], v[160:163], v[240:243], v[12:15]
	v_mfma_f32_16x16x32_bf16 v[8:11], v[192:195], v[240:243], v[8:11]
	s_setprio 0
	s_setprio 1
	v_mfma_f32_16x16x32_bf16 v[52:55], v[196:199], v[212:215], v[52:55]
	v_mfma_f32_16x16x32_bf16 v[48:51], v[204:207], v[212:215], v[48:51]
	v_mfma_f32_16x16x32_bf16 v[36:39], v[196:199], v[220:223], v[36:39]
	v_mfma_f32_16x16x32_bf16 v[32:35], v[204:207], v[220:223], v[32:35]
	v_mfma_f32_16x16x32_bf16 v[20:23], v[196:199], v[228:231], v[20:23]
	v_mfma_f32_16x16x32_bf16 v[16:19], v[204:207], v[228:231], v[16:19]
	v_mfma_f32_16x16x32_bf16 v[4:7], v[196:199], v[236:239], v[4:7]
	v_mfma_f32_16x16x32_bf16 v[0:3], v[204:207], v[236:239], v[0:3]
	v_mfma_f32_16x16x32_bf16 v[52:55], v[200:203], v[216:219], v[52:55]
	v_mfma_f32_16x16x32_bf16 v[48:51], v[208:211], v[216:219], v[48:51]
	v_mfma_f32_16x16x32_bf16 v[36:39], v[200:203], v[224:227], v[36:39]
	v_mfma_f32_16x16x32_bf16 v[32:35], v[208:211], v[224:227], v[32:35]
	v_mfma_f32_16x16x32_bf16 v[20:23], v[200:203], v[232:235], v[20:23]
	v_mfma_f32_16x16x32_bf16 v[16:19], v[208:211], v[232:235], v[16:19]
	v_mfma_f32_16x16x32_bf16 v[4:7], v[200:203], v[240:243], v[4:7]
	v_mfma_f32_16x16x32_bf16 v[0:3], v[208:211], v[240:243], v[0:3]
	s_setprio 0
	s_barrier
	s_add_u32 s33, s33, 0x100
	s_addc_u32 s50, s50, 0
	s_add_u32 s2, s2, 0x100
	s_addc_u32 s3, s3, 0
	s_cmp_ge_i32 s51, s45
	s_mov_b32 s46, s51
	s_cbranch_scc0 .LBB0_1602
	s_movk_i32 s51, 0x200
	s_movk_i32 s33, 0x300

; #define PG8_STAGE(bufoff, gbase, voff) do { _Pragma("unroll") for (int _i = 0; _i < 2; ++_i) \
;         __builtin_amdgcn_global_load_lds((const unsigned*)((const char*)(gbase) + (voff)[_i]), (PG8_LAS unsigned*)(lds + (bufoff) + ldsw + _i * 8192), 16, 0, 0); } while (0)
; #define PG8_LDA(dst, b, h) do { _Pragma("unroll") for (int m = 0; m < 4; ++m) _Pragma("unroll") for (int k = 0; k < 2; ++k) dst[m][k] = *(const PG8_LAS bf16x8*)(lds + PG8_SA(b, h) + aoff + m * 2048 + k * 1024); } while (0)
; #define PG8_LDB(dst, b, h) do { _Pragma("unroll") for (int n = 0; n < 2; ++n) _Pragma("unroll") for (int k = 0; k < 2; ++k) dst[n][k] = *(const PG8_LAS bf16x8*)(lds + PG8_SB(b, h) + boff + n * 2048 + k * 1024); } while (0)
; #define PG8_MMA(ai, bj, At, Bt) do { __builtin_amdgcn_s_setprio(1); _Pragma("unroll") for (int m = 0; m < 4; ++m) _Pragma("unroll") for (int n = 0; n < 2; ++n) _Pragma("unroll") for (int k = 0; k < 2; ++k) \
;         acc[ai][bj][m][n] = __builtin_amdgcn_mfma_f32_16x16x32_bf16(Bt[n][k], At[m][k], acc[ai][bj][m][n], 0, 0, 0); __builtin_amdgcn_s_setprio(0); } while (0)
; #define PG8_WAIT_V(n) asm volatile("s_waitcnt vmcnt(" #n ")" ::: "memory")
; #define PG8_WAIT_L(n) asm volatile("s_waitcnt lgkmcnt(" #n ")" ::: "memory")
; #define PG8_BAR __builtin_amdgcn_s_barrier()
; #define PG8_SCHED __builtin_amdgcn_sched_barrier(0)
; template <class Epi, class Sched>
; __device__ __forceinline__ void gemm_phase(int wid_s, PG8_LAS unsigned char* lds, const Gemm g, const Sched& S, const Epi& E) {
;     ...
;             const bool last = (t == nt - 2);
;             const char* a1 = cA + (size_t)(t + 1) * kstep;
;             const char* a2 = last ? nA : cA + (size_t)(t + 2) * kstep; const char* b2 = last ? nB : cB + (size_t)(t + 2) * kstep;
;             const char* a3 = a2 + kstep; const char* b3 = b2 + kstep;
;             PG8_LDB(B0, 0, 0); PG8_LDB(B1, 0, 1); PG8_SCHED; PG8_LDA(At, 0, 0); PG8_STAGE(PG8_SA(1, 1), a1 + hstepA, voffA);
;             PG8_WAIT_V(8); PG8_WAIT_L(0); PG8_BAR; PG8_MMA(0, 0, At, B0); PG8_MMA(0, 1, At, B1); PG8_BAR; PG8_SCHED;
;             PG8_LDA(At, 0, 1); PG8_STAGE(PG8_SB(0, 0), b2, voffB); PG8_STAGE(PG8_SB(0, 1), b2 + hstepB, voffB); PG8_STAGE(PG8_SA(0, 0), a2, voffA);
.LBB0_1717:
	s_add_i32 s44, s34, 2
	s_add_u32 s45, s4, 0x80
	s_addc_u32 s35, s5, 0
	s_add_i32 s18, 0, 0x10000
	s_cmp_eq_u32 s95, s34
	s_cselect_b32 s35, s29, s35
	s_cselect_b32 s34, s28, s45
	v_add_u32_e32 v142, s18, v157
	s_cselect_b32 vcc_hi, s31, s51
	s_cselect_b32 vcc_lo, s30, s33
	s_add_i32 s45, 0, 0x14000
	ds_read_b128 v[138:141], v142
	ds_read_b128 v[160:163], v142 offset:1024
	ds_read_b128 v[164:167], v142 offset:2048
	ds_read_b128 v[192:195], v142 offset:3072
	v_add_u32_e32 v142, s45, v157
	ds_read_b128 v[196:199], v142
	ds_read_b128 v[200:203], v142 offset:1024
	ds_read_b128 v[204:207], v142 offset:2048
	ds_read_b128 v[208:211], v142 offset:3072
	v_lshl_add_u64 v[142:143], s[4:5], 0, v[136:137]
	s_add_i32 m0, s52, 0xc000
	ds_read_b128 v[212:215], v159
	ds_read_b128 v[216:219], v159 offset:1024
	ds_read_b128 v[220:223], v159 offset:2048
	ds_read_b128 v[224:227], v159 offset:3072
	ds_read_b128 v[228:231], v159 offset:4096
	ds_read_b128 v[232:235], v159 offset:5120
	ds_read_b128 v[236:239], v159 offset:6144
	ds_read_b128 v[240:243], v159 offset:7168
	global_load_lds_dwordx4 v[142:143], off
	v_lshl_add_u64 v[142:143], s[4:5], 0, v[134:135]
	s_add_i32 m0, s52, 0xe000
	s_nop 0
	global_load_lds_dwordx4 v[142:143], off
	s_waitcnt vmcnt(8)
	s_barrier
	s_setprio 1
	s_waitcnt lgkmcnt(0)
	v_mfma_f32_16x16x32_bf16 v[124:127], v[138:141], v[212:215], v[124:127]
	v_mfma_f32_16x16x32_bf16 v[120:123], v[164:167], v[212:215], v[120:123]
	v_mfma_f32_16x16x32_bf16 v[108:111], v[138:141], v[220:223], v[108:111]
	v_mfma_f32_16x16x32_bf16 v[104:107], v[164:167], v[220:223], v[104:107]
	v_mfma_f32_16x16x32_bf16 v[92:95], v[138:141], v[228:231], v[92:95]
	v_mfma_f32_16x16x32_bf16 v[88:91], v[164:167], v[228:231], v[88:91]
	v_mfma_f32_16x16x32_bf16 v[76:79], v[138:141], v[236:239], v[76:79]
	v_mfma_f32_16x16x32_bf16 v[72:75], v[164:167], v[236:239], v[72:75]
	v_mfma_f32_16x16x32_bf16 v[124:127], v[160:163], v[216:219], v[124:127]
	v_mfma_f32_16x16x32_bf16 v[120:123], v[192:195], v[216:219], v[120:123]
	v_mfma_f32_16x16x32_bf16 v[108:111], v[160:163], v[224:227], v[108:111]
	v_mfma_f32_16x16x32_bf16 v[104:107], v[192:195], v[224:227], v[104:107]
	v_mfma_f32_16x16x32_bf16 v[92:95], v[160:163], v[232:235], v[92:95]
	v_mfma_f32_16x16x32_bf16 v[88:91], v[192:195], v[232:235], v[88:91]
	v_mfma_f32_16x16x32_bf16 v[76:79], v[160:163], v[240:243], v[76:79]
	v_mfma_f32_16x16x32_bf16 v[72:75], v[192:195], v[240:243], v[72:75]
	s_setprio 0
	s_setprio 1
	v_mfma_f32_16x16x32_bf16 v[116:119], v[196:199], v[212:215], v[116:119]
	v_mfma_f32_16x16x32_bf16 v[112:115], v[204:207], v[212:215], v[112:115]
	v_mfma_f32_16x16x32_bf16 v[100:103], v[196:199], v[220:223], v[100:103]
	v_mfma_f32_16x16x32_bf16 v[96:99], v[204:207], v[220:223], v[96:99]
	v_mfma_f32_16x16x32_bf16 v[84:87], v[196:199], v[228:231], v[84:87]
	v_mfma_f32_16x16x32_bf16 v[80:83], v[204:207], v[228:231], v[80:83]
	v_mfma_f32_16x16x32_bf16 v[68:71], v[196:199], v[236:239], v[68:71]
	v_mfma_f32_16x16x32_bf16 v[64:67], v[204:207], v[236:239], v[64:67]
	v_mfma_f32_16x16x32_bf16 v[116:119], v[200:203], v[216:219], v[116:119]
	v_mfma_f32_16x16x32_bf16 v[112:115], v[208:211], v[216:219], v[112:115]
	v_mfma_f32_16x16x32_bf16 v[100:103], v[200:203], v[224:227], v[100:103]
	v_mfma_f32_16x16x32_bf16 v[96:99], v[208:211], v[224:227], v[96:99]
	v_mfma_f32_16x16x32_bf16 v[84:87], v[200:203], v[232:235], v[84:87]
	v_mfma_f32_16x16x32_bf16 v[80:83], v[208:211], v[232:235], v[80:83]
	v_mfma_f32_16x16x32_bf16 v[68:71], v[200:203], v[240:243], v[68:71]
	v_mfma_f32_16x16x32_bf16 v[64:67], v[208:211], v[240:243], v[64:67]
	s_setprio 0
	s_barrier
	s_add_i32 s18, s18, s47
	v_lshl_add_u64 v[142:143], vcc, 0, v[144:145]
	s_mov_b32 m0, s18
	ds_read_b128 v[212:215], v159 offset:16384
	ds_read_b128 v[216:219], v159 offset:17408
	ds_read_b128 v[220:223], v159 offset:18432
	ds_read_b128 v[224:227], v159 offset:19456
	ds_read_b128 v[228:231], v159 offset:20480
	ds_read_b128 v[232:235], v159 offset:21504
	ds_read_b128 v[236:239], v159 offset:22528
	ds_read_b128 v[240:243], v159 offset:23552
	global_load_lds_dwordx4 v[142:143], off
	s_add_i32 m0, s18, 0x2000
	v_lshl_add_u64 v[244:245], vcc, 0, v[132:133]
	s_add_u32 vcc_lo, vcc_lo, s12
	s_addc_u32 vcc_hi, vcc_hi, s13
	s_add_i32 s18, s45, s47
	global_load_lds_dwordx4 v[244:245], off
	v_lshl_add_u64 v[246:247], vcc, 0, v[144:145]
	s_mov_b32 m0, s18
	v_lshl_add_u64 v[248:249], vcc, 0, v[132:133]
	global_load_lds_dwordx4 v[246:247], off
	s_add_i32 m0, s18, 0x2000
	v_lshl_add_u64 v[250:251], s[34:35], 0, v[128:129]
	global_load_lds_dwordx4 v[248:249], off
	s_mov_b32 m0, s52
	v_lshl_add_u64 v[252:253], s[34:35], 0, v[130:131]
	global_load_lds_dwordx4 v[250:251], off
	s_mov_b32 m0, s53
	s_nop 0
	global_load_lds_dwordx4 v[252:253], off
	s_waitcnt vmcnt(8)
	s_barrier
; #define PG8_STAGE(bufoff, gbase, voff) do { _Pragma("unroll") for (int _i = 0; _i < 2; ++_i) \
;         __builtin_amdgcn_global_load_lds((const unsigned*)((const char*)(gbase) + (voff)[_i]), (PG8_LAS unsigned*)(lds + (bufoff) + ldsw + _i * 8192), 16, 0, 0); } while (0)
; #define PG8_LDA(dst, b, h) do { _Pragma("unroll") for (int m = 0; m < 4; ++m) _Pragma("unroll") for (int k = 0; k < 2; ++k) dst[m][k] = *(const PG8_LAS bf16x8*)(lds + PG8_SA(b, h) + aoff + m * 2048 + k * 1024); } while (0)
; #define PG8_LDB(dst, b, h) do { _Pragma("unroll") for (int n = 0; n < 2; ++n) _Pragma("unroll") for (int k = 0; k < 2; ++k) dst[n][k] = *(const PG8_LAS bf16x8*)(lds + PG8_SB(b, h) + boff + n * 2048 + k * 1024); } while (0)
; #define PG8_MMA(ai, bj, At, Bt) do { __builtin_amdgcn_s_setprio(1); _Pragma("unroll") for (int m = 0; m < 4; ++m) _Pragma("unroll") for (int n = 0; n < 2; ++n) _Pragma("unroll") for (int k = 0; k < 2; ++k) \
;         acc[ai][bj][m][n] = __builtin_amdgcn_mfma_f32_16x16x32_bf16(Bt[n][k], At[m][k], acc[ai][bj][m][n], 0, 0, 0); __builtin_amdgcn_s_setprio(0); } while (0)
; #define PG8_WAIT_V(n) asm volatile("s_waitcnt vmcnt(" #n ")" ::: "memory")
; #define PG8_WAIT_L(n) asm volatile("s_waitcnt lgkmcnt(" #n ")" ::: "memory")
; #define PG8_BAR __builtin_amdgcn_s_barrier()
; #define PG8_SCHED __builtin_amdgcn_sched_barrier(0)
; template <class Epi, class Sched>
; __device__ __forceinline__ void gemm_phase(int wid_s, PG8_LAS unsigned char* lds, const Gemm g, const Sched& S, const Epi& E) {
;     ...
;             PG8_WAIT_V(8); PG8_WAIT_L(0); PG8_BAR; PG8_MMA(1, 0, At, B0); PG8_MMA(1, 1, At, B1); PG8_BAR; PG8_SCHED;
;             PG8_LDB(B0, 1, 0); PG8_LDB(B1, 1, 1); PG8_SCHED; PG8_LDA(At, 1, 0); PG8_STAGE(PG8_SA(0, 1), a2 + hstepA, voffA);
;             PG8_WAIT_V(8); PG8_WAIT_L(0); PG8_BAR; PG8_MMA(0, 0, At, B0); PG8_MMA(0, 1, At, B1); PG8_BAR; PG8_SCHED;
	s_setprio 1
	s_waitcnt lgkmcnt(0)
	v_mfma_f32_16x16x32_bf16 v[60:63], v[138:141], v[212:215], v[60:63]
	v_mfma_f32_16x16x32_bf16 v[56:59], v[164:167], v[212:215], v[56:59]
	v_mfma_f32_16x16x32_bf16 v[44:47], v[138:141], v[220:223], v[44:47]
	v_mfma_f32_16x16x32_bf16 v[40:43], v[164:167], v[220:223], v[40:43]
	v_mfma_f32_16x16x32_bf16 v[28:31], v[138:141], v[228:231], v[28:31]
	v_mfma_f32_16x16x32_bf16 v[24:27], v[164:167], v[228:231], v[24:27]
	v_mfma_f32_16x16x32_bf16 v[12:15], v[138:141], v[236:239], v[12:15]
	v_mfma_f32_16x16x32_bf16 v[8:11], v[164:167], v[236:239], v[8:11]
	v_mfma_f32_16x16x32_bf16 v[60:63], v[160:163], v[216:219], v[60:63]
	v_mfma_f32_16x16x32_bf16 v[56:59], v[192:195], v[216:219], v[56:59]
	v_mfma_f32_16x16x32_bf16 v[44:47], v[160:163], v[224:227], v[44:47]
	v_mfma_f32_16x16x32_bf16 v[40:43], v[192:195], v[224:227], v[40:43]
	v_mfma_f32_16x16x32_bf16 v[28:31], v[160:163], v[232:235], v[28:31]
	v_mfma_f32_16x16x32_bf16 v[24:27], v[192:195], v[232:235], v[24:27]
	v_mfma_f32_16x16x32_bf16 v[12:15], v[160:163], v[240:243], v[12:15]
	v_mfma_f32_16x16x32_bf16 v[8:11], v[192:195], v[240:243], v[8:11]
	s_setprio 0
	s_setprio 1
	v_mfma_f32_16x16x32_bf16 v[52:55], v[196:199], v[212:215], v[52:55]
	v_mfma_f32_16x16x32_bf16 v[48:51], v[204:207], v[212:215], v[48:51]
	v_mfma_f32_16x16x32_bf16 v[36:39], v[196:199], v[220:223], v[36:39]
	v_mfma_f32_16x16x32_bf16 v[32:35], v[204:207], v[220:223], v[32:35]
	v_mfma_f32_16x16x32_bf16 v[20:23], v[196:199], v[228:231], v[20:23]
	v_mfma_f32_16x16x32_bf16 v[16:19], v[204:207], v[228:231], v[16:19]
	v_mfma_f32_16x16x32_bf16 v[4:7], v[196:199], v[236:239], v[4:7]
	v_mfma_f32_16x16x32_bf16 v[0:3], v[204:207], v[236:239], v[0:3]
	v_mfma_f32_16x16x32_bf16 v[52:55], v[200:203], v[216:219], v[52:55]
	v_mfma_f32_16x16x32_bf16 v[48:51], v[208:211], v[216:219], v[48:51]
	v_mfma_f32_16x16x32_bf16 v[36:39], v[200:203], v[224:227], v[36:39]
	v_mfma_f32_16x16x32_bf16 v[32:35], v[208:211], v[224:227], v[32:35]
	v_mfma_f32_16x16x32_bf16 v[20:23], v[200:203], v[232:235], v[20:23]
	v_mfma_f32_16x16x32_bf16 v[16:19], v[208:211], v[232:235], v[16:19]
	v_mfma_f32_16x16x32_bf16 v[4:7], v[200:203], v[240:243], v[4:7]
	v_mfma_f32_16x16x32_bf16 v[0:3], v[208:211], v[240:243], v[0:3]
	s_setprio 0
	s_barrier
	s_add_i32 s18, 0, 0x18000
	v_add_u32_e32 v188, s18, v157
	s_add_i32 s45, 0, 0x1c000
	ds_read_b128 v[138:141], v188
	ds_read_b128 v[160:163], v188 offset:1024
	ds_read_b128 v[164:167], v188 offset:2048
	ds_read_b128 v[192:195], v188 offset:3072
	v_add_u32_e32 v188, s45, v157
	ds_read_b128 v[196:199], v188
	ds_read_b128 v[200:203], v188 offset:1024
	ds_read_b128 v[204:207], v188 offset:2048
	ds_read_b128 v[208:211], v188 offset:3072
	s_add_u32 s34, s34, s10
	s_addc_u32 s35, s35, s11
	s_mov_b32 m0, s54
	v_lshl_add_u64 v[188:189], s[34:35], 0, v[128:129]
	ds_read_b128 v[212:215], v159 offset:32768
	ds_read_b128 v[216:219], v159 offset:33792
	ds_read_b128 v[220:223], v159 offset:34816
	ds_read_b128 v[224:227], v159 offset:35840
	ds_read_b128 v[228:231], v159 offset:36864
	ds_read_b128 v[232:235], v159 offset:37888
	ds_read_b128 v[236:239], v159 offset:38912
	ds_read_b128 v[240:243], v159 offset:39936
	global_load_lds_dwordx4 v[188:189], off
	v_lshl_add_u64 v[188:189], s[34:35], 0, v[130:131]
	s_mov_b32 m0, s55
	s_nop 0
	global_load_lds_dwordx4 v[188:189], off
	s_waitcnt vmcnt(8)
	s_barrier
	s_setprio 1
	s_waitcnt lgkmcnt(0)
	v_mfma_f32_16x16x32_bf16 v[124:127], v[138:141], v[212:215], v[124:127]
	v_mfma_f32_16x16x32_bf16 v[120:123], v[164:167], v[212:215], v[120:123]
	v_mfma_f32_16x16x32_bf16 v[108:111], v[138:141], v[220:223], v[108:111]
	v_mfma_f32_16x16x32_bf16 v[104:107], v[164:167], v[220:223], v[104:107]
	v_mfma_f32_16x16x32_bf16 v[92:95], v[138:141], v[228:231], v[92:95]
	v_mfma_f32_16x16x32_bf16 v[88:91], v[164:167], v[228:231], v[88:91]
	v_mfma_f32_16x16x32_bf16 v[76:79], v[138:141], v[236:239], v[76:79]
	v_mfma_f32_16x16x32_bf16 v[72:75], v[164:167], v[236:239], v[72:75]
	v_mfma_f32_16x16x32_bf16 v[124:127], v[160:163], v[216:219], v[124:127]
	v_mfma_f32_16x16x32_bf16 v[120:123], v[192:195], v[216:219], v[120:123]
	v_mfma_f32_16x16x32_bf16 v[108:111], v[160:163], v[224:227], v[108:111]
	v_mfma_f32_16x16x32_bf16 v[104:107], v[192:195], v[224:227], v[104:107]
	v_mfma_f32_16x16x32_bf16 v[92:95], v[160:163], v[232:235], v[92:95]
	v_mfma_f32_16x16x32_bf16 v[88:91], v[192:195], v[232:235], v[88:91]
	v_mfma_f32_16x16x32_bf16 v[76:79], v[160:163], v[240:243], v[76:79]
	v_mfma_f32_16x16x32_bf16 v[72:75], v[192:195], v[240:243], v[72:75]
	s_setprio 0
	s_setprio 1
	v_mfma_f32_16x16x32_bf16 v[116:119], v[196:199], v[212:215], v[116:119]
	v_mfma_f32_16x16x32_bf16 v[112:115], v[204:207], v[212:215], v[112:115]
	v_mfma_f32_16x16x32_bf16 v[100:103], v[196:199], v[220:223], v[100:103]
	v_mfma_f32_16x16x32_bf16 v[96:99], v[204:207], v[220:223], v[96:99]
	v_mfma_f32_16x16x32_bf16 v[84:87], v[196:199], v[228:231], v[84:87]
	v_mfma_f32_16x16x32_bf16 v[80:83], v[204:207], v[228:231], v[80:83]
	v_mfma_f32_16x16x32_bf16 v[68:71], v[196:199], v[236:239], v[68:71]
	v_mfma_f32_16x16x32_bf16 v[64:67], v[204:207], v[236:239], v[64:67]
	v_mfma_f32_16x16x32_bf16 v[116:119], v[200:203], v[216:219], v[116:119]
	v_mfma_f32_16x16x32_bf16 v[112:115], v[208:211], v[216:219], v[112:115]
	v_mfma_f32_16x16x32_bf16 v[100:103], v[200:203], v[224:227], v[100:103]
	v_mfma_f32_16x16x32_bf16 v[96:99], v[208:211], v[224:227], v[96:99]
	v_mfma_f32_16x16x32_bf16 v[84:87], v[200:203], v[232:235], v[84:87]
	v_mfma_f32_16x16x32_bf16 v[80:83], v[208:211], v[232:235], v[80:83]
	v_mfma_f32_16x16x32_bf16 v[68:71], v[200:203], v[240:243], v[68:71]
	v_mfma_f32_16x16x32_bf16 v[64:67], v[208:211], v[240:243], v[64:67]
	s_setprio 0
	s_barrier
; #define PG8_STAGE(bufoff, gbase, voff) do { _Pragma("unroll") for (int _i = 0; _i < 2; ++_i) \
;         __builtin_amdgcn_global_load_lds((const unsigned*)((const char*)(gbase) + (voff)[_i]), (PG8_LAS unsigned*)(lds + (bufoff) + ldsw + _i * 8192), 16, 0, 0); } while (0)
; #define PG8_LDA(dst, b, h) do { _Pragma("unroll") for (int m = 0; m < 4; ++m) _Pragma("unroll") for (int k = 0; k < 2; ++k) dst[m][k] = *(const PG8_LAS bf16x8*)(lds + PG8_SA(b, h) + aoff + m * 2048 + k * 1024); } while (0)
; #define PG8_MMA(ai, bj, At, Bt) do { __builtin_amdgcn_s_setprio(1); _Pragma("unroll") for (int m = 0; m < 4; ++m) _Pragma("unroll") for (int n = 0; n < 2; ++n) _Pragma("unroll") for (int k = 0; k < 2; ++k) \
;         acc[ai][bj][m][n] = __builtin_amdgcn_mfma_f32_16x16x32_bf16(Bt[n][k], At[m][k], acc[ai][bj][m][n], 0, 0, 0); __builtin_amdgcn_s_setprio(0); } while (0)
; #define PG8_WAIT_V(n) asm volatile("s_waitcnt vmcnt(" #n ")" ::: "memory")
; #define PG8_WAIT_L(n) asm volatile("s_waitcnt lgkmcnt(" #n ")" ::: "memory")
; #define PG8_BAR __builtin_amdgcn_s_barrier()
; #define PG8_SCHED __builtin_amdgcn_sched_barrier(0)
; template <class Epi, class Sched>
; __device__ __forceinline__ void gemm_phase(int wid_s, PG8_LAS unsigned char* lds, const Gemm g, const Sched& S, const Epi& E) {
;     ...
;             PG8_LDA(At, 1, 1); PG8_STAGE(PG8_SB(1, 0), b3, voffB); PG8_STAGE(PG8_SB(1, 1), b3 + hstepB, voffB); PG8_STAGE(PG8_SA(1, 0), a3, voffA);
;             PG8_WAIT_V(8); PG8_WAIT_L(0); PG8_BAR; PG8_MMA(1, 0, At, B0); PG8_MMA(1, 1, At, B1); PG8_BAR; PG8_SCHED;
;         }
	s_add_i32 s18, s18, s47
	v_lshl_add_u64 v[142:143], v[142:143], 0, s[96:97]
	s_mov_b32 m0, s18
	ds_read_b128 v[212:215], v159 offset:49152
	ds_read_b128 v[216:219], v159 offset:50176
	ds_read_b128 v[220:223], v159 offset:51200
	ds_read_b128 v[224:227], v159 offset:52224
	ds_read_b128 v[228:231], v159 offset:53248
	ds_read_b128 v[232:235], v159 offset:54272
	ds_read_b128 v[236:239], v159 offset:55296
	ds_read_b128 v[240:243], v159 offset:56320
	global_load_lds_dwordx4 v[142:143], off
	v_lshl_add_u64 v[142:143], v[244:245], 0, s[96:97]
	s_add_i32 m0, s18, 0x2000
	s_add_i32 s18, s45, s47
	global_load_lds_dwordx4 v[142:143], off
	v_lshl_add_u64 v[142:143], v[246:247], 0, s[96:97]
	s_mov_b32 m0, s18
	s_nop 0
	global_load_lds_dwordx4 v[142:143], off
	v_lshl_add_u64 v[142:143], v[248:249], 0, s[96:97]
	s_add_i32 m0, s18, 0x2000
	s_nop 0
	global_load_lds_dwordx4 v[142:143], off
	v_lshl_add_u64 v[142:143], v[250:251], 0, s[96:97]
	s_mov_b32 m0, s56
	s_nop 0
	global_load_lds_dwordx4 v[142:143], off
	v_lshl_add_u64 v[142:143], v[252:253], 0, s[96:97]
	s_mov_b32 m0, s57
	s_nop 0
	global_load_lds_dwordx4 v[142:143], off
	s_waitcnt vmcnt(8)
	s_barrier
	s_setprio 1
	s_waitcnt lgkmcnt(0)
	v_mfma_f32_16x16x32_bf16 v[60:63], v[138:141], v[212:215], v[60:63]
	v_mfma_f32_16x16x32_bf16 v[56:59], v[164:167], v[212:215], v[56:59]
	v_mfma_f32_16x16x32_bf16 v[44:47], v[138:141], v[220:223], v[44:47]
	v_mfma_f32_16x16x32_bf16 v[40:43], v[164:167], v[220:223], v[40:43]
	v_mfma_f32_16x16x32_bf16 v[28:31], v[138:141], v[228:231], v[28:31]
	v_mfma_f32_16x16x32_bf16 v[24:27], v[164:167], v[228:231], v[24:27]
	v_mfma_f32_16x16x32_bf16 v[12:15], v[138:141], v[236:239], v[12:15]
	v_mfma_f32_16x16x32_bf16 v[8:11], v[164:167], v[236:239], v[8:11]
	v_mfma_f32_16x16x32_bf16 v[60:63], v[160:163], v[216:219], v[60:63]
	v_mfma_f32_16x16x32_bf16 v[56:59], v[192:195], v[216:219], v[56:59]
	v_mfma_f32_16x16x32_bf16 v[44:47], v[160:163], v[224:227], v[44:47]
	v_mfma_f32_16x16x32_bf16 v[40:43], v[192:195], v[224:227], v[40:43]
	v_mfma_f32_16x16x32_bf16 v[28:31], v[160:163], v[232:235], v[28:31]
	v_mfma_f32_16x16x32_bf16 v[24:27], v[192:195], v[232:235], v[24:27]
	v_mfma_f32_16x16x32_bf16 v[12:15], v[160:163], v[240:243], v[12:15]
	v_mfma_f32_16x16x32_bf16 v[8:11], v[192:195], v[240:243], v[8:11]
	s_setprio 0
	s_setprio 1
	v_mfma_f32_16x16x32_bf16 v[52:55], v[196:199], v[212:215], v[52:55]
	v_mfma_f32_16x16x32_bf16 v[48:51], v[204:207], v[212:215], v[48:51]
	v_mfma_f32_16x16x32_bf16 v[36:39], v[196:199], v[220:223], v[36:39]
	v_mfma_f32_16x16x32_bf16 v[32:35], v[204:207], v[220:223], v[32:35]
	v_mfma_f32_16x16x32_bf16 v[20:23], v[196:199], v[228:231], v[20:23]
	v_mfma_f32_16x16x32_bf16 v[16:19], v[204:207], v[228:231], v[16:19]
	v_mfma_f32_16x16x32_bf16 v[4:7], v[196:199], v[236:239], v[4:7]
	v_mfma_f32_16x16x32_bf16 v[0:3], v[204:207], v[236:239], v[0:3]
	v_mfma_f32_16x16x32_bf16 v[52:55], v[200:203], v[216:219], v[52:55]
	v_mfma_f32_16x16x32_bf16 v[48:51], v[208:211], v[216:219], v[48:51]
	v_mfma_f32_16x16x32_bf16 v[36:39], v[200:203], v[224:227], v[36:39]
	v_mfma_f32_16x16x32_bf16 v[32:35], v[208:211], v[224:227], v[32:35]
	v_mfma_f32_16x16x32_bf16 v[20:23], v[200:203], v[232:235], v[20:23]
	v_mfma_f32_16x16x32_bf16 v[16:19], v[208:211], v[232:235], v[16:19]
	v_mfma_f32_16x16x32_bf16 v[4:7], v[200:203], v[240:243], v[4:7]
	v_mfma_f32_16x16x32_bf16 v[0:3], v[208:211], v[240:243], v[0:3]
	s_setprio 0
	s_barrier
	s_add_u32 s33, s33, 0x100
	s_addc_u32 s51, s51, 0
	s_add_u32 s4, s4, 0x100
	s_addc_u32 s5, s5, 0
	s_cmp_ge_i32 s44, s94
	s_mov_b32 s34, s44
	s_cbranch_scc0 .LBB0_1717
	s_movk_i32 s33, 0x300

; #define PG8_STAGE(bufoff, gbase, voff) do { _Pragma("unroll") for (int _i = 0; _i < 2; ++_i) \
;         __builtin_amdgcn_global_load_lds((const unsigned*)((const char*)(gbase) + (voff)[_i]), (PG8_LAS unsigned*)(lds + (bufoff) + ldsw + _i * 8192), 16, 0, 0); } while (0)
; #define PG8_LDA(dst, b, h) do { _Pragma("unroll") for (int m = 0; m < 4; ++m) _Pragma("unroll") for (int k = 0; k < 2; ++k) dst[m][k] = *(const PG8_LAS bf16x8*)(lds + PG8_SA(b, h) + aoff + m * 2048 + k * 1024); } while (0)
; #define PG8_LDB(dst, b, h) do { _Pragma("unroll") for (int n = 0; n < 2; ++n) _Pragma("unroll") for (int k = 0; k < 2; ++k) dst[n][k] = *(const PG8_LAS bf16x8*)(lds + PG8_SB(b, h) + boff + n * 2048 + k * 1024); } while (0)
; #define PG8_MMA(ai, bj, At, Bt) do { __builtin_amdgcn_s_setprio(1); _Pragma("unroll") for (int m = 0; m < 4; ++m) _Pragma("unroll") for (int n = 0; n < 2; ++n) _Pragma("unroll") for (int k = 0; k < 2; ++k) \
;         acc[ai][bj][m][n] = __builtin_amdgcn_mfma_f32_16x16x32_bf16(Bt[n][k], At[m][k], acc[ai][bj][m][n], 0, 0, 0); __builtin_amdgcn_s_setprio(0); } while (0)
; #define PG8_WAIT_V(n) asm volatile("s_waitcnt vmcnt(" #n ")" ::: "memory")
; #define PG8_WAIT_L(n) asm volatile("s_waitcnt lgkmcnt(" #n ")" ::: "memory")
; #define PG8_BAR __builtin_amdgcn_s_barrier()
; #define PG8_SCHED __builtin_amdgcn_sched_barrier(0)
; template <class Epi, class Sched>
; __device__ __forceinline__ void gemm_phase(int wid_s, PG8_LAS unsigned char* lds, const Gemm g, const Sched& S, const Epi& E) {
;     ...
;             const bool last = (t == nt - 2);
;             const char* a1 = cA + (size_t)(t + 1) * kstep;
;             const char* a2 = last ? nA : cA + (size_t)(t + 2) * kstep; const char* b2 = last ? nB : cB + (size_t)(t + 2) * kstep;
;             const char* a3 = a2 + kstep; const char* b3 = b2 + kstep;
;             PG8_LDB(B0, 0, 0); PG8_LDB(B1, 0, 1); PG8_SCHED; PG8_LDA(At, 0, 0); PG8_STAGE(PG8_SA(1, 1), a1 + hstepA, voffA);
;             PG8_WAIT_V(8); PG8_WAIT_L(0); PG8_BAR; PG8_MMA(0, 0, At, B0); PG8_MMA(0, 1, At, B1); PG8_BAR; PG8_SCHED;
;             PG8_LDA(At, 0, 1); PG8_STAGE(PG8_SB(0, 0), b2, voffB); PG8_STAGE(PG8_SB(0, 1), b2 + hstepB, voffB); PG8_STAGE(PG8_SA(0, 0), a2, voffA);
.LBB0_1845:
	s_add_i32 s57, s28, 2
	s_add_u32 s92, s26, 0x80
	s_addc_u32 s29, s27, 0
	s_add_i32 vcc_lo, 0, 0x10000
	s_cmp_eq_u32 s49, s28
	s_cselect_b32 s29, s23, s29
	s_cselect_b32 s28, s22, s92
	v_add_u32_e32 v155, vcc_lo, v143
	s_cselect_b32 s95, s25, s56
	s_cselect_b32 s94, s24, s33
	s_add_i32 s92, 0, 0x14000
	ds_read_b128 v[156:159], v155
	ds_read_b128 v[160:163], v155 offset:1024
	ds_read_b128 v[164:167], v155 offset:2048
	ds_read_b128 v[192:195], v155 offset:3072
	v_add_u32_e32 v155, s92, v143
	ds_read_b128 v[196:199], v155
	ds_read_b128 v[200:203], v155 offset:1024
	ds_read_b128 v[204:207], v155 offset:2048
	ds_read_b128 v[208:211], v155 offset:3072
	v_lshl_add_u64 v[188:189], s[26:27], 0, v[140:141]
	s_add_i32 m0, s40, 0xc000
	ds_read_b128 v[212:215], v154
	ds_read_b128 v[216:219], v154 offset:1024
	ds_read_b128 v[220:223], v154 offset:2048
	ds_read_b128 v[224:227], v154 offset:3072
	ds_read_b128 v[228:231], v154 offset:4096
	ds_read_b128 v[232:235], v154 offset:5120
	ds_read_b128 v[236:239], v154 offset:6144
	ds_read_b128 v[240:243], v154 offset:7168
	global_load_lds_dwordx4 v[188:189], off
	v_lshl_add_u64 v[188:189], s[26:27], 0, v[138:139]
	s_add_i32 m0, s40, 0xe000
	s_nop 0
	global_load_lds_dwordx4 v[188:189], off
	s_waitcnt vmcnt(8)
	s_barrier
	s_setprio 1
	s_waitcnt lgkmcnt(0)
	v_mfma_f32_16x16x32_bf16 v[124:127], v[156:159], v[212:215], v[124:127]
	v_mfma_f32_16x16x32_bf16 v[120:123], v[164:167], v[212:215], v[120:123]
	v_mfma_f32_16x16x32_bf16 v[112:115], v[156:159], v[220:223], v[112:115]
	v_mfma_f32_16x16x32_bf16 v[108:111], v[164:167], v[220:223], v[108:111]
	v_mfma_f32_16x16x32_bf16 v[92:95], v[156:159], v[228:231], v[92:95]
	v_mfma_f32_16x16x32_bf16 v[88:91], v[164:167], v[228:231], v[88:91]
	v_mfma_f32_16x16x32_bf16 v[76:79], v[156:159], v[236:239], v[76:79]
	v_mfma_f32_16x16x32_bf16 v[72:75], v[164:167], v[236:239], v[72:75]
	v_mfma_f32_16x16x32_bf16 v[124:127], v[160:163], v[216:219], v[124:127]
	v_mfma_f32_16x16x32_bf16 v[120:123], v[192:195], v[216:219], v[120:123]
	v_mfma_f32_16x16x32_bf16 v[112:115], v[160:163], v[224:227], v[112:115]
	v_mfma_f32_16x16x32_bf16 v[108:111], v[192:195], v[224:227], v[108:111]
	v_mfma_f32_16x16x32_bf16 v[92:95], v[160:163], v[232:235], v[92:95]
	v_mfma_f32_16x16x32_bf16 v[88:91], v[192:195], v[232:235], v[88:91]
	v_mfma_f32_16x16x32_bf16 v[76:79], v[160:163], v[240:243], v[76:79]
	v_mfma_f32_16x16x32_bf16 v[72:75], v[192:195], v[240:243], v[72:75]
	s_setprio 0
	s_setprio 1
	v_mfma_f32_16x16x32_bf16 v[104:107], v[196:199], v[212:215], v[104:107]
	v_mfma_f32_16x16x32_bf16 v[116:119], v[204:207], v[212:215], v[116:119]
	v_mfma_f32_16x16x32_bf16 v[100:103], v[196:199], v[220:223], v[100:103]
	v_mfma_f32_16x16x32_bf16 v[96:99], v[204:207], v[220:223], v[96:99]
	v_mfma_f32_16x16x32_bf16 v[84:87], v[196:199], v[228:231], v[84:87]
	v_mfma_f32_16x16x32_bf16 v[80:83], v[204:207], v[228:231], v[80:83]
	v_mfma_f32_16x16x32_bf16 v[68:71], v[196:199], v[236:239], v[68:71]
	v_mfma_f32_16x16x32_bf16 v[64:67], v[204:207], v[236:239], v[64:67]
	v_mfma_f32_16x16x32_bf16 v[104:107], v[200:203], v[216:219], v[104:107]
	v_mfma_f32_16x16x32_bf16 v[116:119], v[208:211], v[216:219], v[116:119]
	v_mfma_f32_16x16x32_bf16 v[100:103], v[200:203], v[224:227], v[100:103]
	v_mfma_f32_16x16x32_bf16 v[96:99], v[208:211], v[224:227], v[96:99]
	v_mfma_f32_16x16x32_bf16 v[84:87], v[200:203], v[232:235], v[84:87]
	v_mfma_f32_16x16x32_bf16 v[80:83], v[208:211], v[232:235], v[80:83]
	v_mfma_f32_16x16x32_bf16 v[68:71], v[200:203], v[240:243], v[68:71]
	v_mfma_f32_16x16x32_bf16 v[64:67], v[208:211], v[240:243], v[64:67]
	s_setprio 0
	s_barrier
	s_add_i32 vcc_lo, vcc_lo, s39
	v_lshl_add_u64 v[188:189], s[94:95], 0, v[130:131]
	s_mov_b32 m0, vcc_lo
	ds_read_b128 v[212:215], v154 offset:16384
	ds_read_b128 v[216:219], v154 offset:17408
	ds_read_b128 v[220:223], v154 offset:18432
	ds_read_b128 v[224:227], v154 offset:19456
	ds_read_b128 v[228:231], v154 offset:20480
	ds_read_b128 v[232:235], v154 offset:21504
	ds_read_b128 v[236:239], v154 offset:22528
	ds_read_b128 v[240:243], v154 offset:23552
	global_load_lds_dwordx4 v[188:189], off
	s_add_i32 m0, vcc_lo, 0x2000
	v_lshl_add_u64 v[244:245], s[94:95], 0, v[134:135]
	s_add_u32 s94, s94, s6
	s_addc_u32 s95, s95, s7
	s_add_i32 s92, s92, s39
	global_load_lds_dwordx4 v[244:245], off
	v_lshl_add_u64 v[246:247], s[94:95], 0, v[130:131]
	s_mov_b32 m0, s92
	v_lshl_add_u64 v[248:249], s[94:95], 0, v[134:135]
	global_load_lds_dwordx4 v[246:247], off
	s_add_i32 m0, s92, 0x2000
	v_lshl_add_u64 v[250:251], s[28:29], 0, v[128:129]
	global_load_lds_dwordx4 v[248:249], off
	s_mov_b32 m0, s40
	v_lshl_add_u64 v[252:253], s[28:29], 0, v[132:133]
	global_load_lds_dwordx4 v[250:251], off
	s_mov_b32 m0, s41
	s_nop 0
	global_load_lds_dwordx4 v[252:253], off
	s_waitcnt vmcnt(8)
	s_barrier
; #define PG8_STAGE(bufoff, gbase, voff) do { _Pragma("unroll") for (int _i = 0; _i < 2; ++_i) \
;         __builtin_amdgcn_global_load_lds((const unsigned*)((const char*)(gbase) + (voff)[_i]), (PG8_LAS unsigned*)(lds + (bufoff) + ldsw + _i * 8192), 16, 0, 0); } while (0)
; #define PG8_LDA(dst, b, h) do { _Pragma("unroll") for (int m = 0; m < 4; ++m) _Pragma("unroll") for (int k = 0; k < 2; ++k) dst[m][k] = *(const PG8_LAS bf16x8*)(lds + PG8_SA(b, h) + aoff + m * 2048 + k * 1024); } while (0)
; #define PG8_LDB(dst, b, h) do { _Pragma("unroll") for (int n = 0; n < 2; ++n) _Pragma("unroll") for (int k = 0; k < 2; ++k) dst[n][k] = *(const PG8_LAS bf16x8*)(lds + PG8_SB(b, h) + boff + n * 2048 + k * 1024); } while (0)
; #define PG8_MMA(ai, bj, At, Bt) do { __builtin_amdgcn_s_setprio(1); _Pragma("unroll") for (int m = 0; m < 4; ++m) _Pragma("unroll") for (int n = 0; n < 2; ++n) _Pragma("unroll") for (int k = 0; k < 2; ++k) \
;         acc[ai][bj][m][n] = __builtin_amdgcn_mfma_f32_16x16x32_bf16(Bt[n][k], At[m][k], acc[ai][bj][m][n], 0, 0, 0); __builtin_amdgcn_s_setprio(0); } while (0)
; #define PG8_WAIT_V(n) asm volatile("s_waitcnt vmcnt(" #n ")" ::: "memory")
; #define PG8_WAIT_L(n) asm volatile("s_waitcnt lgkmcnt(" #n ")" ::: "memory")
; #define PG8_BAR __builtin_amdgcn_s_barrier()
; #define PG8_SCHED __builtin_amdgcn_sched_barrier(0)
; template <class Epi, class Sched>
; __device__ __forceinline__ void gemm_phase(int wid_s, PG8_LAS unsigned char* lds, const Gemm g, const Sched& S, const Epi& E) {
;     ...
;             PG8_WAIT_V(8); PG8_WAIT_L(0); PG8_BAR; PG8_MMA(1, 0, At, B0); PG8_MMA(1, 1, At, B1); PG8_BAR; PG8_SCHED;
;             PG8_LDB(B0, 1, 0); PG8_LDB(B1, 1, 1); PG8_SCHED; PG8_LDA(At, 1, 0); PG8_STAGE(PG8_SA(0, 1), a2 + hstepA, voffA);
;             PG8_WAIT_V(8); PG8_WAIT_L(0); PG8_BAR; PG8_MMA(0, 0, At, B0); PG8_MMA(0, 1, At, B1); PG8_BAR; PG8_SCHED;
	s_setprio 1
	s_waitcnt lgkmcnt(0)
	v_mfma_f32_16x16x32_bf16 v[60:63], v[156:159], v[212:215], v[60:63]
	v_mfma_f32_16x16x32_bf16 v[56:59], v[164:167], v[212:215], v[56:59]
	v_mfma_f32_16x16x32_bf16 v[44:47], v[156:159], v[220:223], v[44:47]
	v_mfma_f32_16x16x32_bf16 v[40:43], v[164:167], v[220:223], v[40:43]
	v_mfma_f32_16x16x32_bf16 v[28:31], v[156:159], v[228:231], v[28:31]
	v_mfma_f32_16x16x32_bf16 v[24:27], v[164:167], v[228:231], v[24:27]
	v_mfma_f32_16x16x32_bf16 v[12:15], v[156:159], v[236:239], v[12:15]
	v_mfma_f32_16x16x32_bf16 v[8:11], v[164:167], v[236:239], v[8:11]
	v_mfma_f32_16x16x32_bf16 v[60:63], v[160:163], v[216:219], v[60:63]
	v_mfma_f32_16x16x32_bf16 v[56:59], v[192:195], v[216:219], v[56:59]
	v_mfma_f32_16x16x32_bf16 v[44:47], v[160:163], v[224:227], v[44:47]
	v_mfma_f32_16x16x32_bf16 v[40:43], v[192:195], v[224:227], v[40:43]
	v_mfma_f32_16x16x32_bf16 v[28:31], v[160:163], v[232:235], v[28:31]
	v_mfma_f32_16x16x32_bf16 v[24:27], v[192:195], v[232:235], v[24:27]
	v_mfma_f32_16x16x32_bf16 v[12:15], v[160:163], v[240:243], v[12:15]
	v_mfma_f32_16x16x32_bf16 v[8:11], v[192:195], v[240:243], v[8:11]
	s_setprio 0
	s_setprio 1
	v_mfma_f32_16x16x32_bf16 v[52:55], v[196:199], v[212:215], v[52:55]
	v_mfma_f32_16x16x32_bf16 v[48:51], v[204:207], v[212:215], v[48:51]
	v_mfma_f32_16x16x32_bf16 v[36:39], v[196:199], v[220:223], v[36:39]
	v_mfma_f32_16x16x32_bf16 v[32:35], v[204:207], v[220:223], v[32:35]
	v_mfma_f32_16x16x32_bf16 v[20:23], v[196:199], v[228:231], v[20:23]
	v_mfma_f32_16x16x32_bf16 v[16:19], v[204:207], v[228:231], v[16:19]
	v_mfma_f32_16x16x32_bf16 v[4:7], v[196:199], v[236:239], v[4:7]
	v_mfma_f32_16x16x32_bf16 v[0:3], v[204:207], v[236:239], v[0:3]
	v_mfma_f32_16x16x32_bf16 v[52:55], v[200:203], v[216:219], v[52:55]
	v_mfma_f32_16x16x32_bf16 v[48:51], v[208:211], v[216:219], v[48:51]
	v_mfma_f32_16x16x32_bf16 v[36:39], v[200:203], v[224:227], v[36:39]
	v_mfma_f32_16x16x32_bf16 v[32:35], v[208:211], v[224:227], v[32:35]
	v_mfma_f32_16x16x32_bf16 v[20:23], v[200:203], v[232:235], v[20:23]
	v_mfma_f32_16x16x32_bf16 v[16:19], v[208:211], v[232:235], v[16:19]
	v_mfma_f32_16x16x32_bf16 v[4:7], v[200:203], v[240:243], v[4:7]
	v_mfma_f32_16x16x32_bf16 v[0:3], v[208:211], v[240:243], v[0:3]
	s_setprio 0
	s_barrier
	s_add_i32 s92, 0, 0x18000
	v_add_u32_e32 v155, s92, v143
	s_add_i32 s94, 0, 0x1c000
	ds_read_b128 v[156:159], v155
	ds_read_b128 v[160:163], v155 offset:1024
	ds_read_b128 v[164:167], v155 offset:2048
	ds_read_b128 v[192:195], v155 offset:3072
	v_add_u32_e32 v155, s94, v143
	ds_read_b128 v[196:199], v155
	ds_read_b128 v[200:203], v155 offset:1024
	ds_read_b128 v[204:207], v155 offset:2048
	ds_read_b128 v[208:211], v155 offset:3072
	s_add_u32 s28, s28, s4
	s_addc_u32 s29, s29, s5
	s_mov_b32 m0, s42
	v_lshl_add_u64 v[190:191], s[28:29], 0, v[128:129]
	ds_read_b128 v[212:215], v154 offset:32768
	ds_read_b128 v[216:219], v154 offset:33792
	ds_read_b128 v[220:223], v154 offset:34816
	ds_read_b128 v[224:227], v154 offset:35840
	ds_read_b128 v[228:231], v154 offset:36864
	ds_read_b128 v[232:235], v154 offset:37888
	ds_read_b128 v[236:239], v154 offset:38912
	ds_read_b128 v[240:243], v154 offset:39936
	global_load_lds_dwordx4 v[190:191], off
	v_lshl_add_u64 v[190:191], s[28:29], 0, v[132:133]
	s_mov_b32 m0, s44
	s_nop 0
	global_load_lds_dwordx4 v[190:191], off
	s_waitcnt vmcnt(8)
	s_barrier
	s_setprio 1
	s_waitcnt lgkmcnt(0)
	v_mfma_f32_16x16x32_bf16 v[124:127], v[156:159], v[212:215], v[124:127]
	v_mfma_f32_16x16x32_bf16 v[120:123], v[164:167], v[212:215], v[120:123]
	v_mfma_f32_16x16x32_bf16 v[112:115], v[156:159], v[220:223], v[112:115]
	v_mfma_f32_16x16x32_bf16 v[108:111], v[164:167], v[220:223], v[108:111]
	v_mfma_f32_16x16x32_bf16 v[92:95], v[156:159], v[228:231], v[92:95]
	v_mfma_f32_16x16x32_bf16 v[88:91], v[164:167], v[228:231], v[88:91]
	v_mfma_f32_16x16x32_bf16 v[76:79], v[156:159], v[236:239], v[76:79]
	v_mfma_f32_16x16x32_bf16 v[72:75], v[164:167], v[236:239], v[72:75]
	v_mfma_f32_16x16x32_bf16 v[124:127], v[160:163], v[216:219], v[124:127]
	v_mfma_f32_16x16x32_bf16 v[120:123], v[192:195], v[216:219], v[120:123]
	v_mfma_f32_16x16x32_bf16 v[112:115], v[160:163], v[224:227], v[112:115]
	v_mfma_f32_16x16x32_bf16 v[108:111], v[192:195], v[224:227], v[108:111]
	v_mfma_f32_16x16x32_bf16 v[92:95], v[160:163], v[232:235], v[92:95]
	v_mfma_f32_16x16x32_bf16 v[88:91], v[192:195], v[232:235], v[88:91]
	v_mfma_f32_16x16x32_bf16 v[76:79], v[160:163], v[240:243], v[76:79]
	v_mfma_f32_16x16x32_bf16 v[72:75], v[192:195], v[240:243], v[72:75]
	s_setprio 0
	s_setprio 1
	v_mfma_f32_16x16x32_bf16 v[104:107], v[196:199], v[212:215], v[104:107]
	v_mfma_f32_16x16x32_bf16 v[116:119], v[204:207], v[212:215], v[116:119]
	v_mfma_f32_16x16x32_bf16 v[100:103], v[196:199], v[220:223], v[100:103]
	v_mfma_f32_16x16x32_bf16 v[96:99], v[204:207], v[220:223], v[96:99]
	v_mfma_f32_16x16x32_bf16 v[84:87], v[196:199], v[228:231], v[84:87]
	v_mfma_f32_16x16x32_bf16 v[80:83], v[204:207], v[228:231], v[80:83]
	v_mfma_f32_16x16x32_bf16 v[68:71], v[196:199], v[236:239], v[68:71]
	v_mfma_f32_16x16x32_bf16 v[64:67], v[204:207], v[236:239], v[64:67]
	v_mfma_f32_16x16x32_bf16 v[104:107], v[200:203], v[216:219], v[104:107]
	v_mfma_f32_16x16x32_bf16 v[116:119], v[208:211], v[216:219], v[116:119]
	v_mfma_f32_16x16x32_bf16 v[100:103], v[200:203], v[224:227], v[100:103]
	v_mfma_f32_16x16x32_bf16 v[96:99], v[208:211], v[224:227], v[96:99]
	v_mfma_f32_16x16x32_bf16 v[84:87], v[200:203], v[232:235], v[84:87]
	v_mfma_f32_16x16x32_bf16 v[80:83], v[208:211], v[232:235], v[80:83]
	v_mfma_f32_16x16x32_bf16 v[68:71], v[200:203], v[240:243], v[68:71]
	v_mfma_f32_16x16x32_bf16 v[64:67], v[208:211], v[240:243], v[64:67]
	s_setprio 0
	s_barrier
; #define PG8_STAGE(bufoff, gbase, voff) do { _Pragma("unroll") for (int _i = 0; _i < 2; ++_i) \
;         __builtin_amdgcn_global_load_lds((const unsigned*)((const char*)(gbase) + (voff)[_i]), (PG8_LAS unsigned*)(lds + (bufoff) + ldsw + _i * 8192), 16, 0, 0); } while (0)
; #define PG8_LDA(dst, b, h) do { _Pragma("unroll") for (int m = 0; m < 4; ++m) _Pragma("unroll") for (int k = 0; k < 2; ++k) dst[m][k] = *(const PG8_LAS bf16x8*)(lds + PG8_SA(b, h) + aoff + m * 2048 + k * 1024); } while (0)
; #define PG8_MMA(ai, bj, At, Bt) do { __builtin_amdgcn_s_setprio(1); _Pragma("unroll") for (int m = 0; m < 4; ++m) _Pragma("unroll") for (int n = 0; n < 2; ++n) _Pragma("unroll") for (int k = 0; k < 2; ++k) \
;         acc[ai][bj][m][n] = __builtin_amdgcn_mfma_f32_16x16x32_bf16(Bt[n][k], At[m][k], acc[ai][bj][m][n], 0, 0, 0); __builtin_amdgcn_s_setprio(0); } while (0)
; #define PG8_WAIT_V(n) asm volatile("s_waitcnt vmcnt(" #n ")" ::: "memory")
; #define PG8_WAIT_L(n) asm volatile("s_waitcnt lgkmcnt(" #n ")" ::: "memory")
; #define PG8_BAR __builtin_amdgcn_s_barrier()
; #define PG8_SCHED __builtin_amdgcn_sched_barrier(0)
; template <class Epi, class Sched>
; __device__ __forceinline__ void gemm_phase(int wid_s, PG8_LAS unsigned char* lds, const Gemm g, const Sched& S, const Epi& E) {
;     ...
;             PG8_LDA(At, 1, 1); PG8_STAGE(PG8_SB(1, 0), b3, voffB); PG8_STAGE(PG8_SB(1, 1), b3 + hstepB, voffB); PG8_STAGE(PG8_SA(1, 0), a3, voffA);
;             PG8_WAIT_V(8); PG8_WAIT_L(0); PG8_BAR; PG8_MMA(1, 0, At, B0); PG8_MMA(1, 1, At, B1); PG8_BAR; PG8_SCHED;
;         }
	s_add_i32 s28, s92, s39
	v_lshl_add_u64 v[188:189], v[188:189], 0, s[96:97]
	s_mov_b32 m0, s28
	ds_read_b128 v[212:215], v154 offset:49152
	ds_read_b128 v[216:219], v154 offset:50176
	ds_read_b128 v[220:223], v154 offset:51200
	ds_read_b128 v[224:227], v154 offset:52224
	ds_read_b128 v[228:231], v154 offset:53248
	ds_read_b128 v[232:235], v154 offset:54272
	ds_read_b128 v[236:239], v154 offset:55296
	ds_read_b128 v[240:243], v154 offset:56320
	global_load_lds_dwordx4 v[188:189], off
	v_lshl_add_u64 v[188:189], v[244:245], 0, s[96:97]
	s_add_i32 m0, s28, 0x2000
	s_add_i32 s28, s94, s39
	global_load_lds_dwordx4 v[188:189], off
	v_lshl_add_u64 v[188:189], v[246:247], 0, s[96:97]
	s_mov_b32 m0, s28
	s_nop 0
	global_load_lds_dwordx4 v[188:189], off
	v_lshl_add_u64 v[188:189], v[248:249], 0, s[96:97]
	s_add_i32 m0, s28, 0x2000
	s_nop 0
	global_load_lds_dwordx4 v[188:189], off
	v_lshl_add_u64 v[188:189], v[250:251], 0, s[96:97]
	s_mov_b32 m0, s47
	s_nop 0
	global_load_lds_dwordx4 v[188:189], off
	v_lshl_add_u64 v[188:189], v[252:253], 0, s[96:97]
	s_mov_b32 m0, s48
	s_nop 0
	global_load_lds_dwordx4 v[188:189], off
	s_waitcnt vmcnt(8)
	s_barrier
	s_setprio 1
	s_waitcnt lgkmcnt(0)
	v_mfma_f32_16x16x32_bf16 v[60:63], v[156:159], v[212:215], v[60:63]
	v_mfma_f32_16x16x32_bf16 v[56:59], v[164:167], v[212:215], v[56:59]
	v_mfma_f32_16x16x32_bf16 v[44:47], v[156:159], v[220:223], v[44:47]
	v_mfma_f32_16x16x32_bf16 v[40:43], v[164:167], v[220:223], v[40:43]
	v_mfma_f32_16x16x32_bf16 v[28:31], v[156:159], v[228:231], v[28:31]
	v_mfma_f32_16x16x32_bf16 v[24:27], v[164:167], v[228:231], v[24:27]
	v_mfma_f32_16x16x32_bf16 v[12:15], v[156:159], v[236:239], v[12:15]
	v_mfma_f32_16x16x32_bf16 v[8:11], v[164:167], v[236:239], v[8:11]
	v_mfma_f32_16x16x32_bf16 v[60:63], v[160:163], v[216:219], v[60:63]
	v_mfma_f32_16x16x32_bf16 v[56:59], v[192:195], v[216:219], v[56:59]
	v_mfma_f32_16x16x32_bf16 v[44:47], v[160:163], v[224:227], v[44:47]
	v_mfma_f32_16x16x32_bf16 v[40:43], v[192:195], v[224:227], v[40:43]
	v_mfma_f32_16x16x32_bf16 v[28:31], v[160:163], v[232:235], v[28:31]
	v_mfma_f32_16x16x32_bf16 v[24:27], v[192:195], v[232:235], v[24:27]
	v_mfma_f32_16x16x32_bf16 v[12:15], v[160:163], v[240:243], v[12:15]
	v_mfma_f32_16x16x32_bf16 v[8:11], v[192:195], v[240:243], v[8:11]
	s_setprio 0
	s_setprio 1
	v_mfma_f32_16x16x32_bf16 v[52:55], v[196:199], v[212:215], v[52:55]
	v_mfma_f32_16x16x32_bf16 v[48:51], v[204:207], v[212:215], v[48:51]
	v_mfma_f32_16x16x32_bf16 v[36:39], v[196:199], v[220:223], v[36:39]
	v_mfma_f32_16x16x32_bf16 v[32:35], v[204:207], v[220:223], v[32:35]
	v_mfma_f32_16x16x32_bf16 v[20:23], v[196:199], v[228:231], v[20:23]
	v_mfma_f32_16x16x32_bf16 v[16:19], v[204:207], v[228:231], v[16:19]
	v_mfma_f32_16x16x32_bf16 v[4:7], v[196:199], v[236:239], v[4:7]
	v_mfma_f32_16x16x32_bf16 v[0:3], v[204:207], v[236:239], v[0:3]
	v_mfma_f32_16x16x32_bf16 v[52:55], v[200:203], v[216:219], v[52:55]
	v_mfma_f32_16x16x32_bf16 v[48:51], v[208:211], v[216:219], v[48:51]
	v_mfma_f32_16x16x32_bf16 v[36:39], v[200:203], v[224:227], v[36:39]
	v_mfma_f32_16x16x32_bf16 v[32:35], v[208:211], v[224:227], v[32:35]
	v_mfma_f32_16x16x32_bf16 v[20:23], v[200:203], v[232:235], v[20:23]
	v_mfma_f32_16x16x32_bf16 v[16:19], v[208:211], v[232:235], v[16:19]
	v_mfma_f32_16x16x32_bf16 v[4:7], v[200:203], v[240:243], v[4:7]
	v_mfma_f32_16x16x32_bf16 v[0:3], v[208:211], v[240:243], v[0:3]
	s_setprio 0
	s_barrier
	s_add_u32 s33, s33, 0x100
	s_addc_u32 s56, s56, 0
	s_add_u32 s26, s26, 0x100
	s_addc_u32 s27, s27, 0
	s_cmp_ge_i32 s57, s45
	s_mov_b32 s28, s57
	s_cbranch_scc0 .LBB0_1845
	v_readlane_b32 s95, v254, 51
	v_readlane_b32 s92, v254, 54
	v_readlane_b32 s94, v254, 55
	s_and_b64 vcc, exec, s[20:21]
	s_cbranch_vccnz .LBB0_1850
	s_branch .LBB0_1851

; #define PG8_STAGE(bufoff, gbase, voff) do { _Pragma("unroll") for (int _i = 0; _i < 2; ++_i) \
;         __builtin_amdgcn_global_load_lds((const unsigned*)((const char*)(gbase) + (voff)[_i]), (PG8_LAS unsigned*)(lds + (bufoff) + ldsw + _i * 8192), 16, 0, 0); } while (0)
; #define PG8_LDA(dst, b, h) do { _Pragma("unroll") for (int m = 0; m < 4; ++m) _Pragma("unroll") for (int k = 0; k < 2; ++k) dst[m][k] = *(const PG8_LAS bf16x8*)(lds + PG8_SA(b, h) + aoff + m * 2048 + k * 1024); } while (0)
; #define PG8_LDB(dst, b, h) do { _Pragma("unroll") for (int n = 0; n < 2; ++n) _Pragma("unroll") for (int k = 0; k < 2; ++k) dst[n][k] = *(const PG8_LAS bf16x8*)(lds + PG8_SB(b, h) + boff + n * 2048 + k * 1024); } while (0)
; #define PG8_MMA(ai, bj, At, Bt) do { __builtin_amdgcn_s_setprio(1); _Pragma("unroll") for (int m = 0; m < 4; ++m) _Pragma("unroll") for (int n = 0; n < 2; ++n) _Pragma("unroll") for (int k = 0; k < 2; ++k) \
;         acc[ai][bj][m][n] = __builtin_amdgcn_mfma_f32_16x16x32_bf16(Bt[n][k], At[m][k], acc[ai][bj][m][n], 0, 0, 0); __builtin_amdgcn_s_setprio(0); } while (0)
; #define PG8_WAIT_V(n) asm volatile("s_waitcnt vmcnt(" #n ")" ::: "memory")
; #define PG8_WAIT_L(n) asm volatile("s_waitcnt lgkmcnt(" #n ")" ::: "memory")
; #define PG8_BAR __builtin_amdgcn_s_barrier()
; #define PG8_SCHED __builtin_amdgcn_sched_barrier(0)
; template <class Epi, class Sched>
; __device__ __forceinline__ void gemm_phase(int wid_s, PG8_LAS unsigned char* lds, const Gemm g, const Sched& S, const Epi& E) {
;     ...
;             const bool last = (t == nt - 2);
;             const char* a1 = cA + (size_t)(t + 1) * kstep;
;             const char* a2 = last ? nA : cA + (size_t)(t + 2) * kstep; const char* b2 = last ? nB : cB + (size_t)(t + 2) * kstep;
;             const char* a3 = a2 + kstep; const char* b3 = b2 + kstep;
;             PG8_LDB(B0, 0, 0); PG8_LDB(B1, 0, 1); PG8_SCHED; PG8_LDA(At, 0, 0); PG8_STAGE(PG8_SA(1, 1), a1 + hstepA, voffA);
;             PG8_WAIT_V(8); PG8_WAIT_L(0); PG8_BAR; PG8_MMA(0, 0, At, B0); PG8_MMA(0, 1, At, B1); PG8_BAR; PG8_SCHED;
;             PG8_LDA(At, 0, 1); PG8_STAGE(PG8_SB(0, 0), b2, voffB); PG8_STAGE(PG8_SB(0, 1), b2 + hstepB, voffB); PG8_STAGE(PG8_SA(0, 0), a2, voffA);
.LBB0_2148:
	s_add_i32 s55, s28, 2
	s_add_u32 s56, s26, 0x80
	s_addc_u32 s29, s27, 0
	s_add_i32 s92, 0, 0x10000
	s_cmp_eq_u32 s47, s28
	s_cselect_b32 s29, s5, s29
	s_cselect_b32 s28, s4, s56
	v_add_u32_e32 v138, s92, v142
	s_cselect_b32 s57, s25, s54
	s_cselect_b32 s56, s24, s33
	s_add_i32 s94, 0, 0x14000
	ds_read_b128 v[156:159], v138
	ds_read_b128 v[160:163], v138 offset:1024
	ds_read_b128 v[164:167], v138 offset:2048
	ds_read_b128 v[188:191], v138 offset:3072
	v_add_u32_e32 v138, s94, v142
	ds_read_b128 v[192:195], v138
	ds_read_b128 v[196:199], v138 offset:1024
	ds_read_b128 v[200:203], v138 offset:2048
	ds_read_b128 v[204:207], v138 offset:3072
	v_lshl_add_u64 v[138:139], s[26:27], 0, v[136:137]
	s_add_i32 m0, s39, 0xc000
	ds_read_b128 v[208:211], v154
	ds_read_b128 v[212:215], v154 offset:1024
	ds_read_b128 v[216:219], v154 offset:2048
	ds_read_b128 v[220:223], v154 offset:3072
	ds_read_b128 v[224:227], v154 offset:4096
	ds_read_b128 v[228:231], v154 offset:5120
	ds_read_b128 v[232:235], v154 offset:6144
	ds_read_b128 v[236:239], v154 offset:7168
	global_load_lds_dwordx4 v[138:139], off
	v_lshl_add_u64 v[138:139], s[26:27], 0, v[134:135]
	s_add_i32 m0, s39, 0xe000
	s_nop 0
	global_load_lds_dwordx4 v[138:139], off
	s_waitcnt vmcnt(8)
	s_barrier
	s_setprio 1
	s_waitcnt lgkmcnt(0)
	v_mfma_f32_16x16x32_bf16 v[120:123], v[156:159], v[208:211], v[120:123]
	v_mfma_f32_16x16x32_bf16 v[124:127], v[164:167], v[208:211], v[124:127]
	v_mfma_f32_16x16x32_bf16 v[108:111], v[156:159], v[216:219], v[108:111]
	v_mfma_f32_16x16x32_bf16 v[104:107], v[164:167], v[216:219], v[104:107]
	v_mfma_f32_16x16x32_bf16 v[92:95], v[156:159], v[224:227], v[92:95]
	v_mfma_f32_16x16x32_bf16 v[88:91], v[164:167], v[224:227], v[88:91]
	v_mfma_f32_16x16x32_bf16 v[76:79], v[156:159], v[232:235], v[76:79]
	v_mfma_f32_16x16x32_bf16 v[72:75], v[164:167], v[232:235], v[72:75]
	v_mfma_f32_16x16x32_bf16 v[120:123], v[160:163], v[212:215], v[120:123]
	v_mfma_f32_16x16x32_bf16 v[124:127], v[188:191], v[212:215], v[124:127]
	v_mfma_f32_16x16x32_bf16 v[108:111], v[160:163], v[220:223], v[108:111]
	v_mfma_f32_16x16x32_bf16 v[104:107], v[188:191], v[220:223], v[104:107]
	v_mfma_f32_16x16x32_bf16 v[92:95], v[160:163], v[228:231], v[92:95]
	v_mfma_f32_16x16x32_bf16 v[88:91], v[188:191], v[228:231], v[88:91]
	v_mfma_f32_16x16x32_bf16 v[76:79], v[160:163], v[236:239], v[76:79]
	v_mfma_f32_16x16x32_bf16 v[72:75], v[188:191], v[236:239], v[72:75]
	s_setprio 0
	s_setprio 1
	v_mfma_f32_16x16x32_bf16 v[116:119], v[192:195], v[208:211], v[116:119]
	v_mfma_f32_16x16x32_bf16 v[112:115], v[200:203], v[208:211], v[112:115]
	v_mfma_f32_16x16x32_bf16 v[100:103], v[192:195], v[216:219], v[100:103]
	v_mfma_f32_16x16x32_bf16 v[96:99], v[200:203], v[216:219], v[96:99]
	v_mfma_f32_16x16x32_bf16 v[84:87], v[192:195], v[224:227], v[84:87]
	v_mfma_f32_16x16x32_bf16 v[80:83], v[200:203], v[224:227], v[80:83]
	v_mfma_f32_16x16x32_bf16 v[68:71], v[192:195], v[232:235], v[68:71]
	v_mfma_f32_16x16x32_bf16 v[64:67], v[200:203], v[232:235], v[64:67]
	v_mfma_f32_16x16x32_bf16 v[116:119], v[196:199], v[212:215], v[116:119]
	v_mfma_f32_16x16x32_bf16 v[112:115], v[204:207], v[212:215], v[112:115]
	v_mfma_f32_16x16x32_bf16 v[100:103], v[196:199], v[220:223], v[100:103]
	v_mfma_f32_16x16x32_bf16 v[96:99], v[204:207], v[220:223], v[96:99]
	v_mfma_f32_16x16x32_bf16 v[84:87], v[196:199], v[228:231], v[84:87]
	v_mfma_f32_16x16x32_bf16 v[80:83], v[204:207], v[228:231], v[80:83]
	v_mfma_f32_16x16x32_bf16 v[68:71], v[196:199], v[236:239], v[68:71]
	v_mfma_f32_16x16x32_bf16 v[64:67], v[204:207], v[236:239], v[64:67]
	s_setprio 0
	s_barrier
	s_add_i32 s92, s92, s37
	v_lshl_add_u64 v[138:139], s[56:57], 0, v[144:145]
	s_mov_b32 m0, s92
	ds_read_b128 v[208:211], v154 offset:16384
	ds_read_b128 v[212:215], v154 offset:17408
	ds_read_b128 v[216:219], v154 offset:18432
	ds_read_b128 v[220:223], v154 offset:19456
	ds_read_b128 v[224:227], v154 offset:20480
	ds_read_b128 v[228:231], v154 offset:21504
	ds_read_b128 v[232:235], v154 offset:22528
	ds_read_b128 v[236:239], v154 offset:23552
	global_load_lds_dwordx4 v[138:139], off
	s_add_i32 m0, s92, 0x2000
	v_lshl_add_u64 v[240:241], s[56:57], 0, v[132:133]
	s_add_u32 s56, s56, s8
	s_addc_u32 s57, s57, s9
	s_add_i32 s92, s94, s37
	global_load_lds_dwordx4 v[240:241], off
	v_lshl_add_u64 v[242:243], s[56:57], 0, v[144:145]
	s_mov_b32 m0, s92
	v_lshl_add_u64 v[244:245], s[56:57], 0, v[132:133]
	global_load_lds_dwordx4 v[242:243], off
	s_add_i32 m0, s92, 0x2000
	v_lshl_add_u64 v[246:247], s[28:29], 0, v[128:129]
	global_load_lds_dwordx4 v[244:245], off
	s_mov_b32 m0, s39
	v_lshl_add_u64 v[248:249], s[28:29], 0, v[130:131]
	global_load_lds_dwordx4 v[246:247], off
	s_mov_b32 m0, s40
	s_nop 0
	global_load_lds_dwordx4 v[248:249], off
	s_waitcnt vmcnt(8)
	s_barrier
; #define PG8_STAGE(bufoff, gbase, voff) do { _Pragma("unroll") for (int _i = 0; _i < 2; ++_i) \
;         __builtin_amdgcn_global_load_lds((const unsigned*)((const char*)(gbase) + (voff)[_i]), (PG8_LAS unsigned*)(lds + (bufoff) + ldsw + _i * 8192), 16, 0, 0); } while (0)
; #define PG8_LDA(dst, b, h) do { _Pragma("unroll") for (int m = 0; m < 4; ++m) _Pragma("unroll") for (int k = 0; k < 2; ++k) dst[m][k] = *(const PG8_LAS bf16x8*)(lds + PG8_SA(b, h) + aoff + m * 2048 + k * 1024); } while (0)
; #define PG8_LDB(dst, b, h) do { _Pragma("unroll") for (int n = 0; n < 2; ++n) _Pragma("unroll") for (int k = 0; k < 2; ++k) dst[n][k] = *(const PG8_LAS bf16x8*)(lds + PG8_SB(b, h) + boff + n * 2048 + k * 1024); } while (0)
; #define PG8_MMA(ai, bj, At, Bt) do { __builtin_amdgcn_s_setprio(1); _Pragma("unroll") for (int m = 0; m < 4; ++m) _Pragma("unroll") for (int n = 0; n < 2; ++n) _Pragma("unroll") for (int k = 0; k < 2; ++k) \
;         acc[ai][bj][m][n] = __builtin_amdgcn_mfma_f32_16x16x32_bf16(Bt[n][k], At[m][k], acc[ai][bj][m][n], 0, 0, 0); __builtin_amdgcn_s_setprio(0); } while (0)
; #define PG8_WAIT_V(n) asm volatile("s_waitcnt vmcnt(" #n ")" ::: "memory")
; #define PG8_WAIT_L(n) asm volatile("s_waitcnt lgkmcnt(" #n ")" ::: "memory")
; #define PG8_BAR __builtin_amdgcn_s_barrier()
; #define PG8_SCHED __builtin_amdgcn_sched_barrier(0)
; template <class Epi, class Sched>
; __device__ __forceinline__ void gemm_phase(int wid_s, PG8_LAS unsigned char* lds, const Gemm g, const Sched& S, const Epi& E) {
;     ...
;             PG8_WAIT_V(8); PG8_WAIT_L(0); PG8_BAR; PG8_MMA(1, 0, At, B0); PG8_MMA(1, 1, At, B1); PG8_BAR; PG8_SCHED;
;             PG8_LDB(B0, 1, 0); PG8_LDB(B1, 1, 1); PG8_SCHED; PG8_LDA(At, 1, 0); PG8_STAGE(PG8_SA(0, 1), a2 + hstepA, voffA);
;             PG8_WAIT_V(8); PG8_WAIT_L(0); PG8_BAR; PG8_MMA(0, 0, At, B0); PG8_MMA(0, 1, At, B1); PG8_BAR; PG8_SCHED;
	s_setprio 1
	s_waitcnt lgkmcnt(0)
	v_mfma_f32_16x16x32_bf16 v[60:63], v[156:159], v[208:211], v[60:63]
	v_mfma_f32_16x16x32_bf16 v[56:59], v[164:167], v[208:211], v[56:59]
	v_mfma_f32_16x16x32_bf16 v[44:47], v[156:159], v[216:219], v[44:47]
	v_mfma_f32_16x16x32_bf16 v[40:43], v[164:167], v[216:219], v[40:43]
	v_mfma_f32_16x16x32_bf16 v[28:31], v[156:159], v[224:227], v[28:31]
	v_mfma_f32_16x16x32_bf16 v[24:27], v[164:167], v[224:227], v[24:27]
	v_mfma_f32_16x16x32_bf16 v[12:15], v[156:159], v[232:235], v[12:15]
	v_mfma_f32_16x16x32_bf16 v[8:11], v[164:167], v[232:235], v[8:11]
	v_mfma_f32_16x16x32_bf16 v[60:63], v[160:163], v[212:215], v[60:63]
	v_mfma_f32_16x16x32_bf16 v[56:59], v[188:191], v[212:215], v[56:59]
	v_mfma_f32_16x16x32_bf16 v[44:47], v[160:163], v[220:223], v[44:47]
	v_mfma_f32_16x16x32_bf16 v[40:43], v[188:191], v[220:223], v[40:43]
	v_mfma_f32_16x16x32_bf16 v[28:31], v[160:163], v[228:231], v[28:31]
	v_mfma_f32_16x16x32_bf16 v[24:27], v[188:191], v[228:231], v[24:27]
	v_mfma_f32_16x16x32_bf16 v[12:15], v[160:163], v[236:239], v[12:15]
	v_mfma_f32_16x16x32_bf16 v[8:11], v[188:191], v[236:239], v[8:11]
	s_setprio 0
	s_setprio 1
	v_mfma_f32_16x16x32_bf16 v[52:55], v[192:195], v[208:211], v[52:55]
	v_mfma_f32_16x16x32_bf16 v[48:51], v[200:203], v[208:211], v[48:51]
	v_mfma_f32_16x16x32_bf16 v[36:39], v[192:195], v[216:219], v[36:39]
	v_mfma_f32_16x16x32_bf16 v[32:35], v[200:203], v[216:219], v[32:35]
	v_mfma_f32_16x16x32_bf16 v[20:23], v[192:195], v[224:227], v[20:23]
	v_mfma_f32_16x16x32_bf16 v[16:19], v[200:203], v[224:227], v[16:19]
	v_mfma_f32_16x16x32_bf16 v[4:7], v[192:195], v[232:235], v[4:7]
	v_mfma_f32_16x16x32_bf16 v[0:3], v[200:203], v[232:235], v[0:3]
	v_mfma_f32_16x16x32_bf16 v[52:55], v[196:199], v[212:215], v[52:55]
	v_mfma_f32_16x16x32_bf16 v[48:51], v[204:207], v[212:215], v[48:51]
	v_mfma_f32_16x16x32_bf16 v[36:39], v[196:199], v[220:223], v[36:39]
	v_mfma_f32_16x16x32_bf16 v[32:35], v[204:207], v[220:223], v[32:35]
	v_mfma_f32_16x16x32_bf16 v[20:23], v[196:199], v[228:231], v[20:23]
	v_mfma_f32_16x16x32_bf16 v[16:19], v[204:207], v[228:231], v[16:19]
	v_mfma_f32_16x16x32_bf16 v[4:7], v[196:199], v[236:239], v[4:7]
	v_mfma_f32_16x16x32_bf16 v[0:3], v[204:207], v[236:239], v[0:3]
	s_setprio 0
	s_barrier
	s_add_i32 s56, 0, 0x18000
	v_add_u32_e32 v140, s56, v142
	s_add_i32 s57, 0, 0x1c000
	ds_read_b128 v[156:159], v140
	ds_read_b128 v[160:163], v140 offset:1024
	ds_read_b128 v[164:167], v140 offset:2048
	ds_read_b128 v[188:191], v140 offset:3072
	v_add_u32_e32 v140, s57, v142
	ds_read_b128 v[192:195], v140
	ds_read_b128 v[196:199], v140 offset:1024
	ds_read_b128 v[200:203], v140 offset:2048
	ds_read_b128 v[204:207], v140 offset:3072
	s_add_u32 s28, s28, s6
	s_addc_u32 s29, s29, s7
	s_mov_b32 m0, s41
	v_lshl_add_u64 v[250:251], s[28:29], 0, v[128:129]
	ds_read_b128 v[208:211], v154 offset:32768
	ds_read_b128 v[212:215], v154 offset:33792
	ds_read_b128 v[216:219], v154 offset:34816
	ds_read_b128 v[220:223], v154 offset:35840
	ds_read_b128 v[224:227], v154 offset:36864
	ds_read_b128 v[228:231], v154 offset:37888
	ds_read_b128 v[232:235], v154 offset:38912
	ds_read_b128 v[236:239], v154 offset:39936
	global_load_lds_dwordx4 v[250:251], off
	v_lshl_add_u64 v[250:251], s[28:29], 0, v[130:131]
	s_mov_b32 m0, s42
	s_nop 0
	global_load_lds_dwordx4 v[250:251], off
	s_waitcnt vmcnt(8)
	s_barrier
	s_setprio 1
	s_waitcnt lgkmcnt(0)
	v_mfma_f32_16x16x32_bf16 v[120:123], v[156:159], v[208:211], v[120:123]
	v_mfma_f32_16x16x32_bf16 v[124:127], v[164:167], v[208:211], v[124:127]
	v_mfma_f32_16x16x32_bf16 v[108:111], v[156:159], v[216:219], v[108:111]
	v_mfma_f32_16x16x32_bf16 v[104:107], v[164:167], v[216:219], v[104:107]
	v_mfma_f32_16x16x32_bf16 v[92:95], v[156:159], v[224:227], v[92:95]
	v_mfma_f32_16x16x32_bf16 v[88:91], v[164:167], v[224:227], v[88:91]
	v_mfma_f32_16x16x32_bf16 v[76:79], v[156:159], v[232:235], v[76:79]
	v_mfma_f32_16x16x32_bf16 v[72:75], v[164:167], v[232:235], v[72:75]
	v_mfma_f32_16x16x32_bf16 v[120:123], v[160:163], v[212:215], v[120:123]
	v_mfma_f32_16x16x32_bf16 v[124:127], v[188:191], v[212:215], v[124:127]
	v_mfma_f32_16x16x32_bf16 v[108:111], v[160:163], v[220:223], v[108:111]
	v_mfma_f32_16x16x32_bf16 v[104:107], v[188:191], v[220:223], v[104:107]
	v_mfma_f32_16x16x32_bf16 v[92:95], v[160:163], v[228:231], v[92:95]
	v_mfma_f32_16x16x32_bf16 v[88:91], v[188:191], v[228:231], v[88:91]
	v_mfma_f32_16x16x32_bf16 v[76:79], v[160:163], v[236:239], v[76:79]
	v_mfma_f32_16x16x32_bf16 v[72:75], v[188:191], v[236:239], v[72:75]
	s_setprio 0
	s_setprio 1
	v_mfma_f32_16x16x32_bf16 v[116:119], v[192:195], v[208:211], v[116:119]
	v_mfma_f32_16x16x32_bf16 v[112:115], v[200:203], v[208:211], v[112:115]
	v_mfma_f32_16x16x32_bf16 v[100:103], v[192:195], v[216:219], v[100:103]
	v_mfma_f32_16x16x32_bf16 v[96:99], v[200:203], v[216:219], v[96:99]
	v_mfma_f32_16x16x32_bf16 v[84:87], v[192:195], v[224:227], v[84:87]
	v_mfma_f32_16x16x32_bf16 v[80:83], v[200:203], v[224:227], v[80:83]
	v_mfma_f32_16x16x32_bf16 v[68:71], v[192:195], v[232:235], v[68:71]
	v_mfma_f32_16x16x32_bf16 v[64:67], v[200:203], v[232:235], v[64:67]
	v_mfma_f32_16x16x32_bf16 v[116:119], v[196:199], v[212:215], v[116:119]
	v_mfma_f32_16x16x32_bf16 v[112:115], v[204:207], v[212:215], v[112:115]
	v_mfma_f32_16x16x32_bf16 v[100:103], v[196:199], v[220:223], v[100:103]
	v_mfma_f32_16x16x32_bf16 v[96:99], v[204:207], v[220:223], v[96:99]
	v_mfma_f32_16x16x32_bf16 v[84:87], v[196:199], v[228:231], v[84:87]
	v_mfma_f32_16x16x32_bf16 v[80:83], v[204:207], v[228:231], v[80:83]
	v_mfma_f32_16x16x32_bf16 v[68:71], v[196:199], v[236:239], v[68:71]
	v_mfma_f32_16x16x32_bf16 v[64:67], v[204:207], v[236:239], v[64:67]
	s_setprio 0
	s_barrier
; #define PG8_STAGE(bufoff, gbase, voff) do { _Pragma("unroll") for (int _i = 0; _i < 2; ++_i) \
;         __builtin_amdgcn_global_load_lds((const unsigned*)((const char*)(gbase) + (voff)[_i]), (PG8_LAS unsigned*)(lds + (bufoff) + ldsw + _i * 8192), 16, 0, 0); } while (0)
; #define PG8_LDA(dst, b, h) do { _Pragma("unroll") for (int m = 0; m < 4; ++m) _Pragma("unroll") for (int k = 0; k < 2; ++k) dst[m][k] = *(const PG8_LAS bf16x8*)(lds + PG8_SA(b, h) + aoff + m * 2048 + k * 1024); } while (0)
; #define PG8_MMA(ai, bj, At, Bt) do { __builtin_amdgcn_s_setprio(1); _Pragma("unroll") for (int m = 0; m < 4; ++m) _Pragma("unroll") for (int n = 0; n < 2; ++n) _Pragma("unroll") for (int k = 0; k < 2; ++k) \
;         acc[ai][bj][m][n] = __builtin_amdgcn_mfma_f32_16x16x32_bf16(Bt[n][k], At[m][k], acc[ai][bj][m][n], 0, 0, 0); __builtin_amdgcn_s_setprio(0); } while (0)
; #define PG8_WAIT_V(n) asm volatile("s_waitcnt vmcnt(" #n ")" ::: "memory")
; #define PG8_WAIT_L(n) asm volatile("s_waitcnt lgkmcnt(" #n ")" ::: "memory")
; #define PG8_BAR __builtin_amdgcn_s_barrier()
; #define PG8_SCHED __builtin_amdgcn_sched_barrier(0)
; template <class Epi, class Sched>
; __device__ __forceinline__ void gemm_phase(int wid_s, PG8_LAS unsigned char* lds, const Gemm g, const Sched& S, const Epi& E) {
;     ...
;             PG8_LDA(At, 1, 1); PG8_STAGE(PG8_SB(1, 0), b3, voffB); PG8_STAGE(PG8_SB(1, 1), b3 + hstepB, voffB); PG8_STAGE(PG8_SA(1, 0), a3, voffA);
;             PG8_WAIT_V(8); PG8_WAIT_L(0); PG8_BAR; PG8_MMA(1, 0, At, B0); PG8_MMA(1, 1, At, B1); PG8_BAR; PG8_SCHED;
;         }
	s_add_i32 s28, s56, s37
	v_lshl_add_u64 v[138:139], v[138:139], 0, s[96:97]
	s_mov_b32 m0, s28
	ds_read_b128 v[208:211], v154 offset:49152
	ds_read_b128 v[212:215], v154 offset:50176
	ds_read_b128 v[216:219], v154 offset:51200
	ds_read_b128 v[220:223], v154 offset:52224
	ds_read_b128 v[224:227], v154 offset:53248
	ds_read_b128 v[228:231], v154 offset:54272
	ds_read_b128 v[232:235], v154 offset:55296
	ds_read_b128 v[236:239], v154 offset:56320
	global_load_lds_dwordx4 v[138:139], off
	v_lshl_add_u64 v[138:139], v[240:241], 0, s[96:97]
	s_add_i32 m0, s28, 0x2000
	s_add_i32 s28, s57, s37
	global_load_lds_dwordx4 v[138:139], off
	v_lshl_add_u64 v[138:139], v[242:243], 0, s[96:97]
	s_mov_b32 m0, s28
	s_nop 0
	global_load_lds_dwordx4 v[138:139], off
	v_lshl_add_u64 v[138:139], v[244:245], 0, s[96:97]
	s_add_i32 m0, s28, 0x2000
	s_nop 0
	global_load_lds_dwordx4 v[138:139], off
	v_lshl_add_u64 v[138:139], v[246:247], 0, s[96:97]
	s_mov_b32 m0, s44
	s_nop 0
	global_load_lds_dwordx4 v[138:139], off
	v_lshl_add_u64 v[138:139], v[248:249], 0, s[96:97]
	s_mov_b32 m0, s45
	s_nop 0
	global_load_lds_dwordx4 v[138:139], off
	s_waitcnt vmcnt(8)
	s_barrier
	s_setprio 1
	s_waitcnt lgkmcnt(0)
	v_mfma_f32_16x16x32_bf16 v[60:63], v[156:159], v[208:211], v[60:63]
	v_mfma_f32_16x16x32_bf16 v[56:59], v[164:167], v[208:211], v[56:59]
	v_mfma_f32_16x16x32_bf16 v[44:47], v[156:159], v[216:219], v[44:47]
	v_mfma_f32_16x16x32_bf16 v[40:43], v[164:167], v[216:219], v[40:43]
	v_mfma_f32_16x16x32_bf16 v[28:31], v[156:159], v[224:227], v[28:31]
	v_mfma_f32_16x16x32_bf16 v[24:27], v[164:167], v[224:227], v[24:27]
	v_mfma_f32_16x16x32_bf16 v[12:15], v[156:159], v[232:235], v[12:15]
	v_mfma_f32_16x16x32_bf16 v[8:11], v[164:167], v[232:235], v[8:11]
	v_mfma_f32_16x16x32_bf16 v[60:63], v[160:163], v[212:215], v[60:63]
	v_mfma_f32_16x16x32_bf16 v[56:59], v[188:191], v[212:215], v[56:59]
	v_mfma_f32_16x16x32_bf16 v[44:47], v[160:163], v[220:223], v[44:47]
	v_mfma_f32_16x16x32_bf16 v[40:43], v[188:191], v[220:223], v[40:43]
	v_mfma_f32_16x16x32_bf16 v[28:31], v[160:163], v[228:231], v[28:31]
	v_mfma_f32_16x16x32_bf16 v[24:27], v[188:191], v[228:231], v[24:27]
	v_mfma_f32_16x16x32_bf16 v[12:15], v[160:163], v[236:239], v[12:15]
	v_mfma_f32_16x16x32_bf16 v[8:11], v[188:191], v[236:239], v[8:11]
	s_setprio 0
	s_setprio 1
	v_mfma_f32_16x16x32_bf16 v[52:55], v[192:195], v[208:211], v[52:55]
	v_mfma_f32_16x16x32_bf16 v[48:51], v[200:203], v[208:211], v[48:51]
	v_mfma_f32_16x16x32_bf16 v[36:39], v[192:195], v[216:219], v[36:39]
	v_mfma_f32_16x16x32_bf16 v[32:35], v[200:203], v[216:219], v[32:35]
	v_mfma_f32_16x16x32_bf16 v[20:23], v[192:195], v[224:227], v[20:23]
	v_mfma_f32_16x16x32_bf16 v[16:19], v[200:203], v[224:227], v[16:19]
	v_mfma_f32_16x16x32_bf16 v[4:7], v[192:195], v[232:235], v[4:7]
	v_mfma_f32_16x16x32_bf16 v[0:3], v[200:203], v[232:235], v[0:3]
	v_mfma_f32_16x16x32_bf16 v[52:55], v[196:199], v[212:215], v[52:55]
	v_mfma_f32_16x16x32_bf16 v[48:51], v[204:207], v[212:215], v[48:51]
	v_mfma_f32_16x16x32_bf16 v[36:39], v[196:199], v[220:223], v[36:39]
	v_mfma_f32_16x16x32_bf16 v[32:35], v[204:207], v[220:223], v[32:35]
	v_mfma_f32_16x16x32_bf16 v[20:23], v[196:199], v[228:231], v[20:23]
	v_mfma_f32_16x16x32_bf16 v[16:19], v[204:207], v[228:231], v[16:19]
	v_mfma_f32_16x16x32_bf16 v[4:7], v[196:199], v[236:239], v[4:7]
	v_mfma_f32_16x16x32_bf16 v[0:3], v[204:207], v[236:239], v[0:3]
	s_setprio 0
	s_barrier
	s_add_u32 s33, s33, 0x100
	s_addc_u32 s54, s54, 0
	s_add_u32 s26, s26, 0x100
	s_addc_u32 s27, s27, 0
	s_cmp_ge_i32 s55, s46
	s_mov_b32 s28, s55
	s_cbranch_scc0 .LBB0_2148
	v_readlane_b32 s54, v254, 52
	v_readlane_b32 s55, v254, 53
	v_readlane_b32 s92, v254, 54
	v_readlane_b32 s94, v254, 55

; #define PG8_STAGE(bufoff, gbase, voff) do { _Pragma("unroll") for (int _i = 0; _i < 2; ++_i) \
;         __builtin_amdgcn_global_load_lds((const unsigned*)((const char*)(gbase) + (voff)[_i]), (PG8_LAS unsigned*)(lds + (bufoff) + ldsw + _i * 8192), 16, 0, 0); } while (0)
; #define PG8_LDA(dst, b, h) do { _Pragma("unroll") for (int m = 0; m < 4; ++m) _Pragma("unroll") for (int k = 0; k < 2; ++k) dst[m][k] = *(const PG8_LAS bf16x8*)(lds + PG8_SA(b, h) + aoff + m * 2048 + k * 1024); } while (0)
; #define PG8_LDB(dst, b, h) do { _Pragma("unroll") for (int n = 0; n < 2; ++n) _Pragma("unroll") for (int k = 0; k < 2; ++k) dst[n][k] = *(const PG8_LAS bf16x8*)(lds + PG8_SB(b, h) + boff + n * 2048 + k * 1024); } while (0)
; #define PG8_MMA(ai, bj, At, Bt) do { __builtin_amdgcn_s_setprio(1); _Pragma("unroll") for (int m = 0; m < 4; ++m) _Pragma("unroll") for (int n = 0; n < 2; ++n) _Pragma("unroll") for (int k = 0; k < 2; ++k) \
;         acc[ai][bj][m][n] = __builtin_amdgcn_mfma_f32_16x16x32_bf16(Bt[n][k], At[m][k], acc[ai][bj][m][n], 0, 0, 0); __builtin_amdgcn_s_setprio(0); } while (0)
; #define PG8_WAIT_V(n) asm volatile("s_waitcnt vmcnt(" #n ")" ::: "memory")
; #define PG8_WAIT_L(n) asm volatile("s_waitcnt lgkmcnt(" #n ")" ::: "memory")
; #define PG8_BAR __builtin_amdgcn_s_barrier()
; #define PG8_SCHED __builtin_amdgcn_sched_barrier(0)
; template <class Epi, class Sched>
; __device__ __forceinline__ void gemm_phase(int wid_s, PG8_LAS unsigned char* lds, const Gemm g, const Sched& S, const Epi& E) {
;     ...
;         for (int t = 0; t < nt; t += 2) {
;             const bool last = (t == nt - 2);
;             const char* a1 = cA + (size_t)(t + 1) * kstep;
;             const char* a2 = last ? nA : cA + (size_t)(t + 2) * kstep; const char* b2 = last ? nB : cB + (size_t)(t + 2) * kstep;
;             const char* a3 = a2 + kstep; const char* b3 = b2 + kstep;
;             PG8_LDB(B0, 0, 0); PG8_LDB(B1, 0, 1); PG8_SCHED; PG8_LDA(At, 0, 0); PG8_STAGE(PG8_SA(1, 1), a1 + hstepA, voffA);
;             PG8_WAIT_V(8); PG8_WAIT_L(0); PG8_BAR; PG8_MMA(0, 0, At, B0); PG8_MMA(0, 1, At, B1); PG8_BAR; PG8_SCHED;
;             PG8_LDA(At, 0, 1); PG8_STAGE(PG8_SB(0, 0), b2, voffB); PG8_STAGE(PG8_SB(0, 1), b2 + hstepB, voffB); PG8_STAGE(PG8_SA(0, 0), a2, voffA);
;             PG8_WAIT_V(8); PG8_WAIT_L(0); PG8_BAR; PG8_MMA(1, 0, At, B0); PG8_MMA(1, 1, At, B1); PG8_BAR; PG8_SCHED;
.LBB0_2305:
	s_add_i32 s44, s34, 2
	s_add_u32 s45, s4, 0x80
	s_addc_u32 s35, s5, 0
	s_add_i32 s18, 0, 0x10000
	s_cmp_eq_u32 s95, s34
	s_cselect_b32 s35, s29, s35
	s_cselect_b32 s34, s28, s45
	v_add_u32_e32 v142, s18, v157
	s_cselect_b32 vcc_hi, s31, s51
	s_cselect_b32 vcc_lo, s30, s33
	s_add_i32 s45, 0, 0x14000
	ds_read_b128 v[138:141], v142
	ds_read_b128 v[160:163], v142 offset:1024
	ds_read_b128 v[164:167], v142 offset:2048
	ds_read_b128 v[188:191], v142 offset:3072
	v_add_u32_e32 v142, s45, v157
	ds_read_b128 v[192:195], v142
	ds_read_b128 v[196:199], v142 offset:1024
	ds_read_b128 v[200:203], v142 offset:2048
	ds_read_b128 v[204:207], v142 offset:3072
	v_lshl_add_u64 v[142:143], s[4:5], 0, v[136:137]
	s_add_i32 m0, s52, 0xc000
	ds_read_b128 v[208:211], v159
	ds_read_b128 v[212:215], v159 offset:1024
	ds_read_b128 v[216:219], v159 offset:2048
	ds_read_b128 v[220:223], v159 offset:3072
	ds_read_b128 v[224:227], v159 offset:4096
	ds_read_b128 v[228:231], v159 offset:5120
	ds_read_b128 v[232:235], v159 offset:6144
	ds_read_b128 v[236:239], v159 offset:7168
	global_load_lds_dwordx4 v[142:143], off
	v_lshl_add_u64 v[142:143], s[4:5], 0, v[134:135]
	s_add_i32 m0, s52, 0xe000
	s_nop 0
	global_load_lds_dwordx4 v[142:143], off
	s_waitcnt vmcnt(8)
	s_barrier
	s_setprio 1
	s_waitcnt lgkmcnt(0)
	v_mfma_f32_16x16x32_bf16 v[124:127], v[138:141], v[208:211], v[124:127]
	v_mfma_f32_16x16x32_bf16 v[120:123], v[164:167], v[208:211], v[120:123]
	v_mfma_f32_16x16x32_bf16 v[108:111], v[138:141], v[216:219], v[108:111]
	v_mfma_f32_16x16x32_bf16 v[104:107], v[164:167], v[216:219], v[104:107]
	v_mfma_f32_16x16x32_bf16 v[92:95], v[138:141], v[224:227], v[92:95]
	v_mfma_f32_16x16x32_bf16 v[88:91], v[164:167], v[224:227], v[88:91]
	v_mfma_f32_16x16x32_bf16 v[76:79], v[138:141], v[232:235], v[76:79]
	v_mfma_f32_16x16x32_bf16 v[72:75], v[164:167], v[232:235], v[72:75]
	v_mfma_f32_16x16x32_bf16 v[124:127], v[160:163], v[212:215], v[124:127]
	v_mfma_f32_16x16x32_bf16 v[120:123], v[188:191], v[212:215], v[120:123]
	v_mfma_f32_16x16x32_bf16 v[108:111], v[160:163], v[220:223], v[108:111]
	v_mfma_f32_16x16x32_bf16 v[104:107], v[188:191], v[220:223], v[104:107]
	v_mfma_f32_16x16x32_bf16 v[92:95], v[160:163], v[228:231], v[92:95]
	v_mfma_f32_16x16x32_bf16 v[88:91], v[188:191], v[228:231], v[88:91]
	v_mfma_f32_16x16x32_bf16 v[76:79], v[160:163], v[236:239], v[76:79]
	v_mfma_f32_16x16x32_bf16 v[72:75], v[188:191], v[236:239], v[72:75]
	s_setprio 0
	s_setprio 1
	v_mfma_f32_16x16x32_bf16 v[116:119], v[192:195], v[208:211], v[116:119]
	v_mfma_f32_16x16x32_bf16 v[112:115], v[200:203], v[208:211], v[112:115]
	v_mfma_f32_16x16x32_bf16 v[100:103], v[192:195], v[216:219], v[100:103]
	v_mfma_f32_16x16x32_bf16 v[96:99], v[200:203], v[216:219], v[96:99]
	v_mfma_f32_16x16x32_bf16 v[84:87], v[192:195], v[224:227], v[84:87]
	v_mfma_f32_16x16x32_bf16 v[80:83], v[200:203], v[224:227], v[80:83]
	v_mfma_f32_16x16x32_bf16 v[68:71], v[192:195], v[232:235], v[68:71]
	v_mfma_f32_16x16x32_bf16 v[64:67], v[200:203], v[232:235], v[64:67]
	v_mfma_f32_16x16x32_bf16 v[116:119], v[196:199], v[212:215], v[116:119]
	v_mfma_f32_16x16x32_bf16 v[112:115], v[204:207], v[212:215], v[112:115]
	v_mfma_f32_16x16x32_bf16 v[100:103], v[196:199], v[220:223], v[100:103]
	v_mfma_f32_16x16x32_bf16 v[96:99], v[204:207], v[220:223], v[96:99]
	v_mfma_f32_16x16x32_bf16 v[84:87], v[196:199], v[228:231], v[84:87]
	v_mfma_f32_16x16x32_bf16 v[80:83], v[204:207], v[228:231], v[80:83]
	v_mfma_f32_16x16x32_bf16 v[68:71], v[196:199], v[236:239], v[68:71]
	v_mfma_f32_16x16x32_bf16 v[64:67], v[204:207], v[236:239], v[64:67]
	s_setprio 0
	s_barrier
	s_add_i32 s18, s18, s47
	v_lshl_add_u64 v[142:143], vcc, 0, v[144:145]
	s_mov_b32 m0, s18
	ds_read_b128 v[208:211], v159 offset:16384
	ds_read_b128 v[212:215], v159 offset:17408
	ds_read_b128 v[216:219], v159 offset:18432
	ds_read_b128 v[220:223], v159 offset:19456
	ds_read_b128 v[224:227], v159 offset:20480
	ds_read_b128 v[228:231], v159 offset:21504
	ds_read_b128 v[232:235], v159 offset:22528
	ds_read_b128 v[236:239], v159 offset:23552
	global_load_lds_dwordx4 v[142:143], off
	s_add_i32 m0, s18, 0x2000
	v_lshl_add_u64 v[240:241], vcc, 0, v[132:133]
	s_add_u32 vcc_lo, vcc_lo, s12
	s_addc_u32 vcc_hi, vcc_hi, s13
	s_add_i32 s18, s45, s47
	global_load_lds_dwordx4 v[240:241], off
	v_lshl_add_u64 v[242:243], vcc, 0, v[144:145]
	s_mov_b32 m0, s18
	v_lshl_add_u64 v[244:245], vcc, 0, v[132:133]
	global_load_lds_dwordx4 v[242:243], off
	s_add_i32 m0, s18, 0x2000
	v_lshl_add_u64 v[246:247], s[34:35], 0, v[128:129]
	global_load_lds_dwordx4 v[244:245], off
	s_mov_b32 m0, s52
	v_lshl_add_u64 v[248:249], s[34:35], 0, v[130:131]
	global_load_lds_dwordx4 v[246:247], off
	s_mov_b32 m0, s53
	s_nop 0
	global_load_lds_dwordx4 v[248:249], off
	s_waitcnt vmcnt(8)
	s_barrier
; #define PG8_STAGE(bufoff, gbase, voff) do { _Pragma("unroll") for (int _i = 0; _i < 2; ++_i) \
;         __builtin_amdgcn_global_load_lds((const unsigned*)((const char*)(gbase) + (voff)[_i]), (PG8_LAS unsigned*)(lds + (bufoff) + ldsw + _i * 8192), 16, 0, 0); } while (0)
; #define PG8_LDA(dst, b, h) do { _Pragma("unroll") for (int m = 0; m < 4; ++m) _Pragma("unroll") for (int k = 0; k < 2; ++k) dst[m][k] = *(const PG8_LAS bf16x8*)(lds + PG8_SA(b, h) + aoff + m * 2048 + k * 1024); } while (0)
; #define PG8_LDB(dst, b, h) do { _Pragma("unroll") for (int n = 0; n < 2; ++n) _Pragma("unroll") for (int k = 0; k < 2; ++k) dst[n][k] = *(const PG8_LAS bf16x8*)(lds + PG8_SB(b, h) + boff + n * 2048 + k * 1024); } while (0)
; #define PG8_MMA(ai, bj, At, Bt) do { __builtin_amdgcn_s_setprio(1); _Pragma("unroll") for (int m = 0; m < 4; ++m) _Pragma("unroll") for (int n = 0; n < 2; ++n) _Pragma("unroll") for (int k = 0; k < 2; ++k) \
;         acc[ai][bj][m][n] = __builtin_amdgcn_mfma_f32_16x16x32_bf16(Bt[n][k], At[m][k], acc[ai][bj][m][n], 0, 0, 0); __builtin_amdgcn_s_setprio(0); } while (0)
; #define PG8_WAIT_V(n) asm volatile("s_waitcnt vmcnt(" #n ")" ::: "memory")
; #define PG8_WAIT_L(n) asm volatile("s_waitcnt lgkmcnt(" #n ")" ::: "memory")
; #define PG8_BAR __builtin_amdgcn_s_barrier()
; #define PG8_SCHED __builtin_amdgcn_sched_barrier(0)
; template <class Epi, class Sched>
; __device__ __forceinline__ void gemm_phase(int wid_s, PG8_LAS unsigned char* lds, const Gemm g, const Sched& S, const Epi& E) {
;     ...
;             PG8_WAIT_V(8); PG8_WAIT_L(0); PG8_BAR; PG8_MMA(1, 0, At, B0); PG8_MMA(1, 1, At, B1); PG8_BAR; PG8_SCHED;
;             PG8_LDB(B0, 1, 0); PG8_LDB(B1, 1, 1); PG8_SCHED; PG8_LDA(At, 1, 0); PG8_STAGE(PG8_SA(0, 1), a2 + hstepA, voffA);
;             PG8_WAIT_V(8); PG8_WAIT_L(0); PG8_BAR; PG8_MMA(0, 0, At, B0); PG8_MMA(0, 1, At, B1); PG8_BAR; PG8_SCHED;
	s_setprio 1
	s_waitcnt lgkmcnt(0)
	v_mfma_f32_16x16x32_bf16 v[60:63], v[138:141], v[208:211], v[60:63]
	v_mfma_f32_16x16x32_bf16 v[56:59], v[164:167], v[208:211], v[56:59]
	v_mfma_f32_16x16x32_bf16 v[44:47], v[138:141], v[216:219], v[44:47]
	v_mfma_f32_16x16x32_bf16 v[40:43], v[164:167], v[216:219], v[40:43]
	v_mfma_f32_16x16x32_bf16 v[28:31], v[138:141], v[224:227], v[28:31]
	v_mfma_f32_16x16x32_bf16 v[24:27], v[164:167], v[224:227], v[24:27]
	v_mfma_f32_16x16x32_bf16 v[12:15], v[138:141], v[232:235], v[12:15]
	v_mfma_f32_16x16x32_bf16 v[8:11], v[164:167], v[232:235], v[8:11]
	v_mfma_f32_16x16x32_bf16 v[60:63], v[160:163], v[212:215], v[60:63]
	v_mfma_f32_16x16x32_bf16 v[56:59], v[188:191], v[212:215], v[56:59]
	v_mfma_f32_16x16x32_bf16 v[44:47], v[160:163], v[220:223], v[44:47]
	v_mfma_f32_16x16x32_bf16 v[40:43], v[188:191], v[220:223], v[40:43]
	v_mfma_f32_16x16x32_bf16 v[28:31], v[160:163], v[228:231], v[28:31]
	v_mfma_f32_16x16x32_bf16 v[24:27], v[188:191], v[228:231], v[24:27]
	v_mfma_f32_16x16x32_bf16 v[12:15], v[160:163], v[236:239], v[12:15]
	v_mfma_f32_16x16x32_bf16 v[8:11], v[188:191], v[236:239], v[8:11]
	s_setprio 0
	s_setprio 1
	v_mfma_f32_16x16x32_bf16 v[52:55], v[192:195], v[208:211], v[52:55]
	v_mfma_f32_16x16x32_bf16 v[48:51], v[200:203], v[208:211], v[48:51]
	v_mfma_f32_16x16x32_bf16 v[36:39], v[192:195], v[216:219], v[36:39]
	v_mfma_f32_16x16x32_bf16 v[32:35], v[200:203], v[216:219], v[32:35]
	v_mfma_f32_16x16x32_bf16 v[20:23], v[192:195], v[224:227], v[20:23]
	v_mfma_f32_16x16x32_bf16 v[16:19], v[200:203], v[224:227], v[16:19]
	v_mfma_f32_16x16x32_bf16 v[4:7], v[192:195], v[232:235], v[4:7]
	v_mfma_f32_16x16x32_bf16 v[0:3], v[200:203], v[232:235], v[0:3]
	v_mfma_f32_16x16x32_bf16 v[52:55], v[196:199], v[212:215], v[52:55]
	v_mfma_f32_16x16x32_bf16 v[48:51], v[204:207], v[212:215], v[48:51]
	v_mfma_f32_16x16x32_bf16 v[36:39], v[196:199], v[220:223], v[36:39]
	v_mfma_f32_16x16x32_bf16 v[32:35], v[204:207], v[220:223], v[32:35]
	v_mfma_f32_16x16x32_bf16 v[20:23], v[196:199], v[228:231], v[20:23]
	v_mfma_f32_16x16x32_bf16 v[16:19], v[204:207], v[228:231], v[16:19]
	v_mfma_f32_16x16x32_bf16 v[4:7], v[196:199], v[236:239], v[4:7]
	v_mfma_f32_16x16x32_bf16 v[0:3], v[204:207], v[236:239], v[0:3]
	s_setprio 0
	s_barrier
	s_add_i32 s18, 0, 0x18000
	v_add_u32_e32 v185, s18, v157
	s_add_i32 s45, 0, 0x1c000
	ds_read_b128 v[138:141], v185
	ds_read_b128 v[160:163], v185 offset:1024
	ds_read_b128 v[164:167], v185 offset:2048
	ds_read_b128 v[188:191], v185 offset:3072
	v_add_u32_e32 v185, s45, v157
	ds_read_b128 v[192:195], v185
	ds_read_b128 v[196:199], v185 offset:1024
	ds_read_b128 v[200:203], v185 offset:2048
	ds_read_b128 v[204:207], v185 offset:3072
	s_add_u32 s34, s34, s10
	s_addc_u32 s35, s35, s11
	s_mov_b32 m0, s54
	v_lshl_add_u64 v[250:251], s[34:35], 0, v[128:129]
	ds_read_b128 v[208:211], v159 offset:32768
	ds_read_b128 v[212:215], v159 offset:33792
	ds_read_b128 v[216:219], v159 offset:34816
	ds_read_b128 v[220:223], v159 offset:35840
	ds_read_b128 v[224:227], v159 offset:36864
	ds_read_b128 v[228:231], v159 offset:37888
	ds_read_b128 v[232:235], v159 offset:38912
	ds_read_b128 v[236:239], v159 offset:39936
	global_load_lds_dwordx4 v[250:251], off
	v_lshl_add_u64 v[250:251], s[34:35], 0, v[130:131]
	s_mov_b32 m0, s55
	s_nop 0
	global_load_lds_dwordx4 v[250:251], off
	s_waitcnt vmcnt(8)
	s_barrier
	s_setprio 1
	s_waitcnt lgkmcnt(0)
	v_mfma_f32_16x16x32_bf16 v[124:127], v[138:141], v[208:211], v[124:127]
	v_mfma_f32_16x16x32_bf16 v[120:123], v[164:167], v[208:211], v[120:123]
	v_mfma_f32_16x16x32_bf16 v[108:111], v[138:141], v[216:219], v[108:111]
	v_mfma_f32_16x16x32_bf16 v[104:107], v[164:167], v[216:219], v[104:107]
	v_mfma_f32_16x16x32_bf16 v[92:95], v[138:141], v[224:227], v[92:95]
	v_mfma_f32_16x16x32_bf16 v[88:91], v[164:167], v[224:227], v[88:91]
	v_mfma_f32_16x16x32_bf16 v[76:79], v[138:141], v[232:235], v[76:79]
	v_mfma_f32_16x16x32_bf16 v[72:75], v[164:167], v[232:235], v[72:75]
	v_mfma_f32_16x16x32_bf16 v[124:127], v[160:163], v[212:215], v[124:127]
	v_mfma_f32_16x16x32_bf16 v[120:123], v[188:191], v[212:215], v[120:123]
	v_mfma_f32_16x16x32_bf16 v[108:111], v[160:163], v[220:223], v[108:111]
	v_mfma_f32_16x16x32_bf16 v[104:107], v[188:191], v[220:223], v[104:107]
	v_mfma_f32_16x16x32_bf16 v[92:95], v[160:163], v[228:231], v[92:95]
	v_mfma_f32_16x16x32_bf16 v[88:91], v[188:191], v[228:231], v[88:91]
	v_mfma_f32_16x16x32_bf16 v[76:79], v[160:163], v[236:239], v[76:79]
	v_mfma_f32_16x16x32_bf16 v[72:75], v[188:191], v[236:239], v[72:75]
	s_setprio 0
	s_setprio 1
	v_mfma_f32_16x16x32_bf16 v[116:119], v[192:195], v[208:211], v[116:119]
	v_mfma_f32_16x16x32_bf16 v[112:115], v[200:203], v[208:211], v[112:115]
	v_mfma_f32_16x16x32_bf16 v[100:103], v[192:195], v[216:219], v[100:103]
	v_mfma_f32_16x16x32_bf16 v[96:99], v[200:203], v[216:219], v[96:99]
	v_mfma_f32_16x16x32_bf16 v[84:87], v[192:195], v[224:227], v[84:87]
	v_mfma_f32_16x16x32_bf16 v[80:83], v[200:203], v[224:227], v[80:83]
	v_mfma_f32_16x16x32_bf16 v[68:71], v[192:195], v[232:235], v[68:71]
	v_mfma_f32_16x16x32_bf16 v[64:67], v[200:203], v[232:235], v[64:67]
	v_mfma_f32_16x16x32_bf16 v[116:119], v[196:199], v[212:215], v[116:119]
	v_mfma_f32_16x16x32_bf16 v[112:115], v[204:207], v[212:215], v[112:115]
	v_mfma_f32_16x16x32_bf16 v[100:103], v[196:199], v[220:223], v[100:103]
	v_mfma_f32_16x16x32_bf16 v[96:99], v[204:207], v[220:223], v[96:99]
	v_mfma_f32_16x16x32_bf16 v[84:87], v[196:199], v[228:231], v[84:87]
	v_mfma_f32_16x16x32_bf16 v[80:83], v[204:207], v[228:231], v[80:83]
	v_mfma_f32_16x16x32_bf16 v[68:71], v[196:199], v[236:239], v[68:71]
	v_mfma_f32_16x16x32_bf16 v[64:67], v[204:207], v[236:239], v[64:67]
	s_setprio 0
	s_barrier
; #define PG8_STAGE(bufoff, gbase, voff) do { _Pragma("unroll") for (int _i = 0; _i < 2; ++_i) \
;         __builtin_amdgcn_global_load_lds((const unsigned*)((const char*)(gbase) + (voff)[_i]), (PG8_LAS unsigned*)(lds + (bufoff) + ldsw + _i * 8192), 16, 0, 0); } while (0)
; #define PG8_LDA(dst, b, h) do { _Pragma("unroll") for (int m = 0; m < 4; ++m) _Pragma("unroll") for (int k = 0; k < 2; ++k) dst[m][k] = *(const PG8_LAS bf16x8*)(lds + PG8_SA(b, h) + aoff + m * 2048 + k * 1024); } while (0)
; #define PG8_MMA(ai, bj, At, Bt) do { __builtin_amdgcn_s_setprio(1); _Pragma("unroll") for (int m = 0; m < 4; ++m) _Pragma("unroll") for (int n = 0; n < 2; ++n) _Pragma("unroll") for (int k = 0; k < 2; ++k) \
;         acc[ai][bj][m][n] = __builtin_amdgcn_mfma_f32_16x16x32_bf16(Bt[n][k], At[m][k], acc[ai][bj][m][n], 0, 0, 0); __builtin_amdgcn_s_setprio(0); } while (0)
; #define PG8_WAIT_V(n) asm volatile("s_waitcnt vmcnt(" #n ")" ::: "memory")
; #define PG8_WAIT_L(n) asm volatile("s_waitcnt lgkmcnt(" #n ")" ::: "memory")
; #define PG8_BAR __builtin_amdgcn_s_barrier()
; #define PG8_SCHED __builtin_amdgcn_sched_barrier(0)
; template <class Epi, class Sched>
; __device__ __forceinline__ void gemm_phase(int wid_s, PG8_LAS unsigned char* lds, const Gemm g, const Sched& S, const Epi& E) {
;     ...
;         for (int t = 0; t < nt; t += 2) {
;             const bool last = (t == nt - 2);
;             const char* a1 = cA + (size_t)(t + 1) * kstep;
;             const char* a2 = last ? nA : cA + (size_t)(t + 2) * kstep; const char* b2 = last ? nB : cB + (size_t)(t + 2) * kstep;
;     ...
;             PG8_LDA(At, 1, 1); PG8_STAGE(PG8_SB(1, 0), b3, voffB); PG8_STAGE(PG8_SB(1, 1), b3 + hstepB, voffB); PG8_STAGE(PG8_SA(1, 0), a3, voffA);
;             PG8_WAIT_V(8); PG8_WAIT_L(0); PG8_BAR; PG8_MMA(1, 0, At, B0); PG8_MMA(1, 1, At, B1); PG8_BAR; PG8_SCHED;
	s_add_i32 s18, s18, s47
	v_lshl_add_u64 v[142:143], v[142:143], 0, s[96:97]
	s_mov_b32 m0, s18
	ds_read_b128 v[208:211], v159 offset:49152
	ds_read_b128 v[212:215], v159 offset:50176
	ds_read_b128 v[216:219], v159 offset:51200
	ds_read_b128 v[220:223], v159 offset:52224
	ds_read_b128 v[224:227], v159 offset:53248
	ds_read_b128 v[228:231], v159 offset:54272
	ds_read_b128 v[232:235], v159 offset:55296
	ds_read_b128 v[236:239], v159 offset:56320
	global_load_lds_dwordx4 v[142:143], off
	v_lshl_add_u64 v[142:143], v[240:241], 0, s[96:97]
	s_add_i32 m0, s18, 0x2000
	s_add_i32 s18, s45, s47
	global_load_lds_dwordx4 v[142:143], off
	v_lshl_add_u64 v[142:143], v[242:243], 0, s[96:97]
	s_mov_b32 m0, s18
	s_nop 0
	global_load_lds_dwordx4 v[142:143], off
	v_lshl_add_u64 v[142:143], v[244:245], 0, s[96:97]
	s_add_i32 m0, s18, 0x2000
	s_nop 0
	global_load_lds_dwordx4 v[142:143], off
	v_lshl_add_u64 v[142:143], v[246:247], 0, s[96:97]
	s_mov_b32 m0, s56
	s_nop 0
	global_load_lds_dwordx4 v[142:143], off
	v_lshl_add_u64 v[142:143], v[248:249], 0, s[96:97]
	s_mov_b32 m0, s57
	s_nop 0
	global_load_lds_dwordx4 v[142:143], off
	s_waitcnt vmcnt(8)
	s_barrier
	s_setprio 1
	s_waitcnt lgkmcnt(0)
	v_mfma_f32_16x16x32_bf16 v[60:63], v[138:141], v[208:211], v[60:63]
	v_mfma_f32_16x16x32_bf16 v[56:59], v[164:167], v[208:211], v[56:59]
	v_mfma_f32_16x16x32_bf16 v[44:47], v[138:141], v[216:219], v[44:47]
	v_mfma_f32_16x16x32_bf16 v[40:43], v[164:167], v[216:219], v[40:43]
	v_mfma_f32_16x16x32_bf16 v[28:31], v[138:141], v[224:227], v[28:31]
	v_mfma_f32_16x16x32_bf16 v[24:27], v[164:167], v[224:227], v[24:27]
	v_mfma_f32_16x16x32_bf16 v[12:15], v[138:141], v[232:235], v[12:15]
	v_mfma_f32_16x16x32_bf16 v[8:11], v[164:167], v[232:235], v[8:11]
	v_mfma_f32_16x16x32_bf16 v[60:63], v[160:163], v[212:215], v[60:63]
	v_mfma_f32_16x16x32_bf16 v[56:59], v[188:191], v[212:215], v[56:59]
	v_mfma_f32_16x16x32_bf16 v[44:47], v[160:163], v[220:223], v[44:47]
	v_mfma_f32_16x16x32_bf16 v[40:43], v[188:191], v[220:223], v[40:43]
	v_mfma_f32_16x16x32_bf16 v[28:31], v[160:163], v[228:231], v[28:31]
	v_mfma_f32_16x16x32_bf16 v[24:27], v[188:191], v[228:231], v[24:27]
	v_mfma_f32_16x16x32_bf16 v[12:15], v[160:163], v[236:239], v[12:15]
	v_mfma_f32_16x16x32_bf16 v[8:11], v[188:191], v[236:239], v[8:11]
	s_setprio 0
	s_setprio 1
	v_mfma_f32_16x16x32_bf16 v[52:55], v[192:195], v[208:211], v[52:55]
	v_mfma_f32_16x16x32_bf16 v[48:51], v[200:203], v[208:211], v[48:51]
	v_mfma_f32_16x16x32_bf16 v[36:39], v[192:195], v[216:219], v[36:39]
	v_mfma_f32_16x16x32_bf16 v[32:35], v[200:203], v[216:219], v[32:35]
	v_mfma_f32_16x16x32_bf16 v[20:23], v[192:195], v[224:227], v[20:23]
	v_mfma_f32_16x16x32_bf16 v[16:19], v[200:203], v[224:227], v[16:19]
	v_mfma_f32_16x16x32_bf16 v[4:7], v[192:195], v[232:235], v[4:7]
	v_mfma_f32_16x16x32_bf16 v[0:3], v[200:203], v[232:235], v[0:3]
	v_mfma_f32_16x16x32_bf16 v[52:55], v[196:199], v[212:215], v[52:55]
	v_mfma_f32_16x16x32_bf16 v[48:51], v[204:207], v[212:215], v[48:51]
	v_mfma_f32_16x16x32_bf16 v[36:39], v[196:199], v[220:223], v[36:39]
	v_mfma_f32_16x16x32_bf16 v[32:35], v[204:207], v[220:223], v[32:35]
	v_mfma_f32_16x16x32_bf16 v[20:23], v[196:199], v[228:231], v[20:23]
	v_mfma_f32_16x16x32_bf16 v[16:19], v[204:207], v[228:231], v[16:19]
	v_mfma_f32_16x16x32_bf16 v[4:7], v[196:199], v[236:239], v[4:7]
	v_mfma_f32_16x16x32_bf16 v[0:3], v[204:207], v[236:239], v[0:3]
	s_setprio 0
	s_barrier
	s_add_u32 s33, s33, 0x100
	s_addc_u32 s51, s51, 0
	s_add_u32 s4, s4, 0x100
	s_addc_u32 s5, s5, 0
	s_cmp_ge_i32 s44, s94
	s_mov_b32 s34, s44
	s_cbranch_scc0 .LBB0_2305
	s_movk_i32 s33, 0x300

; #define PG8_STAGE(bufoff, gbase, voff) do { _Pragma("unroll") for (int _i = 0; _i < 2; ++_i) \
;         __builtin_amdgcn_global_load_lds((const unsigned*)((const char*)(gbase) + (voff)[_i]), (PG8_LAS unsigned*)(lds + (bufoff) + ldsw + _i * 8192), 16, 0, 0); } while (0)
; #define PG8_LDA(dst, b, h) do { _Pragma("unroll") for (int m = 0; m < 4; ++m) _Pragma("unroll") for (int k = 0; k < 2; ++k) dst[m][k] = *(const PG8_LAS bf16x8*)(lds + PG8_SA(b, h) + aoff + m * 2048 + k * 1024); } while (0)
; #define PG8_LDB(dst, b, h) do { _Pragma("unroll") for (int n = 0; n < 2; ++n) _Pragma("unroll") for (int k = 0; k < 2; ++k) dst[n][k] = *(const PG8_LAS bf16x8*)(lds + PG8_SB(b, h) + boff + n * 2048 + k * 1024); } while (0)
; #define PG8_MMA(ai, bj, At, Bt) do { __builtin_amdgcn_s_setprio(1); _Pragma("unroll") for (int m = 0; m < 4; ++m) _Pragma("unroll") for (int n = 0; n < 2; ++n) _Pragma("unroll") for (int k = 0; k < 2; ++k) \
;         acc[ai][bj][m][n] = __builtin_amdgcn_mfma_f32_16x16x32_bf16(Bt[n][k], At[m][k], acc[ai][bj][m][n], 0, 0, 0); __builtin_amdgcn_s_setprio(0); } while (0)
; #define PG8_WAIT_V(n) asm volatile("s_waitcnt vmcnt(" #n ")" ::: "memory")
; #define PG8_WAIT_L(n) asm volatile("s_waitcnt lgkmcnt(" #n ")" ::: "memory")
; #define PG8_BAR __builtin_amdgcn_s_barrier()
; #define PG8_SCHED __builtin_amdgcn_sched_barrier(0)
; template <class Epi, class Sched>
; __device__ __forceinline__ void gemm_phase(int wid_s, PG8_LAS unsigned char* lds, const Gemm g, const Sched& S, const Epi& E) {
;     ...
;         for (int t = 0; t < nt; t += 2) {
;             const bool last = (t == nt - 2);
;             const char* a1 = cA + (size_t)(t + 1) * kstep;
;             const char* a2 = last ? nA : cA + (size_t)(t + 2) * kstep; const char* b2 = last ? nB : cB + (size_t)(t + 2) * kstep;
;             const char* a3 = a2 + kstep; const char* b3 = b2 + kstep;
;             PG8_LDB(B0, 0, 0); PG8_LDB(B1, 0, 1); PG8_SCHED; PG8_LDA(At, 0, 0); PG8_STAGE(PG8_SA(1, 1), a1 + hstepA, voffA);
;             PG8_WAIT_V(8); PG8_WAIT_L(0); PG8_BAR; PG8_MMA(0, 0, At, B0); PG8_MMA(0, 1, At, B1); PG8_BAR; PG8_SCHED;
;             PG8_LDA(At, 0, 1); PG8_STAGE(PG8_SB(0, 0), b2, voffB); PG8_STAGE(PG8_SB(0, 1), b2 + hstepB, voffB); PG8_STAGE(PG8_SA(0, 0), a2, voffA);
;             PG8_WAIT_V(8); PG8_WAIT_L(0); PG8_BAR; PG8_MMA(1, 0, At, B0); PG8_MMA(1, 1, At, B1); PG8_BAR; PG8_SCHED;
.LBB0_2473:
	s_add_i32 s51, s28, 2
	s_add_u32 s56, s26, 0x80
	s_addc_u32 s29, s27, 0
	s_add_i32 s92, 0, 0x10000
	s_cmp_eq_u32 s46, s28
	s_cselect_b32 s29, s5, s29
	s_cselect_b32 s28, s4, s56
	v_add_u32_e32 v138, s92, v154
	s_cselect_b32 s57, s25, s50
	s_cselect_b32 s56, s24, s33
	s_add_i32 s94, 0, 0x14000
	ds_read_b128 v[158:161], v138
	ds_read_b128 v[162:165], v138 offset:1024
	ds_read_b128 v[188:191], v138 offset:2048
	ds_read_b128 v[192:195], v138 offset:3072
	v_add_u32_e32 v138, s94, v154
	ds_read_b128 v[196:199], v138
	ds_read_b128 v[200:203], v138 offset:1024
	ds_read_b128 v[204:207], v138 offset:2048
	ds_read_b128 v[208:211], v138 offset:3072
	v_lshl_add_u64 v[138:139], s[26:27], 0, v[136:137]
	s_add_i32 m0, s36, 0xc000
	ds_read_b128 v[212:215], v156
	ds_read_b128 v[216:219], v156 offset:1024
	ds_read_b128 v[220:223], v156 offset:2048
	ds_read_b128 v[224:227], v156 offset:3072
	ds_read_b128 v[228:231], v156 offset:4096
	ds_read_b128 v[232:235], v156 offset:5120
	ds_read_b128 v[236:239], v156 offset:6144
	ds_read_b128 v[240:243], v156 offset:7168
	global_load_lds_dwordx4 v[138:139], off
	v_lshl_add_u64 v[138:139], s[26:27], 0, v[134:135]
	s_add_i32 m0, s36, 0xe000
	s_nop 0
	global_load_lds_dwordx4 v[138:139], off
	s_waitcnt vmcnt(8)
	s_barrier
	s_setprio 1
	s_waitcnt lgkmcnt(0)
	v_mfma_f32_16x16x32_bf16 v[124:127], v[158:161], v[212:215], v[124:127]
	v_mfma_f32_16x16x32_bf16 v[120:123], v[188:191], v[212:215], v[120:123]
	v_mfma_f32_16x16x32_bf16 v[108:111], v[158:161], v[220:223], v[108:111]
	v_mfma_f32_16x16x32_bf16 v[104:107], v[188:191], v[220:223], v[104:107]
	v_mfma_f32_16x16x32_bf16 v[92:95], v[158:161], v[228:231], v[92:95]
	v_mfma_f32_16x16x32_bf16 v[88:91], v[188:191], v[228:231], v[88:91]
	v_mfma_f32_16x16x32_bf16 v[76:79], v[158:161], v[236:239], v[76:79]
	v_mfma_f32_16x16x32_bf16 v[72:75], v[188:191], v[236:239], v[72:75]
	v_mfma_f32_16x16x32_bf16 v[124:127], v[162:165], v[216:219], v[124:127]
	v_mfma_f32_16x16x32_bf16 v[120:123], v[192:195], v[216:219], v[120:123]
	v_mfma_f32_16x16x32_bf16 v[108:111], v[162:165], v[224:227], v[108:111]
	v_mfma_f32_16x16x32_bf16 v[104:107], v[192:195], v[224:227], v[104:107]
	v_mfma_f32_16x16x32_bf16 v[92:95], v[162:165], v[232:235], v[92:95]
	v_mfma_f32_16x16x32_bf16 v[88:91], v[192:195], v[232:235], v[88:91]
	v_mfma_f32_16x16x32_bf16 v[76:79], v[162:165], v[240:243], v[76:79]
	v_mfma_f32_16x16x32_bf16 v[72:75], v[192:195], v[240:243], v[72:75]
	s_setprio 0
	s_setprio 1
	v_mfma_f32_16x16x32_bf16 v[116:119], v[196:199], v[212:215], v[116:119]
	v_mfma_f32_16x16x32_bf16 v[112:115], v[204:207], v[212:215], v[112:115]
	v_mfma_f32_16x16x32_bf16 v[100:103], v[196:199], v[220:223], v[100:103]
	v_mfma_f32_16x16x32_bf16 v[96:99], v[204:207], v[220:223], v[96:99]
	v_mfma_f32_16x16x32_bf16 v[84:87], v[196:199], v[228:231], v[84:87]
	v_mfma_f32_16x16x32_bf16 v[80:83], v[204:207], v[228:231], v[80:83]
	v_mfma_f32_16x16x32_bf16 v[68:71], v[196:199], v[236:239], v[68:71]
	v_mfma_f32_16x16x32_bf16 v[64:67], v[204:207], v[236:239], v[64:67]
	v_mfma_f32_16x16x32_bf16 v[116:119], v[200:203], v[216:219], v[116:119]
	v_mfma_f32_16x16x32_bf16 v[112:115], v[208:211], v[216:219], v[112:115]
	v_mfma_f32_16x16x32_bf16 v[100:103], v[200:203], v[224:227], v[100:103]
	v_mfma_f32_16x16x32_bf16 v[96:99], v[208:211], v[224:227], v[96:99]
	v_mfma_f32_16x16x32_bf16 v[84:87], v[200:203], v[232:235], v[84:87]
	v_mfma_f32_16x16x32_bf16 v[80:83], v[208:211], v[232:235], v[80:83]
	v_mfma_f32_16x16x32_bf16 v[68:71], v[200:203], v[240:243], v[68:71]
	v_mfma_f32_16x16x32_bf16 v[64:67], v[208:211], v[240:243], v[64:67]
	s_setprio 0
	s_barrier
	s_add_i32 s92, s92, s34
	v_lshl_add_u64 v[138:139], s[56:57], 0, v[144:145]
	s_mov_b32 m0, s92
	ds_read_b128 v[212:215], v156 offset:16384
	ds_read_b128 v[216:219], v156 offset:17408
	ds_read_b128 v[220:223], v156 offset:18432
	ds_read_b128 v[224:227], v156 offset:19456
	ds_read_b128 v[228:231], v156 offset:20480
	ds_read_b128 v[232:235], v156 offset:21504
	ds_read_b128 v[236:239], v156 offset:22528
	ds_read_b128 v[240:243], v156 offset:23552
	global_load_lds_dwordx4 v[138:139], off
	s_add_i32 m0, s92, 0x2000
	v_lshl_add_u64 v[142:143], s[56:57], 0, v[128:129]
	s_add_u32 s56, s56, s8
	s_addc_u32 s57, s57, s9
	s_add_i32 s92, s94, s34
	global_load_lds_dwordx4 v[142:143], off
	v_lshl_add_u64 v[166:167], s[56:57], 0, v[144:145]
	s_mov_b32 m0, s92
	v_lshl_add_u64 v[244:245], s[56:57], 0, v[128:129]
	global_load_lds_dwordx4 v[166:167], off
	s_add_i32 m0, s92, 0x2000
	v_lshl_add_u64 v[246:247], s[28:29], 0, v[132:133]
	global_load_lds_dwordx4 v[244:245], off
	s_mov_b32 m0, s36
	v_lshl_add_u64 v[248:249], s[28:29], 0, v[130:131]
	global_load_lds_dwordx4 v[246:247], off
	s_mov_b32 m0, s37
	s_nop 0
	global_load_lds_dwordx4 v[248:249], off
	s_waitcnt vmcnt(8)
	s_barrier
; #define PG8_STAGE(bufoff, gbase, voff) do { _Pragma("unroll") for (int _i = 0; _i < 2; ++_i) \
;         __builtin_amdgcn_global_load_lds((const unsigned*)((const char*)(gbase) + (voff)[_i]), (PG8_LAS unsigned*)(lds + (bufoff) + ldsw + _i * 8192), 16, 0, 0); } while (0)
; #define PG8_LDA(dst, b, h) do { _Pragma("unroll") for (int m = 0; m < 4; ++m) _Pragma("unroll") for (int k = 0; k < 2; ++k) dst[m][k] = *(const PG8_LAS bf16x8*)(lds + PG8_SA(b, h) + aoff + m * 2048 + k * 1024); } while (0)
; #define PG8_LDB(dst, b, h) do { _Pragma("unroll") for (int n = 0; n < 2; ++n) _Pragma("unroll") for (int k = 0; k < 2; ++k) dst[n][k] = *(const PG8_LAS bf16x8*)(lds + PG8_SB(b, h) + boff + n * 2048 + k * 1024); } while (0)
; #define PG8_MMA(ai, bj, At, Bt) do { __builtin_amdgcn_s_setprio(1); _Pragma("unroll") for (int m = 0; m < 4; ++m) _Pragma("unroll") for (int n = 0; n < 2; ++n) _Pragma("unroll") for (int k = 0; k < 2; ++k) \
;         acc[ai][bj][m][n] = __builtin_amdgcn_mfma_f32_16x16x32_bf16(Bt[n][k], At[m][k], acc[ai][bj][m][n], 0, 0, 0); __builtin_amdgcn_s_setprio(0); } while (0)
; #define PG8_WAIT_V(n) asm volatile("s_waitcnt vmcnt(" #n ")" ::: "memory")
; #define PG8_WAIT_L(n) asm volatile("s_waitcnt lgkmcnt(" #n ")" ::: "memory")
; #define PG8_BAR __builtin_amdgcn_s_barrier()
; #define PG8_SCHED __builtin_amdgcn_sched_barrier(0)
; template <class Epi, class Sched>
; __device__ __forceinline__ void gemm_phase(int wid_s, PG8_LAS unsigned char* lds, const Gemm g, const Sched& S, const Epi& E) {
;     ...
;             PG8_WAIT_V(8); PG8_WAIT_L(0); PG8_BAR; PG8_MMA(1, 0, At, B0); PG8_MMA(1, 1, At, B1); PG8_BAR; PG8_SCHED;
;             PG8_LDB(B0, 1, 0); PG8_LDB(B1, 1, 1); PG8_SCHED; PG8_LDA(At, 1, 0); PG8_STAGE(PG8_SA(0, 1), a2 + hstepA, voffA);
;             PG8_WAIT_V(8); PG8_WAIT_L(0); PG8_BAR; PG8_MMA(0, 0, At, B0); PG8_MMA(0, 1, At, B1); PG8_BAR; PG8_SCHED;
	s_setprio 1
	s_waitcnt lgkmcnt(0)
	v_mfma_f32_16x16x32_bf16 v[60:63], v[158:161], v[212:215], v[60:63]
	v_mfma_f32_16x16x32_bf16 v[56:59], v[188:191], v[212:215], v[56:59]
	v_mfma_f32_16x16x32_bf16 v[44:47], v[158:161], v[220:223], v[44:47]
	v_mfma_f32_16x16x32_bf16 v[40:43], v[188:191], v[220:223], v[40:43]
	v_mfma_f32_16x16x32_bf16 v[28:31], v[158:161], v[228:231], v[28:31]
	v_mfma_f32_16x16x32_bf16 v[24:27], v[188:191], v[228:231], v[24:27]
	v_mfma_f32_16x16x32_bf16 v[12:15], v[158:161], v[236:239], v[12:15]
	v_mfma_f32_16x16x32_bf16 v[8:11], v[188:191], v[236:239], v[8:11]
	v_mfma_f32_16x16x32_bf16 v[60:63], v[162:165], v[216:219], v[60:63]
	v_mfma_f32_16x16x32_bf16 v[56:59], v[192:195], v[216:219], v[56:59]
	v_mfma_f32_16x16x32_bf16 v[44:47], v[162:165], v[224:227], v[44:47]
	v_mfma_f32_16x16x32_bf16 v[40:43], v[192:195], v[224:227], v[40:43]
	v_mfma_f32_16x16x32_bf16 v[28:31], v[162:165], v[232:235], v[28:31]
	v_mfma_f32_16x16x32_bf16 v[24:27], v[192:195], v[232:235], v[24:27]
	v_mfma_f32_16x16x32_bf16 v[12:15], v[162:165], v[240:243], v[12:15]
	v_mfma_f32_16x16x32_bf16 v[8:11], v[192:195], v[240:243], v[8:11]
	s_setprio 0
	s_setprio 1
	v_mfma_f32_16x16x32_bf16 v[52:55], v[196:199], v[212:215], v[52:55]
	v_mfma_f32_16x16x32_bf16 v[48:51], v[204:207], v[212:215], v[48:51]
	v_mfma_f32_16x16x32_bf16 v[36:39], v[196:199], v[220:223], v[36:39]
	v_mfma_f32_16x16x32_bf16 v[32:35], v[204:207], v[220:223], v[32:35]
	v_mfma_f32_16x16x32_bf16 v[20:23], v[196:199], v[228:231], v[20:23]
	v_mfma_f32_16x16x32_bf16 v[16:19], v[204:207], v[228:231], v[16:19]
	v_mfma_f32_16x16x32_bf16 v[4:7], v[196:199], v[236:239], v[4:7]
	v_mfma_f32_16x16x32_bf16 v[0:3], v[204:207], v[236:239], v[0:3]
	v_mfma_f32_16x16x32_bf16 v[52:55], v[200:203], v[216:219], v[52:55]
	v_mfma_f32_16x16x32_bf16 v[48:51], v[208:211], v[216:219], v[48:51]
	v_mfma_f32_16x16x32_bf16 v[36:39], v[200:203], v[224:227], v[36:39]
	v_mfma_f32_16x16x32_bf16 v[32:35], v[208:211], v[224:227], v[32:35]
	v_mfma_f32_16x16x32_bf16 v[20:23], v[200:203], v[232:235], v[20:23]
	v_mfma_f32_16x16x32_bf16 v[16:19], v[208:211], v[232:235], v[16:19]
	v_mfma_f32_16x16x32_bf16 v[4:7], v[200:203], v[240:243], v[4:7]
	v_mfma_f32_16x16x32_bf16 v[0:3], v[208:211], v[240:243], v[0:3]
	s_setprio 0
	s_barrier
	s_add_i32 s56, 0, 0x18000
	v_add_u32_e32 v140, s56, v154
	s_add_i32 s57, 0, 0x1c000
	ds_read_b128 v[158:161], v140
	ds_read_b128 v[162:165], v140 offset:1024
	ds_read_b128 v[188:191], v140 offset:2048
	ds_read_b128 v[192:195], v140 offset:3072
	v_add_u32_e32 v140, s57, v154
	ds_read_b128 v[196:199], v140
	ds_read_b128 v[200:203], v140 offset:1024
	ds_read_b128 v[204:207], v140 offset:2048
	ds_read_b128 v[208:211], v140 offset:3072
	s_add_u32 s28, s28, s6
	s_addc_u32 s29, s29, s7
	s_mov_b32 m0, s39
	v_lshl_add_u64 v[250:251], s[28:29], 0, v[132:133]
	ds_read_b128 v[212:215], v156 offset:32768
	ds_read_b128 v[216:219], v156 offset:33792
	ds_read_b128 v[220:223], v156 offset:34816
	ds_read_b128 v[224:227], v156 offset:35840
	ds_read_b128 v[228:231], v156 offset:36864
	ds_read_b128 v[232:235], v156 offset:37888
	ds_read_b128 v[236:239], v156 offset:38912
	ds_read_b128 v[240:243], v156 offset:39936
	global_load_lds_dwordx4 v[250:251], off
	v_lshl_add_u64 v[250:251], s[28:29], 0, v[130:131]
	s_mov_b32 m0, s40
	s_nop 0
	global_load_lds_dwordx4 v[250:251], off
	s_waitcnt vmcnt(8)
	s_barrier
	s_setprio 1
	s_waitcnt lgkmcnt(0)
	v_mfma_f32_16x16x32_bf16 v[124:127], v[158:161], v[212:215], v[124:127]
	v_mfma_f32_16x16x32_bf16 v[120:123], v[188:191], v[212:215], v[120:123]
	v_mfma_f32_16x16x32_bf16 v[108:111], v[158:161], v[220:223], v[108:111]
	v_mfma_f32_16x16x32_bf16 v[104:107], v[188:191], v[220:223], v[104:107]
	v_mfma_f32_16x16x32_bf16 v[92:95], v[158:161], v[228:231], v[92:95]
	v_mfma_f32_16x16x32_bf16 v[88:91], v[188:191], v[228:231], v[88:91]
	v_mfma_f32_16x16x32_bf16 v[76:79], v[158:161], v[236:239], v[76:79]
	v_mfma_f32_16x16x32_bf16 v[72:75], v[188:191], v[236:239], v[72:75]
	v_mfma_f32_16x16x32_bf16 v[124:127], v[162:165], v[216:219], v[124:127]
	v_mfma_f32_16x16x32_bf16 v[120:123], v[192:195], v[216:219], v[120:123]
	v_mfma_f32_16x16x32_bf16 v[108:111], v[162:165], v[224:227], v[108:111]
	v_mfma_f32_16x16x32_bf16 v[104:107], v[192:195], v[224:227], v[104:107]
	v_mfma_f32_16x16x32_bf16 v[92:95], v[162:165], v[232:235], v[92:95]
	v_mfma_f32_16x16x32_bf16 v[88:91], v[192:195], v[232:235], v[88:91]
	v_mfma_f32_16x16x32_bf16 v[76:79], v[162:165], v[240:243], v[76:79]
	v_mfma_f32_16x16x32_bf16 v[72:75], v[192:195], v[240:243], v[72:75]
	s_setprio 0
	s_setprio 1
	v_mfma_f32_16x16x32_bf16 v[116:119], v[196:199], v[212:215], v[116:119]
	v_mfma_f32_16x16x32_bf16 v[112:115], v[204:207], v[212:215], v[112:115]
	v_mfma_f32_16x16x32_bf16 v[100:103], v[196:199], v[220:223], v[100:103]
	v_mfma_f32_16x16x32_bf16 v[96:99], v[204:207], v[220:223], v[96:99]
	v_mfma_f32_16x16x32_bf16 v[84:87], v[196:199], v[228:231], v[84:87]
	v_mfma_f32_16x16x32_bf16 v[80:83], v[204:207], v[228:231], v[80:83]
	v_mfma_f32_16x16x32_bf16 v[68:71], v[196:199], v[236:239], v[68:71]
	v_mfma_f32_16x16x32_bf16 v[64:67], v[204:207], v[236:239], v[64:67]
	v_mfma_f32_16x16x32_bf16 v[116:119], v[200:203], v[216:219], v[116:119]
	v_mfma_f32_16x16x32_bf16 v[112:115], v[208:211], v[216:219], v[112:115]
	v_mfma_f32_16x16x32_bf16 v[100:103], v[200:203], v[224:227], v[100:103]
	v_mfma_f32_16x16x32_bf16 v[96:99], v[208:211], v[224:227], v[96:99]
	v_mfma_f32_16x16x32_bf16 v[84:87], v[200:203], v[232:235], v[84:87]
	v_mfma_f32_16x16x32_bf16 v[80:83], v[208:211], v[232:235], v[80:83]
	v_mfma_f32_16x16x32_bf16 v[68:71], v[200:203], v[240:243], v[68:71]
	v_mfma_f32_16x16x32_bf16 v[64:67], v[208:211], v[240:243], v[64:67]
	s_setprio 0
	s_barrier
; #define PG8_STAGE(bufoff, gbase, voff) do { _Pragma("unroll") for (int _i = 0; _i < 2; ++_i) \
;         __builtin_amdgcn_global_load_lds((const unsigned*)((const char*)(gbase) + (voff)[_i]), (PG8_LAS unsigned*)(lds + (bufoff) + ldsw + _i * 8192), 16, 0, 0); } while (0)
; #define PG8_LDA(dst, b, h) do { _Pragma("unroll") for (int m = 0; m < 4; ++m) _Pragma("unroll") for (int k = 0; k < 2; ++k) dst[m][k] = *(const PG8_LAS bf16x8*)(lds + PG8_SA(b, h) + aoff + m * 2048 + k * 1024); } while (0)
; #define PG8_MMA(ai, bj, At, Bt) do { __builtin_amdgcn_s_setprio(1); _Pragma("unroll") for (int m = 0; m < 4; ++m) _Pragma("unroll") for (int n = 0; n < 2; ++n) _Pragma("unroll") for (int k = 0; k < 2; ++k) \
;         acc[ai][bj][m][n] = __builtin_amdgcn_mfma_f32_16x16x32_bf16(Bt[n][k], At[m][k], acc[ai][bj][m][n], 0, 0, 0); __builtin_amdgcn_s_setprio(0); } while (0)
; #define PG8_WAIT_V(n) asm volatile("s_waitcnt vmcnt(" #n ")" ::: "memory")
; #define PG8_WAIT_L(n) asm volatile("s_waitcnt lgkmcnt(" #n ")" ::: "memory")
; #define PG8_BAR __builtin_amdgcn_s_barrier()
; #define PG8_SCHED __builtin_amdgcn_sched_barrier(0)
; template <class Epi, class Sched>
; __device__ __forceinline__ void gemm_phase(int wid_s, PG8_LAS unsigned char* lds, const Gemm g, const Sched& S, const Epi& E) {
;     ...
;         for (int t = 0; t < nt; t += 2) {
;             const bool last = (t == nt - 2);
;             const char* a1 = cA + (size_t)(t + 1) * kstep;
;             const char* a2 = last ? nA : cA + (size_t)(t + 2) * kstep; const char* b2 = last ? nB : cB + (size_t)(t + 2) * kstep;
;     ...
;             PG8_LDA(At, 1, 1); PG8_STAGE(PG8_SB(1, 0), b3, voffB); PG8_STAGE(PG8_SB(1, 1), b3 + hstepB, voffB); PG8_STAGE(PG8_SA(1, 0), a3, voffA);
;             PG8_WAIT_V(8); PG8_WAIT_L(0); PG8_BAR; PG8_MMA(1, 0, At, B0); PG8_MMA(1, 1, At, B1); PG8_BAR; PG8_SCHED;
	s_add_i32 s28, s56, s34
	v_lshl_add_u64 v[138:139], v[138:139], 0, s[96:97]
	s_mov_b32 m0, s28
	ds_read_b128 v[212:215], v156 offset:49152
	ds_read_b128 v[216:219], v156 offset:50176
	ds_read_b128 v[220:223], v156 offset:51200
	ds_read_b128 v[224:227], v156 offset:52224
	ds_read_b128 v[228:231], v156 offset:53248
	ds_read_b128 v[232:235], v156 offset:54272
	ds_read_b128 v[236:239], v156 offset:55296
	ds_read_b128 v[240:243], v156 offset:56320
	global_load_lds_dwordx4 v[138:139], off
	v_lshl_add_u64 v[138:139], v[142:143], 0, s[96:97]
	s_add_i32 m0, s28, 0x2000
	s_add_i32 s28, s57, s34
	global_load_lds_dwordx4 v[138:139], off
	v_lshl_add_u64 v[138:139], v[166:167], 0, s[96:97]
	s_mov_b32 m0, s28
	s_nop 0
	global_load_lds_dwordx4 v[138:139], off
	v_lshl_add_u64 v[138:139], v[244:245], 0, s[96:97]
	s_add_i32 m0, s28, 0x2000
	s_nop 0
	global_load_lds_dwordx4 v[138:139], off
	v_lshl_add_u64 v[138:139], v[246:247], 0, s[96:97]
	s_mov_b32 m0, s41
	s_nop 0
	global_load_lds_dwordx4 v[138:139], off
	v_lshl_add_u64 v[138:139], v[248:249], 0, s[96:97]
	s_mov_b32 m0, s44
	s_nop 0
	global_load_lds_dwordx4 v[138:139], off
	s_waitcnt vmcnt(8)
	s_barrier
	s_setprio 1
	s_waitcnt lgkmcnt(0)
	v_mfma_f32_16x16x32_bf16 v[60:63], v[158:161], v[212:215], v[60:63]
	v_mfma_f32_16x16x32_bf16 v[56:59], v[188:191], v[212:215], v[56:59]
	v_mfma_f32_16x16x32_bf16 v[44:47], v[158:161], v[220:223], v[44:47]
	v_mfma_f32_16x16x32_bf16 v[40:43], v[188:191], v[220:223], v[40:43]
	v_mfma_f32_16x16x32_bf16 v[28:31], v[158:161], v[228:231], v[28:31]
	v_mfma_f32_16x16x32_bf16 v[24:27], v[188:191], v[228:231], v[24:27]
	v_mfma_f32_16x16x32_bf16 v[12:15], v[158:161], v[236:239], v[12:15]
	v_mfma_f32_16x16x32_bf16 v[8:11], v[188:191], v[236:239], v[8:11]
	v_mfma_f32_16x16x32_bf16 v[60:63], v[162:165], v[216:219], v[60:63]
	v_mfma_f32_16x16x32_bf16 v[56:59], v[192:195], v[216:219], v[56:59]
	v_mfma_f32_16x16x32_bf16 v[44:47], v[162:165], v[224:227], v[44:47]
	v_mfma_f32_16x16x32_bf16 v[40:43], v[192:195], v[224:227], v[40:43]
	v_mfma_f32_16x16x32_bf16 v[28:31], v[162:165], v[232:235], v[28:31]
	v_mfma_f32_16x16x32_bf16 v[24:27], v[192:195], v[232:235], v[24:27]
	v_mfma_f32_16x16x32_bf16 v[12:15], v[162:165], v[240:243], v[12:15]
	v_mfma_f32_16x16x32_bf16 v[8:11], v[192:195], v[240:243], v[8:11]
	s_setprio 0
	s_setprio 1
	v_mfma_f32_16x16x32_bf16 v[52:55], v[196:199], v[212:215], v[52:55]
	v_mfma_f32_16x16x32_bf16 v[48:51], v[204:207], v[212:215], v[48:51]
	v_mfma_f32_16x16x32_bf16 v[36:39], v[196:199], v[220:223], v[36:39]
	v_mfma_f32_16x16x32_bf16 v[32:35], v[204:207], v[220:223], v[32:35]
	v_mfma_f32_16x16x32_bf16 v[20:23], v[196:199], v[228:231], v[20:23]
	v_mfma_f32_16x16x32_bf16 v[16:19], v[204:207], v[228:231], v[16:19]
	v_mfma_f32_16x16x32_bf16 v[4:7], v[196:199], v[236:239], v[4:7]
	v_mfma_f32_16x16x32_bf16 v[0:3], v[204:207], v[236:239], v[0:3]
	v_mfma_f32_16x16x32_bf16 v[52:55], v[200:203], v[216:219], v[52:55]
	v_mfma_f32_16x16x32_bf16 v[48:51], v[208:211], v[216:219], v[48:51]
	v_mfma_f32_16x16x32_bf16 v[36:39], v[200:203], v[224:227], v[36:39]
	v_mfma_f32_16x16x32_bf16 v[32:35], v[208:211], v[224:227], v[32:35]
	v_mfma_f32_16x16x32_bf16 v[20:23], v[200:203], v[232:235], v[20:23]
	v_mfma_f32_16x16x32_bf16 v[16:19], v[208:211], v[232:235], v[16:19]
	v_mfma_f32_16x16x32_bf16 v[4:7], v[200:203], v[240:243], v[4:7]
	v_mfma_f32_16x16x32_bf16 v[0:3], v[208:211], v[240:243], v[0:3]
	s_setprio 0
	s_barrier
	s_add_u32 s33, s33, 0x100
	s_addc_u32 s50, s50, 0
	s_add_u32 s26, s26, 0x100
	s_addc_u32 s27, s27, 0
	s_cmp_ge_i32 s51, s45
	s_mov_b32 s28, s51
	s_cbranch_scc0 .LBB0_2473
	v_readlane_b32 s92, v254, 54
	v_readlane_b32 s94, v254, 55
	s_movk_i32 s51, 0x200
	s_movk_i32 s33, 0x300
	s_mov_b32 s50, s95

; #define PG8_STAGE(bufoff, gbase, voff) do { _Pragma("unroll") for (int _i = 0; _i < 2; ++_i) \
;         __builtin_amdgcn_global_load_lds((const unsigned*)((const char*)(gbase) + (voff)[_i]), (PG8_LAS unsigned*)(lds + (bufoff) + ldsw + _i * 8192), 16, 0, 0); } while (0)
; #define PG8_LDA(dst, b, h) do { _Pragma("unroll") for (int m = 0; m < 4; ++m) _Pragma("unroll") for (int k = 0; k < 2; ++k) dst[m][k] = *(const PG8_LAS bf16x8*)(lds + PG8_SA(b, h) + aoff + m * 2048 + k * 1024); } while (0)
; #define PG8_LDB(dst, b, h) do { _Pragma("unroll") for (int n = 0; n < 2; ++n) _Pragma("unroll") for (int k = 0; k < 2; ++k) dst[n][k] = *(const PG8_LAS bf16x8*)(lds + PG8_SB(b, h) + boff + n * 2048 + k * 1024); } while (0)
; #define PG8_MMA(ai, bj, At, Bt) do { __builtin_amdgcn_s_setprio(1); _Pragma("unroll") for (int m = 0; m < 4; ++m) _Pragma("unroll") for (int n = 0; n < 2; ++n) _Pragma("unroll") for (int k = 0; k < 2; ++k) \
;         acc[ai][bj][m][n] = __builtin_amdgcn_mfma_f32_16x16x32_bf16(Bt[n][k], At[m][k], acc[ai][bj][m][n], 0, 0, 0); __builtin_amdgcn_s_setprio(0); } while (0)
; #define PG8_WAIT_V(n) asm volatile("s_waitcnt vmcnt(" #n ")" ::: "memory")
; #define PG8_WAIT_L(n) asm volatile("s_waitcnt lgkmcnt(" #n ")" ::: "memory")
; #define PG8_BAR __builtin_amdgcn_s_barrier()
; #define PG8_SCHED __builtin_amdgcn_sched_barrier(0)
; template <class Epi, class Sched>
; __device__ __forceinline__ void gemm_phase(int wid_s, PG8_LAS unsigned char* lds, const Gemm g, const Sched& S, const Epi& E) {
;     ...
;         for (int t = 0; t < nt; t += 2) {
;             const bool last = (t == nt - 2);
;             const char* a1 = cA + (size_t)(t + 1) * kstep;
;             const char* a2 = last ? nA : cA + (size_t)(t + 2) * kstep; const char* b2 = last ? nB : cB + (size_t)(t + 2) * kstep;
;             const char* a3 = a2 + kstep; const char* b3 = b2 + kstep;
;             PG8_LDB(B0, 0, 0); PG8_LDB(B1, 0, 1); PG8_SCHED; PG8_LDA(At, 0, 0); PG8_STAGE(PG8_SA(1, 1), a1 + hstepA, voffA);
;             PG8_WAIT_V(8); PG8_WAIT_L(0); PG8_BAR; PG8_MMA(0, 0, At, B0); PG8_MMA(0, 1, At, B1); PG8_BAR; PG8_SCHED;
;             PG8_LDA(At, 0, 1); PG8_STAGE(PG8_SB(0, 0), b2, voffB); PG8_STAGE(PG8_SB(0, 1), b2 + hstepB, voffB); PG8_STAGE(PG8_SA(0, 0), a2, voffA);
;             PG8_WAIT_V(8); PG8_WAIT_L(0); PG8_BAR; PG8_MMA(1, 0, At, B0); PG8_MMA(1, 1, At, B1); PG8_BAR; PG8_SCHED;
.LBB0_2965:
	s_add_i32 s46, s6, 2
	s_add_u32 s47, s4, 0x80
	s_addc_u32 s7, s5, 0
	s_add_i32 s53, 0, 0x10000
	s_cmp_eq_u32 s23, s6
	s_cselect_b32 s7, s31, s7
	s_cselect_b32 s6, s30, s47
	v_add_u32_e32 v142, s53, v159
	s_cselect_b32 s51, s35, s49
	s_cselect_b32 s50, s34, s33
	s_add_i32 s47, 0, 0x14000
	ds_read_b128 v[138:141], v142
	ds_read_b128 v[162:165], v142 offset:1024
	ds_read_b128 v[186:189], v142 offset:2048
	ds_read_b128 v[190:193], v142 offset:3072
	v_add_u32_e32 v142, s47, v159
	ds_read_b128 v[194:197], v142
	ds_read_b128 v[198:201], v142 offset:1024
	ds_read_b128 v[202:205], v142 offset:2048
	ds_read_b128 v[206:209], v142 offset:3072
	v_lshl_add_u64 v[142:143], s[4:5], 0, v[136:137]
	s_add_i32 m0, s92, 0xc000
	ds_read_b128 v[210:213], v161
	ds_read_b128 v[214:217], v161 offset:1024
	ds_read_b128 v[218:221], v161 offset:2048
	ds_read_b128 v[222:225], v161 offset:3072
	ds_read_b128 v[226:229], v161 offset:4096
	ds_read_b128 v[230:233], v161 offset:5120
	ds_read_b128 v[234:237], v161 offset:6144
	ds_read_b128 v[238:241], v161 offset:7168
	global_load_lds_dwordx4 v[142:143], off
	v_lshl_add_u64 v[142:143], s[4:5], 0, v[134:135]
	s_add_i32 m0, s92, 0xe000
	s_nop 0
	global_load_lds_dwordx4 v[142:143], off
	s_waitcnt vmcnt(8)
	s_barrier
	s_setprio 1
	s_waitcnt lgkmcnt(0)
	v_mfma_f32_16x16x32_bf16 v[124:127], v[138:141], v[210:213], v[124:127]
	v_mfma_f32_16x16x32_bf16 v[120:123], v[186:189], v[210:213], v[120:123]
	v_mfma_f32_16x16x32_bf16 v[108:111], v[138:141], v[218:221], v[108:111]
	v_mfma_f32_16x16x32_bf16 v[104:107], v[186:189], v[218:221], v[104:107]
	v_mfma_f32_16x16x32_bf16 v[92:95], v[138:141], v[226:229], v[92:95]
	v_mfma_f32_16x16x32_bf16 v[88:91], v[186:189], v[226:229], v[88:91]
	v_mfma_f32_16x16x32_bf16 v[76:79], v[138:141], v[234:237], v[76:79]
	v_mfma_f32_16x16x32_bf16 v[72:75], v[186:189], v[234:237], v[72:75]
	v_mfma_f32_16x16x32_bf16 v[124:127], v[162:165], v[214:217], v[124:127]
	v_mfma_f32_16x16x32_bf16 v[120:123], v[190:193], v[214:217], v[120:123]
	v_mfma_f32_16x16x32_bf16 v[108:111], v[162:165], v[222:225], v[108:111]
	v_mfma_f32_16x16x32_bf16 v[104:107], v[190:193], v[222:225], v[104:107]
	v_mfma_f32_16x16x32_bf16 v[92:95], v[162:165], v[230:233], v[92:95]
	v_mfma_f32_16x16x32_bf16 v[88:91], v[190:193], v[230:233], v[88:91]
	v_mfma_f32_16x16x32_bf16 v[76:79], v[162:165], v[238:241], v[76:79]
	v_mfma_f32_16x16x32_bf16 v[72:75], v[190:193], v[238:241], v[72:75]
	s_setprio 0
	s_setprio 1
	v_mfma_f32_16x16x32_bf16 v[116:119], v[194:197], v[210:213], v[116:119]
	v_mfma_f32_16x16x32_bf16 v[112:115], v[202:205], v[210:213], v[112:115]
	v_mfma_f32_16x16x32_bf16 v[100:103], v[194:197], v[218:221], v[100:103]
	v_mfma_f32_16x16x32_bf16 v[96:99], v[202:205], v[218:221], v[96:99]
	v_mfma_f32_16x16x32_bf16 v[84:87], v[194:197], v[226:229], v[84:87]
	v_mfma_f32_16x16x32_bf16 v[80:83], v[202:205], v[226:229], v[80:83]
	v_mfma_f32_16x16x32_bf16 v[68:71], v[194:197], v[234:237], v[68:71]
	v_mfma_f32_16x16x32_bf16 v[64:67], v[202:205], v[234:237], v[64:67]
	v_mfma_f32_16x16x32_bf16 v[116:119], v[198:201], v[214:217], v[116:119]
	v_mfma_f32_16x16x32_bf16 v[112:115], v[206:209], v[214:217], v[112:115]
	v_mfma_f32_16x16x32_bf16 v[100:103], v[198:201], v[222:225], v[100:103]
	v_mfma_f32_16x16x32_bf16 v[96:99], v[206:209], v[222:225], v[96:99]
	v_mfma_f32_16x16x32_bf16 v[84:87], v[198:201], v[230:233], v[84:87]
	v_mfma_f32_16x16x32_bf16 v[80:83], v[206:209], v[230:233], v[80:83]
	v_mfma_f32_16x16x32_bf16 v[68:71], v[198:201], v[238:241], v[68:71]
	v_mfma_f32_16x16x32_bf16 v[64:67], v[206:209], v[238:241], v[64:67]
	s_setprio 0
	s_barrier
	s_add_i32 s53, s53, s55
	v_lshl_add_u64 v[142:143], s[50:51], 0, v[144:145]
	s_mov_b32 m0, s53
	ds_read_b128 v[210:213], v161 offset:16384
	ds_read_b128 v[214:217], v161 offset:17408
	ds_read_b128 v[218:221], v161 offset:18432
	ds_read_b128 v[222:225], v161 offset:19456
	ds_read_b128 v[226:229], v161 offset:20480
	ds_read_b128 v[230:233], v161 offset:21504
	ds_read_b128 v[234:237], v161 offset:22528
	ds_read_b128 v[238:241], v161 offset:23552
	global_load_lds_dwordx4 v[142:143], off
	s_add_i32 m0, s53, 0x2000
	v_lshl_add_u64 v[154:155], s[50:51], 0, v[132:133]
	s_add_u32 s50, s50, s14
	s_addc_u32 s51, s51, s15
	s_add_i32 s47, s47, s55
	global_load_lds_dwordx4 v[154:155], off
	v_lshl_add_u64 v[166:167], s[50:51], 0, v[144:145]
	s_mov_b32 m0, s47
	v_lshl_add_u64 v[242:243], s[50:51], 0, v[132:133]
	global_load_lds_dwordx4 v[166:167], off
	s_add_i32 m0, s47, 0x2000
	v_lshl_add_u64 v[244:245], s[6:7], 0, v[128:129]
	global_load_lds_dwordx4 v[242:243], off
	s_mov_b32 m0, s92
	v_lshl_add_u64 v[246:247], s[6:7], 0, v[130:131]
	global_load_lds_dwordx4 v[244:245], off
	s_mov_b32 m0, s94
	s_nop 0
	global_load_lds_dwordx4 v[246:247], off
	s_waitcnt vmcnt(8)
	s_barrier
; #define PG8_STAGE(bufoff, gbase, voff) do { _Pragma("unroll") for (int _i = 0; _i < 2; ++_i) \
;         __builtin_amdgcn_global_load_lds((const unsigned*)((const char*)(gbase) + (voff)[_i]), (PG8_LAS unsigned*)(lds + (bufoff) + ldsw + _i * 8192), 16, 0, 0); } while (0)
; #define PG8_LDA(dst, b, h) do { _Pragma("unroll") for (int m = 0; m < 4; ++m) _Pragma("unroll") for (int k = 0; k < 2; ++k) dst[m][k] = *(const PG8_LAS bf16x8*)(lds + PG8_SA(b, h) + aoff + m * 2048 + k * 1024); } while (0)
; #define PG8_LDB(dst, b, h) do { _Pragma("unroll") for (int n = 0; n < 2; ++n) _Pragma("unroll") for (int k = 0; k < 2; ++k) dst[n][k] = *(const PG8_LAS bf16x8*)(lds + PG8_SB(b, h) + boff + n * 2048 + k * 1024); } while (0)
; #define PG8_MMA(ai, bj, At, Bt) do { __builtin_amdgcn_s_setprio(1); _Pragma("unroll") for (int m = 0; m < 4; ++m) _Pragma("unroll") for (int n = 0; n < 2; ++n) _Pragma("unroll") for (int k = 0; k < 2; ++k) \
;         acc[ai][bj][m][n] = __builtin_amdgcn_mfma_f32_16x16x32_bf16(Bt[n][k], At[m][k], acc[ai][bj][m][n], 0, 0, 0); __builtin_amdgcn_s_setprio(0); } while (0)
; #define PG8_WAIT_V(n) asm volatile("s_waitcnt vmcnt(" #n ")" ::: "memory")
; #define PG8_WAIT_L(n) asm volatile("s_waitcnt lgkmcnt(" #n ")" ::: "memory")
; #define PG8_BAR __builtin_amdgcn_s_barrier()
; #define PG8_SCHED __builtin_amdgcn_sched_barrier(0)
; template <class Epi, class Sched>
; __device__ __forceinline__ void gemm_phase(int wid_s, PG8_LAS unsigned char* lds, const Gemm g, const Sched& S, const Epi& E) {
;     ...
;             PG8_WAIT_V(8); PG8_WAIT_L(0); PG8_BAR; PG8_MMA(1, 0, At, B0); PG8_MMA(1, 1, At, B1); PG8_BAR; PG8_SCHED;
;             PG8_LDB(B0, 1, 0); PG8_LDB(B1, 1, 1); PG8_SCHED; PG8_LDA(At, 1, 0); PG8_STAGE(PG8_SA(0, 1), a2 + hstepA, voffA);
;             PG8_WAIT_V(8); PG8_WAIT_L(0); PG8_BAR; PG8_MMA(0, 0, At, B0); PG8_MMA(0, 1, At, B1); PG8_BAR; PG8_SCHED;
	s_setprio 1
	s_waitcnt lgkmcnt(0)
	v_mfma_f32_16x16x32_bf16 v[60:63], v[138:141], v[210:213], v[60:63]
	v_mfma_f32_16x16x32_bf16 v[56:59], v[186:189], v[210:213], v[56:59]
	v_mfma_f32_16x16x32_bf16 v[44:47], v[138:141], v[218:221], v[44:47]
	v_mfma_f32_16x16x32_bf16 v[40:43], v[186:189], v[218:221], v[40:43]
	v_mfma_f32_16x16x32_bf16 v[28:31], v[138:141], v[226:229], v[28:31]
	v_mfma_f32_16x16x32_bf16 v[24:27], v[186:189], v[226:229], v[24:27]
	v_mfma_f32_16x16x32_bf16 v[12:15], v[138:141], v[234:237], v[12:15]
	v_mfma_f32_16x16x32_bf16 v[8:11], v[186:189], v[234:237], v[8:11]
	v_mfma_f32_16x16x32_bf16 v[60:63], v[162:165], v[214:217], v[60:63]
	v_mfma_f32_16x16x32_bf16 v[56:59], v[190:193], v[214:217], v[56:59]
	v_mfma_f32_16x16x32_bf16 v[44:47], v[162:165], v[222:225], v[44:47]
	v_mfma_f32_16x16x32_bf16 v[40:43], v[190:193], v[222:225], v[40:43]
	v_mfma_f32_16x16x32_bf16 v[28:31], v[162:165], v[230:233], v[28:31]
	v_mfma_f32_16x16x32_bf16 v[24:27], v[190:193], v[230:233], v[24:27]
	v_mfma_f32_16x16x32_bf16 v[12:15], v[162:165], v[238:241], v[12:15]
	v_mfma_f32_16x16x32_bf16 v[8:11], v[190:193], v[238:241], v[8:11]
	s_setprio 0
	s_setprio 1
	v_mfma_f32_16x16x32_bf16 v[52:55], v[194:197], v[210:213], v[52:55]
	v_mfma_f32_16x16x32_bf16 v[48:51], v[202:205], v[210:213], v[48:51]
	v_mfma_f32_16x16x32_bf16 v[36:39], v[194:197], v[218:221], v[36:39]
	v_mfma_f32_16x16x32_bf16 v[32:35], v[202:205], v[218:221], v[32:35]
	v_mfma_f32_16x16x32_bf16 v[20:23], v[194:197], v[226:229], v[20:23]
	v_mfma_f32_16x16x32_bf16 v[16:19], v[202:205], v[226:229], v[16:19]
	v_mfma_f32_16x16x32_bf16 v[4:7], v[194:197], v[234:237], v[4:7]
	v_mfma_f32_16x16x32_bf16 v[0:3], v[202:205], v[234:237], v[0:3]
	v_mfma_f32_16x16x32_bf16 v[52:55], v[198:201], v[214:217], v[52:55]
	v_mfma_f32_16x16x32_bf16 v[48:51], v[206:209], v[214:217], v[48:51]
	v_mfma_f32_16x16x32_bf16 v[36:39], v[198:201], v[222:225], v[36:39]
	v_mfma_f32_16x16x32_bf16 v[32:35], v[206:209], v[222:225], v[32:35]
	v_mfma_f32_16x16x32_bf16 v[20:23], v[198:201], v[230:233], v[20:23]
	v_mfma_f32_16x16x32_bf16 v[16:19], v[206:209], v[230:233], v[16:19]
	v_mfma_f32_16x16x32_bf16 v[4:7], v[198:201], v[238:241], v[4:7]
	v_mfma_f32_16x16x32_bf16 v[0:3], v[206:209], v[238:241], v[0:3]
	s_setprio 0
	s_barrier
	s_add_i32 s47, 0, 0x18000
	v_add_u32_e32 v185, s47, v159
	s_add_i32 s50, 0, 0x1c000
	ds_read_b128 v[138:141], v185
	ds_read_b128 v[162:165], v185 offset:1024
	ds_read_b128 v[186:189], v185 offset:2048
	ds_read_b128 v[190:193], v185 offset:3072
	v_add_u32_e32 v185, s50, v159
	ds_read_b128 v[194:197], v185
	ds_read_b128 v[198:201], v185 offset:1024
	ds_read_b128 v[202:205], v185 offset:2048
	ds_read_b128 v[206:209], v185 offset:3072
	s_add_u32 s6, s6, s12
	s_addc_u32 s7, s7, s13
	s_mov_b32 m0, s95
	v_lshl_add_u64 v[248:249], s[6:7], 0, v[128:129]
	ds_read_b128 v[210:213], v161 offset:32768
	ds_read_b128 v[214:217], v161 offset:33792
	ds_read_b128 v[218:221], v161 offset:34816
	ds_read_b128 v[222:225], v161 offset:35840
	ds_read_b128 v[226:229], v161 offset:36864
	ds_read_b128 v[230:233], v161 offset:37888
	ds_read_b128 v[234:237], v161 offset:38912
	ds_read_b128 v[238:241], v161 offset:39936
	global_load_lds_dwordx4 v[248:249], off
	v_lshl_add_u64 v[248:249], s[6:7], 0, v[130:131]
	s_mov_b32 m0, s8
	s_nop 0
	global_load_lds_dwordx4 v[248:249], off
	s_waitcnt vmcnt(8)
	s_barrier
	s_setprio 1
	s_waitcnt lgkmcnt(0)
	v_mfma_f32_16x16x32_bf16 v[124:127], v[138:141], v[210:213], v[124:127]
	v_mfma_f32_16x16x32_bf16 v[120:123], v[186:189], v[210:213], v[120:123]
	v_mfma_f32_16x16x32_bf16 v[108:111], v[138:141], v[218:221], v[108:111]
	v_mfma_f32_16x16x32_bf16 v[104:107], v[186:189], v[218:221], v[104:107]
	v_mfma_f32_16x16x32_bf16 v[92:95], v[138:141], v[226:229], v[92:95]
	v_mfma_f32_16x16x32_bf16 v[88:91], v[186:189], v[226:229], v[88:91]
	v_mfma_f32_16x16x32_bf16 v[76:79], v[138:141], v[234:237], v[76:79]
	v_mfma_f32_16x16x32_bf16 v[72:75], v[186:189], v[234:237], v[72:75]
	v_mfma_f32_16x16x32_bf16 v[124:127], v[162:165], v[214:217], v[124:127]
	v_mfma_f32_16x16x32_bf16 v[120:123], v[190:193], v[214:217], v[120:123]
	v_mfma_f32_16x16x32_bf16 v[108:111], v[162:165], v[222:225], v[108:111]
	v_mfma_f32_16x16x32_bf16 v[104:107], v[190:193], v[222:225], v[104:107]
	v_mfma_f32_16x16x32_bf16 v[92:95], v[162:165], v[230:233], v[92:95]
	v_mfma_f32_16x16x32_bf16 v[88:91], v[190:193], v[230:233], v[88:91]
	v_mfma_f32_16x16x32_bf16 v[76:79], v[162:165], v[238:241], v[76:79]
	v_mfma_f32_16x16x32_bf16 v[72:75], v[190:193], v[238:241], v[72:75]
	s_setprio 0
	s_setprio 1
	v_mfma_f32_16x16x32_bf16 v[116:119], v[194:197], v[210:213], v[116:119]
	v_mfma_f32_16x16x32_bf16 v[112:115], v[202:205], v[210:213], v[112:115]
	v_mfma_f32_16x16x32_bf16 v[100:103], v[194:197], v[218:221], v[100:103]
	v_mfma_f32_16x16x32_bf16 v[96:99], v[202:205], v[218:221], v[96:99]
	v_mfma_f32_16x16x32_bf16 v[84:87], v[194:197], v[226:229], v[84:87]
	v_mfma_f32_16x16x32_bf16 v[80:83], v[202:205], v[226:229], v[80:83]
	v_mfma_f32_16x16x32_bf16 v[68:71], v[194:197], v[234:237], v[68:71]
	v_mfma_f32_16x16x32_bf16 v[64:67], v[202:205], v[234:237], v[64:67]
	v_mfma_f32_16x16x32_bf16 v[116:119], v[198:201], v[214:217], v[116:119]
	v_mfma_f32_16x16x32_bf16 v[112:115], v[206:209], v[214:217], v[112:115]
	v_mfma_f32_16x16x32_bf16 v[100:103], v[198:201], v[222:225], v[100:103]
	v_mfma_f32_16x16x32_bf16 v[96:99], v[206:209], v[222:225], v[96:99]
	v_mfma_f32_16x16x32_bf16 v[84:87], v[198:201], v[230:233], v[84:87]
	v_mfma_f32_16x16x32_bf16 v[80:83], v[206:209], v[230:233], v[80:83]
	v_mfma_f32_16x16x32_bf16 v[68:71], v[198:201], v[238:241], v[68:71]
	v_mfma_f32_16x16x32_bf16 v[64:67], v[206:209], v[238:241], v[64:67]
	s_setprio 0
	s_barrier
; #define PG8_STAGE(bufoff, gbase, voff) do { _Pragma("unroll") for (int _i = 0; _i < 2; ++_i) \
;         __builtin_amdgcn_global_load_lds((const unsigned*)((const char*)(gbase) + (voff)[_i]), (PG8_LAS unsigned*)(lds + (bufoff) + ldsw + _i * 8192), 16, 0, 0); } while (0)
; #define PG8_LDA(dst, b, h) do { _Pragma("unroll") for (int m = 0; m < 4; ++m) _Pragma("unroll") for (int k = 0; k < 2; ++k) dst[m][k] = *(const PG8_LAS bf16x8*)(lds + PG8_SA(b, h) + aoff + m * 2048 + k * 1024); } while (0)
; #define PG8_MMA(ai, bj, At, Bt) do { __builtin_amdgcn_s_setprio(1); _Pragma("unroll") for (int m = 0; m < 4; ++m) _Pragma("unroll") for (int n = 0; n < 2; ++n) _Pragma("unroll") for (int k = 0; k < 2; ++k) \
;         acc[ai][bj][m][n] = __builtin_amdgcn_mfma_f32_16x16x32_bf16(Bt[n][k], At[m][k], acc[ai][bj][m][n], 0, 0, 0); __builtin_amdgcn_s_setprio(0); } while (0)
; #define PG8_WAIT_V(n) asm volatile("s_waitcnt vmcnt(" #n ")" ::: "memory")
; #define PG8_WAIT_L(n) asm volatile("s_waitcnt lgkmcnt(" #n ")" ::: "memory")
; #define PG8_BAR __builtin_amdgcn_s_barrier()
; #define PG8_SCHED __builtin_amdgcn_sched_barrier(0)
; template <class Epi, class Sched>
; __device__ __forceinline__ void gemm_phase(int wid_s, PG8_LAS unsigned char* lds, const Gemm g, const Sched& S, const Epi& E) {
;     ...
;         for (int t = 0; t < nt; t += 2) {
;             const bool last = (t == nt - 2);
;             const char* a1 = cA + (size_t)(t + 1) * kstep;
;             const char* a2 = last ? nA : cA + (size_t)(t + 2) * kstep; const char* b2 = last ? nB : cB + (size_t)(t + 2) * kstep;
;     ...
;             PG8_LDA(At, 1, 1); PG8_STAGE(PG8_SB(1, 0), b3, voffB); PG8_STAGE(PG8_SB(1, 1), b3 + hstepB, voffB); PG8_STAGE(PG8_SA(1, 0), a3, voffA);
;             PG8_WAIT_V(8); PG8_WAIT_L(0); PG8_BAR; PG8_MMA(1, 0, At, B0); PG8_MMA(1, 1, At, B1); PG8_BAR; PG8_SCHED;
	s_add_i32 s6, s47, s55
	v_lshl_add_u64 v[142:143], v[142:143], 0, s[96:97]
	s_mov_b32 m0, s6
	ds_read_b128 v[210:213], v161 offset:49152
	ds_read_b128 v[214:217], v161 offset:50176
	ds_read_b128 v[218:221], v161 offset:51200
	ds_read_b128 v[222:225], v161 offset:52224
	ds_read_b128 v[226:229], v161 offset:53248
	ds_read_b128 v[230:233], v161 offset:54272
	ds_read_b128 v[234:237], v161 offset:55296
	ds_read_b128 v[238:241], v161 offset:56320
	global_load_lds_dwordx4 v[142:143], off
	v_lshl_add_u64 v[142:143], v[154:155], 0, s[96:97]
	s_add_i32 m0, s6, 0x2000
	s_add_i32 s6, s50, s55
	global_load_lds_dwordx4 v[142:143], off
	v_lshl_add_u64 v[142:143], v[166:167], 0, s[96:97]
	s_mov_b32 m0, s6
	s_nop 0
	global_load_lds_dwordx4 v[142:143], off
	v_lshl_add_u64 v[142:143], v[242:243], 0, s[96:97]
	s_add_i32 m0, s6, 0x2000
	s_nop 0
	global_load_lds_dwordx4 v[142:143], off
	v_lshl_add_u64 v[142:143], v[244:245], 0, s[96:97]
	s_mov_b32 m0, s9
	s_nop 0
	global_load_lds_dwordx4 v[142:143], off
	v_lshl_add_u64 v[142:143], v[246:247], 0, s[96:97]
	s_mov_b32 m0, s0
	s_nop 0
	global_load_lds_dwordx4 v[142:143], off
	s_waitcnt vmcnt(8)
	s_barrier
	s_setprio 1
	s_waitcnt lgkmcnt(0)
	v_mfma_f32_16x16x32_bf16 v[60:63], v[138:141], v[210:213], v[60:63]
	v_mfma_f32_16x16x32_bf16 v[56:59], v[186:189], v[210:213], v[56:59]
	v_mfma_f32_16x16x32_bf16 v[44:47], v[138:141], v[218:221], v[44:47]
	v_mfma_f32_16x16x32_bf16 v[40:43], v[186:189], v[218:221], v[40:43]
	v_mfma_f32_16x16x32_bf16 v[28:31], v[138:141], v[226:229], v[28:31]
	v_mfma_f32_16x16x32_bf16 v[24:27], v[186:189], v[226:229], v[24:27]
	v_mfma_f32_16x16x32_bf16 v[12:15], v[138:141], v[234:237], v[12:15]
	v_mfma_f32_16x16x32_bf16 v[8:11], v[186:189], v[234:237], v[8:11]
	v_mfma_f32_16x16x32_bf16 v[60:63], v[162:165], v[214:217], v[60:63]
	v_mfma_f32_16x16x32_bf16 v[56:59], v[190:193], v[214:217], v[56:59]
	v_mfma_f32_16x16x32_bf16 v[44:47], v[162:165], v[222:225], v[44:47]
	v_mfma_f32_16x16x32_bf16 v[40:43], v[190:193], v[222:225], v[40:43]
	v_mfma_f32_16x16x32_bf16 v[28:31], v[162:165], v[230:233], v[28:31]
	v_mfma_f32_16x16x32_bf16 v[24:27], v[190:193], v[230:233], v[24:27]
	v_mfma_f32_16x16x32_bf16 v[12:15], v[162:165], v[238:241], v[12:15]
	v_mfma_f32_16x16x32_bf16 v[8:11], v[190:193], v[238:241], v[8:11]
	s_setprio 0
	s_setprio 1
	v_mfma_f32_16x16x32_bf16 v[52:55], v[194:197], v[210:213], v[52:55]
	v_mfma_f32_16x16x32_bf16 v[48:51], v[202:205], v[210:213], v[48:51]
	v_mfma_f32_16x16x32_bf16 v[36:39], v[194:197], v[218:221], v[36:39]
	v_mfma_f32_16x16x32_bf16 v[32:35], v[202:205], v[218:221], v[32:35]
	v_mfma_f32_16x16x32_bf16 v[20:23], v[194:197], v[226:229], v[20:23]
	v_mfma_f32_16x16x32_bf16 v[16:19], v[202:205], v[226:229], v[16:19]
	v_mfma_f32_16x16x32_bf16 v[4:7], v[194:197], v[234:237], v[4:7]
	v_mfma_f32_16x16x32_bf16 v[0:3], v[202:205], v[234:237], v[0:3]
	v_mfma_f32_16x16x32_bf16 v[52:55], v[198:201], v[214:217], v[52:55]
	v_mfma_f32_16x16x32_bf16 v[48:51], v[206:209], v[214:217], v[48:51]
	v_mfma_f32_16x16x32_bf16 v[36:39], v[198:201], v[222:225], v[36:39]
	v_mfma_f32_16x16x32_bf16 v[32:35], v[206:209], v[222:225], v[32:35]
	v_mfma_f32_16x16x32_bf16 v[20:23], v[198:201], v[230:233], v[20:23]
	v_mfma_f32_16x16x32_bf16 v[16:19], v[206:209], v[230:233], v[16:19]
	v_mfma_f32_16x16x32_bf16 v[4:7], v[198:201], v[238:241], v[4:7]
	v_mfma_f32_16x16x32_bf16 v[0:3], v[206:209], v[238:241], v[0:3]
	s_setprio 0
	s_barrier
	s_add_u32 s33, s33, 0x100
	s_addc_u32 s49, s49, 0
	s_add_u32 s4, s4, 0x100
	s_addc_u32 s5, s5, 0
	s_cmp_ge_i32 s46, s22
	s_mov_b32 s6, s46
	s_cbranch_scc0 .LBB0_2965
	s_movk_i32 s51, 0x200
	s_movk_i32 s33, 0x300
